# loop header alignment: the 8 GEMM K-loop headers and the attention inner-loop headers padded to 64-byte boundaries (on the v052 base)
# speedup vs baseline: 1.0015x; 1.0015x over previous
; #define PG8_STAGE(bufoff, gbase, voff) do { _Pragma("unroll") for (int _i = 0; _i < 2; ++_i) \
;         __builtin_amdgcn_global_load_lds((const unsigned*)((const char*)(gbase) + (voff)[_i]), (PG8_LAS unsigned*)(lds + (bufoff) + ldsw + _i * 8192), 16, 0, 0); } while (0)
; #define PG8_LDA(dst, b, h) do { _Pragma("unroll") for (int m = 0; m < 4; ++m) _Pragma("unroll") for (int k = 0; k < 2; ++k) dst[m][k] = *(const PG8_LAS bf16x8*)(lds + PG8_SA(b, h) + aoff + m * 2048 + k * 1024); } while (0)
; #define PG8_LDB(dst, b, h) do { _Pragma("unroll") for (int n = 0; n < 2; ++n) _Pragma("unroll") for (int k = 0; k < 2; ++k) dst[n][k] = *(const PG8_LAS bf16x8*)(lds + PG8_SB(b, h) + boff + n * 2048 + k * 1024); } while (0)
; #define PG8_WAIT_V(n) asm volatile("s_waitcnt vmcnt(" #n ")" ::: "memory")
; #define PG8_WAIT_L(n) asm volatile("s_waitcnt lgkmcnt(" #n ")" ::: "memory")
; #define PG8_BAR __builtin_amdgcn_s_barrier()
; #define PG8_SCHED __builtin_amdgcn_sched_barrier(0)
; template <class Epi, class Sched, bool ALIGN_EPI = false, bool SP2 = false>
; __device__ __forceinline__ void gemm_phase(PG8_LAS unsigned char* lds, const Gemm g, const Sched& S, const Epi& E, const int tid_in) {
;     ...
;     for (;;) {
;         const bool has_next = S.next(ui + 1, nxt);
;         const char* nA = has_next ? (const char*)g.A + (size_t)nxt.pm * tstep : cA; const char* nB = has_next ? (const char*)g.Bt + (size_t)nxt.pn * tstep : cB;
;         for (int t = 0; t < nt; t += 2) {
;             const bool last = (t == nt - 2);
;             const char* a1 = cA + (size_t)(t + 1) * kstep;
;             const char* a2 = last ? nA : cA + (size_t)(t + 2) * kstep; const char* b2 = last ? nB : cB + (size_t)(t + 2) * kstep;
;             const char* a3 = a2 + kstep; const char* b3 = b2 + kstep;
;             if (last && has_next) S.a_ready(nxt);
;             if constexpr (SP2) {
;             PG8_LDB(B0, 0, 0); PG8_LDB(B1, 0, 1); PG8_SCHED; PG8_LDA(At, 0, 0); PG8_STAGE(PG8_SA(1, 1), a1 + hstep, voffA);
;             PG8_WAIT_V(8); PG8_WAIT_L(0); PG8_BAR; PG8_MMA(0, 0, At, B0); PG8_MMA(0, 1, At, B1); PG8_BAR; PG8_SCHED;
;             PG8_LDA(At, 0, 1); PG8_STAGE(PG8_SB(0, 0), b2, voffB); PG8_STAGE(PG8_SB(0, 1), b2 + hstep, voffB); PG8_STAGE(PG8_SA(0, 0), a2, voffA);
;             PG8_WAIT_V(8); PG8_WAIT_L(0); PG8_BAR; PG8_MMA(1, 0, At, B0); PG8_MMA(1, 1, At, B1); PG8_BAR; PG8_SCHED;
.LBB0_485:
	s_ashr_i32 s55, s54, 31
	s_lshl_b64 s[76:77], s[54:55], 19
	s_add_u32 s78, s36, s76
	s_addc_u32 s79, s37, s77
	s_and_b64 s[76:77], s[4:5], exec
	s_cselect_b32 s7, s79, s75
	s_cselect_b32 s18, s78, s74
	s_ashr_i32 s53, s52, 31
	s_lshl_b64 s[76:77], s[52:53], 19
	s_add_u32 s80, s34, s76
	s_addc_u32 s81, s35, s77
	s_and_b64 s[76:77], s[4:5], exec
	s_cselect_b32 s53, s81, s1
	s_cselect_b32 s55, s80, s0
	s_add_u32 s82, s74, 0x40080
	s_addc_u32 s83, s75, 0
	s_add_u32 s73, s0, 0x100
	v_mov_b32_e32 v0, 0
	s_addc_u32 s76, s1, 0
	s_mov_b32 s77, -2
	ds_read_b128 v[128:131], v174
	ds_read_b128 v[132:135], v174 offset:1024
	ds_read_b128 v[136:139], v174 offset:2048
	ds_read_b128 v[140:143], v174 offset:3072
	ds_read_b128 v[160:163], v175
	ds_read_b128 v[180:183], v175 offset:1024
	ds_read_b128 v[184:187], v175 offset:2048
	ds_read_b128 v[188:191], v175 offset:3072
	s_add_u32 s0, s82, 0xfffc0080
	s_addc_u32 s1, s83, -1
	s_cmp_eq_u32 s77, 12
	s_cselect_b32 s75, s7, s1
	s_cselect_b32 s74, s18, s0
	s_cselect_b32 s1, s53, s76
	s_cselect_b32 s0, s55, s73
	v_lshl_add_u64 v[164:165], s[82:83], 0, v[152:153]
	s_add_i32 m0, s17, 0xc000
	ds_read_b128 v[192:195], v176
	ds_read_b128 v[196:199], v176 offset:1024
	ds_read_b128 v[200:203], v176 offset:2048
	ds_read_b128 v[204:207], v176 offset:3072
	ds_read_b128 v[208:211], v176 offset:4096
	ds_read_b128 v[212:215], v176 offset:5120
	ds_read_b128 v[216:219], v176 offset:6144
	ds_read_b128 v[220:223], v176 offset:7168
	global_load_lds_dwordx4 v[164:165], off
	v_lshl_add_u64 v[164:165], s[82:83], 0, v[154:155]
	s_add_i32 m0, s17, 0xe000
	s_nop 0
	global_load_lds_dwordx4 v[164:165], off
	s_waitcnt vmcnt(8)
	s_waitcnt lgkmcnt(0)
	s_barrier
	s_waitcnt lgkmcnt(0)
	v_mfma_f32_16x16x32_bf16 v[124:127], v[128:131], v[192:195], 0
	v_mfma_f32_16x16x32_bf16 v[120:123], v[136:139], v[192:195], 0
	v_mfma_f32_16x16x32_bf16 v[108:111], v[128:131], v[200:203], 0
	v_mfma_f32_16x16x32_bf16 v[104:107], v[136:139], v[200:203], 0
	v_mfma_f32_16x16x32_bf16 v[92:95], v[128:131], v[208:211], 0
	v_mfma_f32_16x16x32_bf16 v[88:91], v[136:139], v[208:211], 0
	v_mfma_f32_16x16x32_bf16 v[76:79], v[128:131], v[216:219], 0
	v_mfma_f32_16x16x32_bf16 v[72:75], v[136:139], v[216:219], 0
	v_mfma_f32_16x16x32_bf16 v[124:127], v[132:135], v[196:199], v[124:127]
	v_mfma_f32_16x16x32_bf16 v[120:123], v[140:143], v[196:199], v[120:123]
	v_mfma_f32_16x16x32_bf16 v[108:111], v[132:135], v[204:207], v[108:111]
	v_mfma_f32_16x16x32_bf16 v[104:107], v[140:143], v[204:207], v[104:107]
	v_mfma_f32_16x16x32_bf16 v[92:95], v[132:135], v[212:215], v[92:95]
	v_mfma_f32_16x16x32_bf16 v[88:91], v[140:143], v[212:215], v[88:91]
	v_mfma_f32_16x16x32_bf16 v[76:79], v[132:135], v[220:223], v[76:79]
	v_mfma_f32_16x16x32_bf16 v[72:75], v[140:143], v[220:223], v[72:75]
	v_mfma_f32_16x16x32_bf16 v[116:119], v[160:163], v[192:195], 0
	v_mfma_f32_16x16x32_bf16 v[112:115], v[184:187], v[192:195], 0
	v_mfma_f32_16x16x32_bf16 v[100:103], v[160:163], v[200:203], 0
	v_mfma_f32_16x16x32_bf16 v[96:99], v[184:187], v[200:203], 0
	v_mfma_f32_16x16x32_bf16 v[84:87], v[160:163], v[208:211], 0
	v_mfma_f32_16x16x32_bf16 v[80:83], v[184:187], v[208:211], 0
	v_mfma_f32_16x16x32_bf16 v[68:71], v[160:163], v[216:219], 0
	v_mfma_f32_16x16x32_bf16 v[64:67], v[184:187], v[216:219], 0
	v_mfma_f32_16x16x32_bf16 v[116:119], v[180:183], v[196:199], v[116:119]
	v_mfma_f32_16x16x32_bf16 v[112:115], v[188:191], v[196:199], v[112:115]
	v_mfma_f32_16x16x32_bf16 v[100:103], v[180:183], v[204:207], v[100:103]
	v_mfma_f32_16x16x32_bf16 v[96:99], v[188:191], v[204:207], v[96:99]
	v_mfma_f32_16x16x32_bf16 v[84:87], v[180:183], v[212:215], v[84:87]
	v_mfma_f32_16x16x32_bf16 v[80:83], v[188:191], v[212:215], v[80:83]
	v_mfma_f32_16x16x32_bf16 v[68:71], v[180:183], v[220:223], v[68:71]
	v_mfma_f32_16x16x32_bf16 v[64:67], v[188:191], v[220:223], v[64:67]
	s_barrier
	s_add_i32 s84, s47, s2
	v_lshl_add_u64 v[164:165], s[0:1], 0, v[146:147]
	s_mov_b32 m0, s84
	ds_read_b128 v[192:195], v176 offset:16384
	ds_read_b128 v[196:199], v176 offset:17408
	ds_read_b128 v[200:203], v176 offset:18432
	ds_read_b128 v[204:207], v176 offset:19456
	ds_read_b128 v[208:211], v176 offset:20480
	ds_read_b128 v[212:215], v176 offset:21504
	ds_read_b128 v[216:219], v176 offset:22528
	ds_read_b128 v[220:223], v176 offset:23552
	global_load_lds_dwordx4 v[164:165], off
	s_add_i32 m0, s84, 0x2000
	s_add_u32 s84, s0, 0x40000
	v_lshl_add_u64 v[224:225], s[0:1], 0, v[150:151]
	s_addc_u32 s85, s1, 0
	s_add_i32 s86, s48, s2
	global_load_lds_dwordx4 v[224:225], off
	v_lshl_add_u64 v[226:227], s[84:85], 0, v[146:147]
	s_mov_b32 m0, s86
	v_lshl_add_u64 v[228:229], s[74:75], 0, v[148:149]
	global_load_lds_dwordx4 v[226:227], off
	v_lshl_add_u64 v[226:227], s[84:85], 0, v[150:151]
	s_add_i32 m0, s86, 0x2000
	s_nop 0
	global_load_lds_dwordx4 v[226:227], off
	v_lshl_add_u64 v[226:227], s[74:75], 0, v[144:145]
	s_mov_b32 m0, s17
	s_nop 0
	global_load_lds_dwordx4 v[226:227], off
	s_mov_b32 m0, s38
	s_nop 0
	global_load_lds_dwordx4 v[228:229], off
	s_waitcnt vmcnt(8)
	s_waitcnt lgkmcnt(0)
	s_barrier
; #define PG8_STAGE(bufoff, gbase, voff) do { _Pragma("unroll") for (int _i = 0; _i < 2; ++_i) \
;         __builtin_amdgcn_global_load_lds((const unsigned*)((const char*)(gbase) + (voff)[_i]), (PG8_LAS unsigned*)(lds + (bufoff) + ldsw + _i * 8192), 16, 0, 0); } while (0)
; #define PG8_LDA(dst, b, h) do { _Pragma("unroll") for (int m = 0; m < 4; ++m) _Pragma("unroll") for (int k = 0; k < 2; ++k) dst[m][k] = *(const PG8_LAS bf16x8*)(lds + PG8_SA(b, h) + aoff + m * 2048 + k * 1024); } while (0)
; #define PG8_LDB(dst, b, h) do { _Pragma("unroll") for (int n = 0; n < 2; ++n) _Pragma("unroll") for (int k = 0; k < 2; ++k) dst[n][k] = *(const PG8_LAS bf16x8*)(lds + PG8_SB(b, h) + boff + n * 2048 + k * 1024); } while (0)
; #define PG8_MMA(ai, bj, At, Bt) do { __builtin_amdgcn_s_setprio(1); _Pragma("unroll") for (int m = 0; m < 4; ++m) _Pragma("unroll") for (int n = 0; n < 2; ++n) _Pragma("unroll") for (int k = 0; k < 2; ++k) \
;         acc[ai][bj][m][n] = __builtin_amdgcn_mfma_f32_16x16x32_bf16(Bt[n][k], At[m][k], acc[ai][bj][m][n], 0, 0, 0); __builtin_amdgcn_s_setprio(0); } while (0)
; #define PG8_WAIT_V(n) asm volatile("s_waitcnt vmcnt(" #n ")" ::: "memory")
; #define PG8_WAIT_L(n) asm volatile("s_waitcnt lgkmcnt(" #n ")" ::: "memory")
; #define PG8_BAR __builtin_amdgcn_s_barrier()
; #define PG8_SCHED __builtin_amdgcn_sched_barrier(0)
; template <class Epi, class Sched, bool ALIGN_EPI = false, bool SP2 = false>
; __device__ __forceinline__ void gemm_phase(PG8_LAS unsigned char* lds, const Gemm g, const Sched& S, const Epi& E, const int tid_in) {
;     ...
;             PG8_WAIT_V(8); PG8_WAIT_L(0); PG8_BAR; PG8_MMA(0, 0, At, B0); PG8_MMA(0, 1, At, B1); PG8_BAR; PG8_SCHED;
;             PG8_LDA(At, 0, 1); PG8_STAGE(PG8_SB(0, 0), b2, voffB); PG8_STAGE(PG8_SB(0, 1), b2 + hstep, voffB); PG8_STAGE(PG8_SA(0, 0), a2, voffA);
;             PG8_WAIT_V(8); PG8_WAIT_L(0); PG8_BAR; PG8_MMA(1, 0, At, B0); PG8_MMA(1, 1, At, B1); PG8_BAR; PG8_SCHED;
;             PG8_LDB(B0, 1, 0); PG8_LDB(B1, 1, 1); PG8_SCHED; PG8_LDA(At, 1, 0); PG8_STAGE(PG8_SA(0, 1), a2 + hstep, voffA);
;             PG8_WAIT_V(8); PG8_WAIT_L(0); PG8_BAR; PG8_MMA(0, 0, At, B0); PG8_MMA(0, 1, At, B1); PG8_BAR; PG8_SCHED;
	s_waitcnt lgkmcnt(0)
	v_mfma_f32_16x16x32_bf16 v[60:63], v[128:131], v[192:195], 0
	v_mfma_f32_16x16x32_bf16 v[56:59], v[136:139], v[192:195], 0
	v_mfma_f32_16x16x32_bf16 v[44:47], v[128:131], v[200:203], 0
	v_mfma_f32_16x16x32_bf16 v[40:43], v[136:139], v[200:203], 0
	v_mfma_f32_16x16x32_bf16 v[28:31], v[128:131], v[208:211], 0
	v_mfma_f32_16x16x32_bf16 v[24:27], v[136:139], v[208:211], 0
	v_mfma_f32_16x16x32_bf16 v[12:15], v[128:131], v[216:219], 0
	v_mfma_f32_16x16x32_bf16 v[8:11], v[136:139], v[216:219], 0
	v_mfma_f32_16x16x32_bf16 v[60:63], v[132:135], v[196:199], v[60:63]
	v_mfma_f32_16x16x32_bf16 v[56:59], v[140:143], v[196:199], v[56:59]
	v_mfma_f32_16x16x32_bf16 v[44:47], v[132:135], v[204:207], v[44:47]
	v_mfma_f32_16x16x32_bf16 v[40:43], v[140:143], v[204:207], v[40:43]
	v_mfma_f32_16x16x32_bf16 v[28:31], v[132:135], v[212:215], v[28:31]
	v_mfma_f32_16x16x32_bf16 v[24:27], v[140:143], v[212:215], v[24:27]
	v_mfma_f32_16x16x32_bf16 v[12:15], v[132:135], v[220:223], v[12:15]
	v_mfma_f32_16x16x32_bf16 v[8:11], v[140:143], v[220:223], v[8:11]
	v_mfma_f32_16x16x32_bf16 v[52:55], v[160:163], v[192:195], 0
	v_mfma_f32_16x16x32_bf16 v[48:51], v[184:187], v[192:195], 0
	v_mfma_f32_16x16x32_bf16 v[36:39], v[160:163], v[200:203], 0
	v_mfma_f32_16x16x32_bf16 v[32:35], v[184:187], v[200:203], 0
	v_mfma_f32_16x16x32_bf16 v[20:23], v[160:163], v[208:211], 0
	v_mfma_f32_16x16x32_bf16 v[16:19], v[184:187], v[208:211], 0
	v_mfma_f32_16x16x32_bf16 v[4:7], v[160:163], v[216:219], 0
	v_mfma_f32_16x16x32_bf16 v[0:3], v[184:187], v[216:219], 0
	v_mfma_f32_16x16x32_bf16 v[52:55], v[180:183], v[196:199], v[52:55]
	v_mfma_f32_16x16x32_bf16 v[48:51], v[188:191], v[196:199], v[48:51]
	v_mfma_f32_16x16x32_bf16 v[36:39], v[180:183], v[204:207], v[36:39]
	v_mfma_f32_16x16x32_bf16 v[32:35], v[188:191], v[204:207], v[32:35]
	v_mfma_f32_16x16x32_bf16 v[20:23], v[180:183], v[212:215], v[20:23]
	v_mfma_f32_16x16x32_bf16 v[16:19], v[188:191], v[212:215], v[16:19]
	v_mfma_f32_16x16x32_bf16 v[4:7], v[180:183], v[220:223], v[4:7]
	v_mfma_f32_16x16x32_bf16 v[0:3], v[188:191], v[220:223], v[0:3]
	s_barrier
	s_add_i32 s84, 0, 0x18000
	s_add_i32 s85, 0, 0x1c000
	v_add_u32_e32 v140, s84, v168
	v_add_u32_e32 v179, s85, v168
	ds_read_b128 v[128:131], v140
	ds_read_b128 v[132:135], v140 offset:1024
	ds_read_b128 v[136:139], v140 offset:2048
	ds_read_b128 v[140:143], v140 offset:3072
	ds_read_b128 v[160:163], v179
	ds_read_b128 v[180:183], v179 offset:1024
	ds_read_b128 v[184:187], v179 offset:2048
	ds_read_b128 v[188:191], v179 offset:3072
	s_add_u32 s74, s74, 0x40000
	s_addc_u32 s75, s75, 0
	s_mov_b32 m0, s39
	v_lshl_add_u64 v[230:231], s[74:75], 0, v[144:145]
	ds_read_b128 v[192:195], v176 offset:32768
	ds_read_b128 v[196:199], v176 offset:33792
	ds_read_b128 v[200:203], v176 offset:34816
	ds_read_b128 v[204:207], v176 offset:35840
	ds_read_b128 v[208:211], v176 offset:36864
	ds_read_b128 v[212:215], v176 offset:37888
	ds_read_b128 v[216:219], v176 offset:38912
	ds_read_b128 v[220:223], v176 offset:39936
	global_load_lds_dwordx4 v[230:231], off
	v_lshl_add_u64 v[230:231], s[74:75], 0, v[148:149]
	s_mov_b32 m0, s40
	s_nop 0
	global_load_lds_dwordx4 v[230:231], off
	s_waitcnt vmcnt(8)
	s_waitcnt lgkmcnt(0)
	s_barrier
	s_waitcnt lgkmcnt(0)
	v_mfma_f32_16x16x32_bf16 v[124:127], v[128:131], v[192:195], v[124:127]
	v_mfma_f32_16x16x32_bf16 v[120:123], v[136:139], v[192:195], v[120:123]
	v_mfma_f32_16x16x32_bf16 v[108:111], v[128:131], v[200:203], v[108:111]
	v_mfma_f32_16x16x32_bf16 v[104:107], v[136:139], v[200:203], v[104:107]
	v_mfma_f32_16x16x32_bf16 v[92:95], v[128:131], v[208:211], v[92:95]
	v_mfma_f32_16x16x32_bf16 v[88:91], v[136:139], v[208:211], v[88:91]
	v_mfma_f32_16x16x32_bf16 v[76:79], v[128:131], v[216:219], v[76:79]
	v_mfma_f32_16x16x32_bf16 v[72:75], v[136:139], v[216:219], v[72:75]
	v_mfma_f32_16x16x32_bf16 v[124:127], v[132:135], v[196:199], v[124:127]
	v_mfma_f32_16x16x32_bf16 v[120:123], v[140:143], v[196:199], v[120:123]
	v_mfma_f32_16x16x32_bf16 v[108:111], v[132:135], v[204:207], v[108:111]
	v_mfma_f32_16x16x32_bf16 v[104:107], v[140:143], v[204:207], v[104:107]
	v_mfma_f32_16x16x32_bf16 v[92:95], v[132:135], v[212:215], v[92:95]
	v_mfma_f32_16x16x32_bf16 v[88:91], v[140:143], v[212:215], v[88:91]
	v_mfma_f32_16x16x32_bf16 v[76:79], v[132:135], v[220:223], v[76:79]
	v_mfma_f32_16x16x32_bf16 v[72:75], v[140:143], v[220:223], v[72:75]
	v_mfma_f32_16x16x32_bf16 v[116:119], v[160:163], v[192:195], v[116:119]
	v_mfma_f32_16x16x32_bf16 v[112:115], v[184:187], v[192:195], v[112:115]
	v_mfma_f32_16x16x32_bf16 v[100:103], v[160:163], v[200:203], v[100:103]
	v_mfma_f32_16x16x32_bf16 v[96:99], v[184:187], v[200:203], v[96:99]
	v_mfma_f32_16x16x32_bf16 v[84:87], v[160:163], v[208:211], v[84:87]
	v_mfma_f32_16x16x32_bf16 v[80:83], v[184:187], v[208:211], v[80:83]
	v_mfma_f32_16x16x32_bf16 v[68:71], v[160:163], v[216:219], v[68:71]
	v_mfma_f32_16x16x32_bf16 v[64:67], v[184:187], v[216:219], v[64:67]
	v_mfma_f32_16x16x32_bf16 v[116:119], v[180:183], v[196:199], v[116:119]
	v_mfma_f32_16x16x32_bf16 v[112:115], v[188:191], v[196:199], v[112:115]
	v_mfma_f32_16x16x32_bf16 v[100:103], v[180:183], v[204:207], v[100:103]
	v_mfma_f32_16x16x32_bf16 v[96:99], v[188:191], v[204:207], v[96:99]
	v_mfma_f32_16x16x32_bf16 v[84:87], v[180:183], v[212:215], v[84:87]
	v_mfma_f32_16x16x32_bf16 v[80:83], v[188:191], v[212:215], v[80:83]
	v_mfma_f32_16x16x32_bf16 v[68:71], v[180:183], v[220:223], v[68:71]
	v_mfma_f32_16x16x32_bf16 v[64:67], v[188:191], v[220:223], v[64:67]
	s_barrier
; #define PG8_STAGE(bufoff, gbase, voff) do { _Pragma("unroll") for (int _i = 0; _i < 2; ++_i) \
;         __builtin_amdgcn_global_load_lds((const unsigned*)((const char*)(gbase) + (voff)[_i]), (PG8_LAS unsigned*)(lds + (bufoff) + ldsw + _i * 8192), 16, 0, 0); } while (0)
; #define PG8_LDA(dst, b, h) do { _Pragma("unroll") for (int m = 0; m < 4; ++m) _Pragma("unroll") for (int k = 0; k < 2; ++k) dst[m][k] = *(const PG8_LAS bf16x8*)(lds + PG8_SA(b, h) + aoff + m * 2048 + k * 1024); } while (0)
; #define PG8_MMA(ai, bj, At, Bt) do { __builtin_amdgcn_s_setprio(1); _Pragma("unroll") for (int m = 0; m < 4; ++m) _Pragma("unroll") for (int n = 0; n < 2; ++n) _Pragma("unroll") for (int k = 0; k < 2; ++k) \
;         acc[ai][bj][m][n] = __builtin_amdgcn_mfma_f32_16x16x32_bf16(Bt[n][k], At[m][k], acc[ai][bj][m][n], 0, 0, 0); __builtin_amdgcn_s_setprio(0); } while (0)
; #define PG8_WAIT_V(n) asm volatile("s_waitcnt vmcnt(" #n ")" ::: "memory")
; #define PG8_WAIT_L(n) asm volatile("s_waitcnt lgkmcnt(" #n ")" ::: "memory")
; #define PG8_BAR __builtin_amdgcn_s_barrier()
; #define PG8_SCHED __builtin_amdgcn_sched_barrier(0)
; template <class Epi, class Sched, bool ALIGN_EPI = false, bool SP2 = false>
; __device__ __forceinline__ void gemm_phase(PG8_LAS unsigned char* lds, const Gemm g, const Sched& S, const Epi& E, const int tid_in) {
;     ...
;         for (int t = 0; t < nt; t += 2) {
;             const bool last = (t == nt - 2);
;     ...
;             PG8_LDA(At, 1, 1); PG8_STAGE(PG8_SB(1, 0), b3, voffB); PG8_STAGE(PG8_SB(1, 1), b3 + hstep, voffB); PG8_STAGE(PG8_SA(1, 0), a3, voffA);
;             PG8_WAIT_V(8); PG8_WAIT_L(0); PG8_BAR; PG8_MMA(1, 0, At, B0); PG8_MMA(1, 1, At, B1); PG8_BAR; PG8_SCHED;
	s_add_i32 s74, s84, s2
	v_lshl_add_u64 v[164:165], v[164:165], 0, s[28:29]
	s_mov_b32 m0, s74
	ds_read_b128 v[192:195], v176 offset:49152
	ds_read_b128 v[196:199], v176 offset:50176
	ds_read_b128 v[200:203], v176 offset:51200
	ds_read_b128 v[204:207], v176 offset:52224
	ds_read_b128 v[208:211], v176 offset:53248
	ds_read_b128 v[212:215], v176 offset:54272
	ds_read_b128 v[216:219], v176 offset:55296
	ds_read_b128 v[220:223], v176 offset:56320
	global_load_lds_dwordx4 v[164:165], off
	s_add_i32 m0, s74, 0x2000
	s_add_u32 s0, s0, 0x40080
	v_lshl_add_u64 v[164:165], v[224:225], 0, s[28:29]
	s_addc_u32 s1, s1, 0
	s_add_i32 s74, s85, s2
	global_load_lds_dwordx4 v[164:165], off
	v_lshl_add_u64 v[164:165], s[0:1], 0, v[146:147]
	s_mov_b32 m0, s74
	s_nop 0
	global_load_lds_dwordx4 v[164:165], off
	v_lshl_add_u64 v[164:165], s[0:1], 0, v[150:151]
	s_add_i32 m0, s74, 0x2000
	s_nop 0
	global_load_lds_dwordx4 v[164:165], off
	v_lshl_add_u64 v[164:165], v[226:227], 0, s[28:29]
	s_mov_b32 m0, s43
	s_nop 0
	global_load_lds_dwordx4 v[164:165], off
	v_lshl_add_u64 v[164:165], v[228:229], 0, s[28:29]
	s_mov_b32 m0, s44
	s_nop 0
	global_load_lds_dwordx4 v[164:165], off
	s_waitcnt vmcnt(8)
	s_waitcnt lgkmcnt(0)
	s_barrier
	s_waitcnt lgkmcnt(0)
	v_mfma_f32_16x16x32_bf16 v[60:63], v[128:131], v[192:195], v[60:63]
	v_mfma_f32_16x16x32_bf16 v[56:59], v[136:139], v[192:195], v[56:59]
	v_mfma_f32_16x16x32_bf16 v[44:47], v[128:131], v[200:203], v[44:47]
	v_mfma_f32_16x16x32_bf16 v[40:43], v[136:139], v[200:203], v[40:43]
	v_mfma_f32_16x16x32_bf16 v[28:31], v[128:131], v[208:211], v[28:31]
	v_mfma_f32_16x16x32_bf16 v[24:27], v[136:139], v[208:211], v[24:27]
	v_mfma_f32_16x16x32_bf16 v[12:15], v[128:131], v[216:219], v[12:15]
	v_mfma_f32_16x16x32_bf16 v[8:11], v[136:139], v[216:219], v[8:11]
	v_mfma_f32_16x16x32_bf16 v[60:63], v[132:135], v[196:199], v[60:63]
	v_mfma_f32_16x16x32_bf16 v[56:59], v[140:143], v[196:199], v[56:59]
	v_mfma_f32_16x16x32_bf16 v[44:47], v[132:135], v[204:207], v[44:47]
	v_mfma_f32_16x16x32_bf16 v[40:43], v[140:143], v[204:207], v[40:43]
	v_mfma_f32_16x16x32_bf16 v[28:31], v[132:135], v[212:215], v[28:31]
	v_mfma_f32_16x16x32_bf16 v[24:27], v[140:143], v[212:215], v[24:27]
	v_mfma_f32_16x16x32_bf16 v[12:15], v[132:135], v[220:223], v[12:15]
	v_mfma_f32_16x16x32_bf16 v[8:11], v[140:143], v[220:223], v[8:11]
	v_mfma_f32_16x16x32_bf16 v[52:55], v[160:163], v[192:195], v[52:55]
	v_mfma_f32_16x16x32_bf16 v[48:51], v[184:187], v[192:195], v[48:51]
	v_mfma_f32_16x16x32_bf16 v[36:39], v[160:163], v[200:203], v[36:39]
	v_mfma_f32_16x16x32_bf16 v[32:35], v[184:187], v[200:203], v[32:35]
	v_mfma_f32_16x16x32_bf16 v[20:23], v[160:163], v[208:211], v[20:23]
	v_mfma_f32_16x16x32_bf16 v[16:19], v[184:187], v[208:211], v[16:19]
	v_mfma_f32_16x16x32_bf16 v[4:7], v[160:163], v[216:219], v[4:7]
	v_mfma_f32_16x16x32_bf16 v[0:3], v[184:187], v[216:219], v[0:3]
	v_mfma_f32_16x16x32_bf16 v[52:55], v[180:183], v[196:199], v[52:55]
	v_mfma_f32_16x16x32_bf16 v[48:51], v[188:191], v[196:199], v[48:51]
	v_mfma_f32_16x16x32_bf16 v[36:39], v[180:183], v[204:207], v[36:39]
	v_mfma_f32_16x16x32_bf16 v[32:35], v[188:191], v[204:207], v[32:35]
	v_mfma_f32_16x16x32_bf16 v[20:23], v[180:183], v[212:215], v[20:23]
	v_mfma_f32_16x16x32_bf16 v[16:19], v[188:191], v[212:215], v[16:19]
	v_mfma_f32_16x16x32_bf16 v[4:7], v[180:183], v[220:223], v[4:7]
	v_mfma_f32_16x16x32_bf16 v[0:3], v[188:191], v[220:223], v[0:3]
	s_barrier
	s_add_i32 s77, s77, 2
	s_add_u32 s82, s82, 0x100
	s_addc_u32 s83, s83, 0
	s_add_u32 s73, s73, 0x100
	s_addc_u32 s76, s76, 0
	s_cmp_gt_u32 s77, 13
	s_cbranch_scc0 .LBB0_486
	s_branch .Lmy_kdone_1
	.p2alignl 6, 3212836864

; #define PG8_STAGE(bufoff, gbase, voff) do { _Pragma("unroll") for (int _i = 0; _i < 2; ++_i) \
;         __builtin_amdgcn_global_load_lds((const unsigned*)((const char*)(gbase) + (voff)[_i]), (PG8_LAS unsigned*)(lds + (bufoff) + ldsw + _i * 8192), 16, 0, 0); } while (0)
; #define PG8_LDA(dst, b, h) do { _Pragma("unroll") for (int m = 0; m < 4; ++m) _Pragma("unroll") for (int k = 0; k < 2; ++k) dst[m][k] = *(const PG8_LAS bf16x8*)(lds + PG8_SA(b, h) + aoff + m * 2048 + k * 1024); } while (0)
; #define PG8_LDB(dst, b, h) do { _Pragma("unroll") for (int n = 0; n < 2; ++n) _Pragma("unroll") for (int k = 0; k < 2; ++k) dst[n][k] = *(const PG8_LAS bf16x8*)(lds + PG8_SB(b, h) + boff + n * 2048 + k * 1024); } while (0)
; #define PG8_WAIT_V(n) asm volatile("s_waitcnt vmcnt(" #n ")" ::: "memory")
; #define PG8_WAIT_L(n) asm volatile("s_waitcnt lgkmcnt(" #n ")" ::: "memory")
; #define PG8_BAR __builtin_amdgcn_s_barrier()
; #define PG8_SCHED __builtin_amdgcn_sched_barrier(0)
; template <class Epi, class Sched, bool ALIGN_EPI = false, bool SP2 = false>
; __device__ __forceinline__ void gemm_phase(PG8_LAS unsigned char* lds, const Gemm g, const Sched& S, const Epi& E, const int tid_in) {
;     ...
;         const char* nA = has_next ? (const char*)g.A + (size_t)nxt.pm * tstep : cA; const char* nB = has_next ? (const char*)g.Bt + (size_t)nxt.pn * tstep : cB;
;         for (int t = 0; t < nt; t += 2) {
;             const bool last = (t == nt - 2);
;             const char* a1 = cA + (size_t)(t + 1) * kstep;
;             const char* a2 = last ? nA : cA + (size_t)(t + 2) * kstep; const char* b2 = last ? nB : cB + (size_t)(t + 2) * kstep;
;             const char* a3 = a2 + kstep; const char* b3 = b2 + kstep;
;             if (last && has_next) S.a_ready(nxt);
;             if constexpr (SP2) {
;             PG8_LDB(B0, 0, 0); PG8_LDB(B1, 0, 1); PG8_SCHED; PG8_LDA(At, 0, 0); PG8_STAGE(PG8_SA(1, 1), a1 + hstep, voffA);
;             PG8_WAIT_V(8); PG8_WAIT_L(0); PG8_BAR; PG8_MMA(0, 0, At, B0); PG8_MMA(0, 1, At, B1); PG8_BAR; PG8_SCHED;
;             PG8_LDA(At, 0, 1); PG8_STAGE(PG8_SB(0, 0), b2, voffB); PG8_STAGE(PG8_SB(0, 1), b2 + hstep, voffB); PG8_STAGE(PG8_SA(0, 0), a2, voffA);
;             PG8_WAIT_V(8); PG8_WAIT_L(0); PG8_BAR; PG8_MMA(1, 0, At, B0); PG8_MMA(1, 1, At, B1); PG8_BAR; PG8_SCHED;
.LBB0_688:
	s_ashr_i32 s43, s42, 31
	s_lshl_b64 s[44:45], s[42:43], 19
	s_add_u32 s44, s22, s44
	s_addc_u32 s45, s23, s45
	s_and_b64 s[46:47], s[6:7], exec
	s_cselect_b32 s43, s45, s1
	s_cselect_b32 s53, s44, s0
	s_ashr_i32 s41, s40, 31
	s_lshl_b64 s[46:47], s[40:41], 19
	s_add_u32 s46, s8, s46
	s_addc_u32 s47, s9, s47
	s_and_b64 s[54:55], s[6:7], exec
	s_cselect_b32 s41, s47, s57
	s_cselect_b32 s73, s46, s56
	s_add_u32 s54, s0, 0x40080
	s_addc_u32 s55, s1, 0
	s_add_u32 s74, s56, 0x100
	v_mov_b32_e32 v0, 0
	s_addc_u32 s75, s57, 0
	s_mov_b32 s76, -2
	ds_read_b128 v[92:95], v207
	ds_read_b128 v[100:103], v207 offset:1024
	ds_read_b128 v[112:115], v207 offset:2048
	ds_read_b128 v[124:127], v207 offset:3072
	ds_read_b128 v[136:139], v208
	ds_read_b128 v[148:151], v208 offset:1024
	ds_read_b128 v[152:155], v208 offset:2048
	ds_read_b128 v[156:159], v208 offset:3072
	s_add_u32 s0, s54, 0xfffc0080
	s_addc_u32 s1, s55, -1
	s_cmp_eq_u32 s76, 12
	s_cselect_b32 s57, s43, s1
	s_cselect_b32 s56, s53, s0
	s_cselect_b32 s1, s41, s75
	s_cselect_b32 s0, s73, s74
	v_lshl_add_u64 v[214:215], s[54:55], 0, v[192:193]
	s_add_i32 m0, s30, 0xc000
	ds_read_b128 v[160:163], v209
	ds_read_b128 v[164:167], v209 offset:1024
	ds_read_b128 v[168:171], v209 offset:2048
	ds_read_b128 v[172:175], v209 offset:3072
	ds_read_b128 v[176:179], v209 offset:4096
	ds_read_b128 v[180:183], v209 offset:5120
	ds_read_b128 v[200:203], v209 offset:6144
	ds_read_b128 v[210:213], v209 offset:7168
	global_load_lds_dwordx4 v[214:215], off
	v_lshl_add_u64 v[214:215], s[54:55], 0, v[194:195]
	s_add_i32 m0, s30, 0xe000
	s_nop 0
	global_load_lds_dwordx4 v[214:215], off
	s_waitcnt vmcnt(8)
	s_waitcnt lgkmcnt(0)
	s_barrier
	s_waitcnt lgkmcnt(0)
	v_mfma_f32_16x16x32_bf16 v[144:147], v[92:95], v[160:163], 0
	v_mfma_f32_16x16x32_bf16 v[140:143], v[112:115], v[160:163], 0
	v_mfma_f32_16x16x32_bf16 v[120:123], v[92:95], v[168:171], 0
	v_mfma_f32_16x16x32_bf16 v[116:119], v[112:115], v[168:171], 0
	v_mfma_f32_16x16x32_bf16 v[96:99], v[92:95], v[176:179], 0
	v_mfma_f32_16x16x32_bf16 v[88:91], v[112:115], v[176:179], 0
	v_mfma_f32_16x16x32_bf16 v[76:79], v[92:95], v[200:203], 0
	v_mfma_f32_16x16x32_bf16 v[72:75], v[112:115], v[200:203], 0
	v_mfma_f32_16x16x32_bf16 v[144:147], v[100:103], v[164:167], v[144:147]
	v_mfma_f32_16x16x32_bf16 v[140:143], v[124:127], v[164:167], v[140:143]
	v_mfma_f32_16x16x32_bf16 v[120:123], v[100:103], v[172:175], v[120:123]
	v_mfma_f32_16x16x32_bf16 v[116:119], v[124:127], v[172:175], v[116:119]
	v_mfma_f32_16x16x32_bf16 v[96:99], v[100:103], v[180:183], v[96:99]
	v_mfma_f32_16x16x32_bf16 v[88:91], v[124:127], v[180:183], v[88:91]
	v_mfma_f32_16x16x32_bf16 v[76:79], v[100:103], v[210:213], v[76:79]
	v_mfma_f32_16x16x32_bf16 v[72:75], v[124:127], v[210:213], v[72:75]
	v_mfma_f32_16x16x32_bf16 v[132:135], v[136:139], v[160:163], 0
	v_mfma_f32_16x16x32_bf16 v[128:131], v[152:155], v[160:163], 0
	v_mfma_f32_16x16x32_bf16 v[108:111], v[136:139], v[168:171], 0
	v_mfma_f32_16x16x32_bf16 v[104:107], v[152:155], v[168:171], 0
	v_mfma_f32_16x16x32_bf16 v[84:87], v[136:139], v[176:179], 0
	v_mfma_f32_16x16x32_bf16 v[80:83], v[152:155], v[176:179], 0
	v_mfma_f32_16x16x32_bf16 v[68:71], v[136:139], v[200:203], 0
	v_mfma_f32_16x16x32_bf16 v[64:67], v[152:155], v[200:203], 0
	v_mfma_f32_16x16x32_bf16 v[132:135], v[148:151], v[164:167], v[132:135]
	v_mfma_f32_16x16x32_bf16 v[128:131], v[156:159], v[164:167], v[128:131]
	v_mfma_f32_16x16x32_bf16 v[108:111], v[148:151], v[172:175], v[108:111]
	v_mfma_f32_16x16x32_bf16 v[104:107], v[156:159], v[172:175], v[104:107]
	v_mfma_f32_16x16x32_bf16 v[84:87], v[148:151], v[180:183], v[84:87]
	v_mfma_f32_16x16x32_bf16 v[80:83], v[156:159], v[180:183], v[80:83]
	v_mfma_f32_16x16x32_bf16 v[68:71], v[148:151], v[210:213], v[68:71]
	v_mfma_f32_16x16x32_bf16 v[64:67], v[156:159], v[210:213], v[64:67]
	s_barrier
	s_add_i32 s77, s49, s2
	v_lshl_add_u64 v[214:215], s[0:1], 0, v[186:187]
	s_mov_b32 m0, s77
	ds_read_b128 v[160:163], v209 offset:16384
	ds_read_b128 v[164:167], v209 offset:17408
	ds_read_b128 v[168:171], v209 offset:18432
	ds_read_b128 v[172:175], v209 offset:19456
	ds_read_b128 v[176:179], v209 offset:20480
	ds_read_b128 v[180:183], v209 offset:21504
	ds_read_b128 v[200:203], v209 offset:22528
	ds_read_b128 v[210:213], v209 offset:23552
	global_load_lds_dwordx4 v[214:215], off
	s_add_i32 m0, s77, 0x2000
	s_add_u32 s78, s0, 0x40000
	v_lshl_add_u64 v[216:217], s[0:1], 0, v[190:191]
	s_addc_u32 s79, s1, 0
	s_add_i32 s77, s50, s2
	global_load_lds_dwordx4 v[216:217], off
	v_lshl_add_u64 v[218:219], s[78:79], 0, v[186:187]
	s_mov_b32 m0, s77
	v_lshl_add_u64 v[220:221], s[56:57], 0, v[188:189]
	global_load_lds_dwordx4 v[218:219], off
	v_lshl_add_u64 v[218:219], s[78:79], 0, v[190:191]
	s_add_i32 m0, s77, 0x2000
	s_nop 0
	global_load_lds_dwordx4 v[218:219], off
	v_lshl_add_u64 v[218:219], s[56:57], 0, v[184:185]
	s_mov_b32 m0, s30
	s_nop 0
	global_load_lds_dwordx4 v[218:219], off
	s_mov_b32 m0, s31
	s_nop 0
	global_load_lds_dwordx4 v[220:221], off
	s_waitcnt vmcnt(8)
	s_waitcnt lgkmcnt(0)
	s_barrier
; #define PG8_STAGE(bufoff, gbase, voff) do { _Pragma("unroll") for (int _i = 0; _i < 2; ++_i) \
;         __builtin_amdgcn_global_load_lds((const unsigned*)((const char*)(gbase) + (voff)[_i]), (PG8_LAS unsigned*)(lds + (bufoff) + ldsw + _i * 8192), 16, 0, 0); } while (0)
; #define PG8_LDA(dst, b, h) do { _Pragma("unroll") for (int m = 0; m < 4; ++m) _Pragma("unroll") for (int k = 0; k < 2; ++k) dst[m][k] = *(const PG8_LAS bf16x8*)(lds + PG8_SA(b, h) + aoff + m * 2048 + k * 1024); } while (0)
; #define PG8_LDB(dst, b, h) do { _Pragma("unroll") for (int n = 0; n < 2; ++n) _Pragma("unroll") for (int k = 0; k < 2; ++k) dst[n][k] = *(const PG8_LAS bf16x8*)(lds + PG8_SB(b, h) + boff + n * 2048 + k * 1024); } while (0)
; #define PG8_MMA(ai, bj, At, Bt) do { __builtin_amdgcn_s_setprio(1); _Pragma("unroll") for (int m = 0; m < 4; ++m) _Pragma("unroll") for (int n = 0; n < 2; ++n) _Pragma("unroll") for (int k = 0; k < 2; ++k) \
;         acc[ai][bj][m][n] = __builtin_amdgcn_mfma_f32_16x16x32_bf16(Bt[n][k], At[m][k], acc[ai][bj][m][n], 0, 0, 0); __builtin_amdgcn_s_setprio(0); } while (0)
; #define PG8_WAIT_V(n) asm volatile("s_waitcnt vmcnt(" #n ")" ::: "memory")
; #define PG8_WAIT_L(n) asm volatile("s_waitcnt lgkmcnt(" #n ")" ::: "memory")
; #define PG8_BAR __builtin_amdgcn_s_barrier()
; #define PG8_SCHED __builtin_amdgcn_sched_barrier(0)
; template <class Epi, class Sched, bool ALIGN_EPI = false, bool SP2 = false>
; __device__ __forceinline__ void gemm_phase(PG8_LAS unsigned char* lds, const Gemm g, const Sched& S, const Epi& E, const int tid_in) {
;     ...
;             PG8_WAIT_V(8); PG8_WAIT_L(0); PG8_BAR; PG8_MMA(1, 0, At, B0); PG8_MMA(1, 1, At, B1); PG8_BAR; PG8_SCHED;
;             PG8_LDB(B0, 1, 0); PG8_LDB(B1, 1, 1); PG8_SCHED; PG8_LDA(At, 1, 0); PG8_STAGE(PG8_SA(0, 1), a2 + hstep, voffA);
;             PG8_WAIT_V(8); PG8_WAIT_L(0); PG8_BAR; PG8_MMA(0, 0, At, B0); PG8_MMA(0, 1, At, B1); PG8_BAR; PG8_SCHED;
	s_waitcnt lgkmcnt(0)
	v_mfma_f32_16x16x32_bf16 v[60:63], v[92:95], v[160:163], 0
	v_mfma_f32_16x16x32_bf16 v[56:59], v[112:115], v[160:163], 0
	v_mfma_f32_16x16x32_bf16 v[44:47], v[92:95], v[168:171], 0
	v_mfma_f32_16x16x32_bf16 v[40:43], v[112:115], v[168:171], 0
	v_mfma_f32_16x16x32_bf16 v[28:31], v[92:95], v[176:179], 0
	v_mfma_f32_16x16x32_bf16 v[24:27], v[112:115], v[176:179], 0
	v_mfma_f32_16x16x32_bf16 v[12:15], v[92:95], v[200:203], 0
	v_mfma_f32_16x16x32_bf16 v[8:11], v[112:115], v[200:203], 0
	v_mfma_f32_16x16x32_bf16 v[60:63], v[100:103], v[164:167], v[60:63]
	v_mfma_f32_16x16x32_bf16 v[56:59], v[124:127], v[164:167], v[56:59]
	v_mfma_f32_16x16x32_bf16 v[44:47], v[100:103], v[172:175], v[44:47]
	v_mfma_f32_16x16x32_bf16 v[40:43], v[124:127], v[172:175], v[40:43]
	v_mfma_f32_16x16x32_bf16 v[28:31], v[100:103], v[180:183], v[28:31]
	v_mfma_f32_16x16x32_bf16 v[24:27], v[124:127], v[180:183], v[24:27]
	v_mfma_f32_16x16x32_bf16 v[12:15], v[100:103], v[210:213], v[12:15]
	v_mfma_f32_16x16x32_bf16 v[8:11], v[124:127], v[210:213], v[8:11]
	v_mfma_f32_16x16x32_bf16 v[52:55], v[136:139], v[160:163], 0
	v_mfma_f32_16x16x32_bf16 v[48:51], v[152:155], v[160:163], 0
	v_mfma_f32_16x16x32_bf16 v[36:39], v[136:139], v[168:171], 0
	v_mfma_f32_16x16x32_bf16 v[32:35], v[152:155], v[168:171], 0
	v_mfma_f32_16x16x32_bf16 v[20:23], v[136:139], v[176:179], 0
	v_mfma_f32_16x16x32_bf16 v[16:19], v[152:155], v[176:179], 0
	v_mfma_f32_16x16x32_bf16 v[4:7], v[136:139], v[200:203], 0
	v_mfma_f32_16x16x32_bf16 v[0:3], v[152:155], v[200:203], 0
	v_mfma_f32_16x16x32_bf16 v[52:55], v[148:151], v[164:167], v[52:55]
	v_mfma_f32_16x16x32_bf16 v[48:51], v[156:159], v[164:167], v[48:51]
	v_mfma_f32_16x16x32_bf16 v[36:39], v[148:151], v[172:175], v[36:39]
	v_mfma_f32_16x16x32_bf16 v[32:35], v[156:159], v[172:175], v[32:35]
	v_mfma_f32_16x16x32_bf16 v[20:23], v[148:151], v[180:183], v[20:23]
	v_mfma_f32_16x16x32_bf16 v[16:19], v[156:159], v[180:183], v[16:19]
	v_mfma_f32_16x16x32_bf16 v[4:7], v[148:151], v[210:213], v[4:7]
	v_mfma_f32_16x16x32_bf16 v[0:3], v[156:159], v[210:213], v[0:3]
	s_barrier
	s_add_i32 s77, 0, 0x18000
	s_add_i32 s78, 0, 0x1c000
	v_add_u32_e32 v124, s77, v205
	v_add_u32_e32 v156, s78, v205
	ds_read_b128 v[92:95], v124
	ds_read_b128 v[100:103], v124 offset:1024
	ds_read_b128 v[112:115], v124 offset:2048
	ds_read_b128 v[124:127], v124 offset:3072
	ds_read_b128 v[136:139], v156
	ds_read_b128 v[148:151], v156 offset:1024
	ds_read_b128 v[152:155], v156 offset:2048
	ds_read_b128 v[156:159], v156 offset:3072
	s_add_u32 s56, s56, 0x40000
	s_addc_u32 s57, s57, 0
	s_mov_b32 m0, s34
	v_lshl_add_u64 v[222:223], s[56:57], 0, v[184:185]
	ds_read_b128 v[160:163], v209 offset:32768
	ds_read_b128 v[164:167], v209 offset:33792
	ds_read_b128 v[168:171], v209 offset:34816
	ds_read_b128 v[172:175], v209 offset:35840
	ds_read_b128 v[176:179], v209 offset:36864
	ds_read_b128 v[180:183], v209 offset:37888
	ds_read_b128 v[200:203], v209 offset:38912
	ds_read_b128 v[210:213], v209 offset:39936
	global_load_lds_dwordx4 v[222:223], off
	v_lshl_add_u64 v[222:223], s[56:57], 0, v[188:189]
	s_mov_b32 m0, s35
	s_nop 0
	global_load_lds_dwordx4 v[222:223], off
	s_waitcnt vmcnt(8)
	s_waitcnt lgkmcnt(0)
	s_barrier
	s_waitcnt lgkmcnt(0)
	v_mfma_f32_16x16x32_bf16 v[144:147], v[92:95], v[160:163], v[144:147]
	v_mfma_f32_16x16x32_bf16 v[140:143], v[112:115], v[160:163], v[140:143]
	v_mfma_f32_16x16x32_bf16 v[120:123], v[92:95], v[168:171], v[120:123]
	v_mfma_f32_16x16x32_bf16 v[116:119], v[112:115], v[168:171], v[116:119]
	v_mfma_f32_16x16x32_bf16 v[96:99], v[92:95], v[176:179], v[96:99]
	v_mfma_f32_16x16x32_bf16 v[88:91], v[112:115], v[176:179], v[88:91]
	v_mfma_f32_16x16x32_bf16 v[76:79], v[92:95], v[200:203], v[76:79]
	v_mfma_f32_16x16x32_bf16 v[72:75], v[112:115], v[200:203], v[72:75]
	v_mfma_f32_16x16x32_bf16 v[144:147], v[100:103], v[164:167], v[144:147]
	v_mfma_f32_16x16x32_bf16 v[140:143], v[124:127], v[164:167], v[140:143]
	v_mfma_f32_16x16x32_bf16 v[120:123], v[100:103], v[172:175], v[120:123]
	v_mfma_f32_16x16x32_bf16 v[116:119], v[124:127], v[172:175], v[116:119]
	v_mfma_f32_16x16x32_bf16 v[96:99], v[100:103], v[180:183], v[96:99]
	v_mfma_f32_16x16x32_bf16 v[88:91], v[124:127], v[180:183], v[88:91]
	v_mfma_f32_16x16x32_bf16 v[76:79], v[100:103], v[210:213], v[76:79]
	v_mfma_f32_16x16x32_bf16 v[72:75], v[124:127], v[210:213], v[72:75]
	v_mfma_f32_16x16x32_bf16 v[132:135], v[136:139], v[160:163], v[132:135]
	v_mfma_f32_16x16x32_bf16 v[128:131], v[152:155], v[160:163], v[128:131]
	v_mfma_f32_16x16x32_bf16 v[108:111], v[136:139], v[168:171], v[108:111]
	v_mfma_f32_16x16x32_bf16 v[104:107], v[152:155], v[168:171], v[104:107]
	v_mfma_f32_16x16x32_bf16 v[84:87], v[136:139], v[176:179], v[84:87]
	v_mfma_f32_16x16x32_bf16 v[80:83], v[152:155], v[176:179], v[80:83]
	v_mfma_f32_16x16x32_bf16 v[68:71], v[136:139], v[200:203], v[68:71]
	v_mfma_f32_16x16x32_bf16 v[64:67], v[152:155], v[200:203], v[64:67]
	v_mfma_f32_16x16x32_bf16 v[132:135], v[148:151], v[164:167], v[132:135]
	v_mfma_f32_16x16x32_bf16 v[128:131], v[156:159], v[164:167], v[128:131]
	v_mfma_f32_16x16x32_bf16 v[108:111], v[148:151], v[172:175], v[108:111]
	v_mfma_f32_16x16x32_bf16 v[104:107], v[156:159], v[172:175], v[104:107]
	v_mfma_f32_16x16x32_bf16 v[84:87], v[148:151], v[180:183], v[84:87]
	v_mfma_f32_16x16x32_bf16 v[80:83], v[156:159], v[180:183], v[80:83]
	v_mfma_f32_16x16x32_bf16 v[68:71], v[148:151], v[210:213], v[68:71]
	v_mfma_f32_16x16x32_bf16 v[64:67], v[156:159], v[210:213], v[64:67]
	s_barrier
; #define PG8_STAGE(bufoff, gbase, voff) do { _Pragma("unroll") for (int _i = 0; _i < 2; ++_i) \
;         __builtin_amdgcn_global_load_lds((const unsigned*)((const char*)(gbase) + (voff)[_i]), (PG8_LAS unsigned*)(lds + (bufoff) + ldsw + _i * 8192), 16, 0, 0); } while (0)
; #define PG8_LDA(dst, b, h) do { _Pragma("unroll") for (int m = 0; m < 4; ++m) _Pragma("unroll") for (int k = 0; k < 2; ++k) dst[m][k] = *(const PG8_LAS bf16x8*)(lds + PG8_SA(b, h) + aoff + m * 2048 + k * 1024); } while (0)
; #define PG8_MMA(ai, bj, At, Bt) do { __builtin_amdgcn_s_setprio(1); _Pragma("unroll") for (int m = 0; m < 4; ++m) _Pragma("unroll") for (int n = 0; n < 2; ++n) _Pragma("unroll") for (int k = 0; k < 2; ++k) \
;         acc[ai][bj][m][n] = __builtin_amdgcn_mfma_f32_16x16x32_bf16(Bt[n][k], At[m][k], acc[ai][bj][m][n], 0, 0, 0); __builtin_amdgcn_s_setprio(0); } while (0)
; #define PG8_WAIT_V(n) asm volatile("s_waitcnt vmcnt(" #n ")" ::: "memory")
; #define PG8_WAIT_L(n) asm volatile("s_waitcnt lgkmcnt(" #n ")" ::: "memory")
; #define PG8_BAR __builtin_amdgcn_s_barrier()
; #define PG8_SCHED __builtin_amdgcn_sched_barrier(0)
; template <class Epi, class Sched, bool ALIGN_EPI = false, bool SP2 = false>
; __device__ __forceinline__ void gemm_phase(PG8_LAS unsigned char* lds, const Gemm g, const Sched& S, const Epi& E, const int tid_in) {
;     ...
;             PG8_LDA(At, 1, 1); PG8_STAGE(PG8_SB(1, 0), b3, voffB); PG8_STAGE(PG8_SB(1, 1), b3 + hstep, voffB); PG8_STAGE(PG8_SA(1, 0), a3, voffA);
;             PG8_WAIT_V(8); PG8_WAIT_L(0); PG8_BAR; PG8_MMA(1, 0, At, B0); PG8_MMA(1, 1, At, B1); PG8_BAR; PG8_SCHED;
	s_add_i32 s56, s77, s2
	v_lshl_add_u64 v[214:215], v[214:215], 0, s[26:27]
	s_mov_b32 m0, s56
	ds_read_b128 v[160:163], v209 offset:49152
	ds_read_b128 v[164:167], v209 offset:50176
	ds_read_b128 v[168:171], v209 offset:51200
	ds_read_b128 v[172:175], v209 offset:52224
	ds_read_b128 v[176:179], v209 offset:53248
	ds_read_b128 v[180:183], v209 offset:54272
	ds_read_b128 v[200:203], v209 offset:55296
	ds_read_b128 v[210:213], v209 offset:56320
	global_load_lds_dwordx4 v[214:215], off
	s_add_i32 m0, s56, 0x2000
	s_add_u32 s0, s0, 0x40080
	v_lshl_add_u64 v[214:215], v[216:217], 0, s[26:27]
	s_addc_u32 s1, s1, 0
	s_add_i32 s56, s78, s2
	global_load_lds_dwordx4 v[214:215], off
	v_lshl_add_u64 v[214:215], s[0:1], 0, v[186:187]
	s_mov_b32 m0, s56
	s_nop 0
	global_load_lds_dwordx4 v[214:215], off
	v_lshl_add_u64 v[214:215], s[0:1], 0, v[190:191]
	s_add_i32 m0, s56, 0x2000
	s_nop 0
	global_load_lds_dwordx4 v[214:215], off
	v_lshl_add_u64 v[214:215], v[218:219], 0, s[26:27]
	s_mov_b32 m0, s37
	s_nop 0
	global_load_lds_dwordx4 v[214:215], off
	v_lshl_add_u64 v[214:215], v[220:221], 0, s[26:27]
	s_mov_b32 m0, s38
	s_nop 0
	global_load_lds_dwordx4 v[214:215], off
	s_waitcnt vmcnt(8)
	s_waitcnt lgkmcnt(0)
	s_barrier
	s_waitcnt lgkmcnt(0)
	v_mfma_f32_16x16x32_bf16 v[60:63], v[92:95], v[160:163], v[60:63]
	v_mfma_f32_16x16x32_bf16 v[56:59], v[112:115], v[160:163], v[56:59]
	v_mfma_f32_16x16x32_bf16 v[44:47], v[92:95], v[168:171], v[44:47]
	v_mfma_f32_16x16x32_bf16 v[40:43], v[112:115], v[168:171], v[40:43]
	v_mfma_f32_16x16x32_bf16 v[28:31], v[92:95], v[176:179], v[28:31]
	v_mfma_f32_16x16x32_bf16 v[24:27], v[112:115], v[176:179], v[24:27]
	v_mfma_f32_16x16x32_bf16 v[12:15], v[92:95], v[200:203], v[12:15]
	v_mfma_f32_16x16x32_bf16 v[8:11], v[112:115], v[200:203], v[8:11]
	v_mfma_f32_16x16x32_bf16 v[60:63], v[100:103], v[164:167], v[60:63]
	v_mfma_f32_16x16x32_bf16 v[56:59], v[124:127], v[164:167], v[56:59]
	v_mfma_f32_16x16x32_bf16 v[44:47], v[100:103], v[172:175], v[44:47]
	v_mfma_f32_16x16x32_bf16 v[40:43], v[124:127], v[172:175], v[40:43]
	v_mfma_f32_16x16x32_bf16 v[28:31], v[100:103], v[180:183], v[28:31]
	v_mfma_f32_16x16x32_bf16 v[24:27], v[124:127], v[180:183], v[24:27]
	v_mfma_f32_16x16x32_bf16 v[12:15], v[100:103], v[210:213], v[12:15]
	v_mfma_f32_16x16x32_bf16 v[8:11], v[124:127], v[210:213], v[8:11]
	v_mfma_f32_16x16x32_bf16 v[52:55], v[136:139], v[160:163], v[52:55]
	v_mfma_f32_16x16x32_bf16 v[48:51], v[152:155], v[160:163], v[48:51]
	v_mfma_f32_16x16x32_bf16 v[36:39], v[136:139], v[168:171], v[36:39]
	v_mfma_f32_16x16x32_bf16 v[32:35], v[152:155], v[168:171], v[32:35]
	v_mfma_f32_16x16x32_bf16 v[20:23], v[136:139], v[176:179], v[20:23]
	v_mfma_f32_16x16x32_bf16 v[16:19], v[152:155], v[176:179], v[16:19]
	v_mfma_f32_16x16x32_bf16 v[4:7], v[136:139], v[200:203], v[4:7]
	v_mfma_f32_16x16x32_bf16 v[0:3], v[152:155], v[200:203], v[0:3]
	v_mfma_f32_16x16x32_bf16 v[52:55], v[148:151], v[164:167], v[52:55]
	v_mfma_f32_16x16x32_bf16 v[48:51], v[156:159], v[164:167], v[48:51]
	v_mfma_f32_16x16x32_bf16 v[36:39], v[148:151], v[172:175], v[36:39]
	v_mfma_f32_16x16x32_bf16 v[32:35], v[156:159], v[172:175], v[32:35]
	v_mfma_f32_16x16x32_bf16 v[20:23], v[148:151], v[180:183], v[20:23]
	v_mfma_f32_16x16x32_bf16 v[16:19], v[156:159], v[180:183], v[16:19]
	v_mfma_f32_16x16x32_bf16 v[4:7], v[148:151], v[210:213], v[4:7]
	v_mfma_f32_16x16x32_bf16 v[0:3], v[156:159], v[210:213], v[0:3]
	s_barrier
	s_add_i32 s76, s76, 2
	s_add_u32 s54, s54, 0x100
	s_addc_u32 s55, s55, 0
	s_add_u32 s74, s74, 0x100
	s_addc_u32 s75, s75, 0
	s_cmp_gt_u32 s76, 13
	s_cbranch_scc0 .LBB0_689
	s_branch .Lmy_kdone_2
	.p2alignl 6, 3212836864

; #define PG8_STAGE(bufoff, gbase, voff) do { _Pragma("unroll") for (int _i = 0; _i < 2; ++_i) \
;         __builtin_amdgcn_global_load_lds((const unsigned*)((const char*)(gbase) + (voff)[_i]), (PG8_LAS unsigned*)(lds + (bufoff) + ldsw + _i * 8192), 16, 0, 0); } while (0)
; #define PG8_LDA(dst, b, h) do { _Pragma("unroll") for (int m = 0; m < 4; ++m) _Pragma("unroll") for (int k = 0; k < 2; ++k) dst[m][k] = *(const PG8_LAS bf16x8*)(lds + PG8_SA(b, h) + aoff + m * 2048 + k * 1024); } while (0)
; #define PG8_LDB(dst, b, h) do { _Pragma("unroll") for (int n = 0; n < 2; ++n) _Pragma("unroll") for (int k = 0; k < 2; ++k) dst[n][k] = *(const PG8_LAS bf16x8*)(lds + PG8_SB(b, h) + boff + n * 2048 + k * 1024); } while (0)
; #define PG8_WAIT_V(n) asm volatile("s_waitcnt vmcnt(" #n ")" ::: "memory")
; #define PG8_WAIT_L(n) asm volatile("s_waitcnt lgkmcnt(" #n ")" ::: "memory")
; #define PG8_BAR __builtin_amdgcn_s_barrier()
; #define PG8_SCHED __builtin_amdgcn_sched_barrier(0)
; template <class Epi, class Sched, bool ALIGN_EPI = false, bool SP2 = false>
; __device__ __forceinline__ void gemm_phase(PG8_LAS unsigned char* lds, const Gemm g, const Sched& S, const Epi& E, const int tid_in) {
;     ...
;         const char* nA = has_next ? (const char*)g.A + (size_t)nxt.pm * tstep : cA; const char* nB = has_next ? (const char*)g.Bt + (size_t)nxt.pn * tstep : cB;
;         for (int t = 0; t < nt; t += 2) {
;             const bool last = (t == nt - 2);
;             const char* a1 = cA + (size_t)(t + 1) * kstep;
;             const char* a2 = last ? nA : cA + (size_t)(t + 2) * kstep; const char* b2 = last ? nB : cB + (size_t)(t + 2) * kstep;
;             const char* a3 = a2 + kstep; const char* b3 = b2 + kstep;
;             if (last && has_next) S.a_ready(nxt);
;             if constexpr (SP2) {
;             PG8_LDB(B0, 0, 0); PG8_LDB(B1, 0, 1); PG8_SCHED; PG8_LDA(At, 0, 0); PG8_STAGE(PG8_SA(1, 1), a1 + hstep, voffA);
;             PG8_WAIT_V(8); PG8_WAIT_L(0); PG8_BAR; PG8_MMA(0, 0, At, B0); PG8_MMA(0, 1, At, B1); PG8_BAR; PG8_SCHED;
;             PG8_LDA(At, 0, 1); PG8_STAGE(PG8_SB(0, 0), b2, voffB); PG8_STAGE(PG8_SB(0, 1), b2 + hstep, voffB); PG8_STAGE(PG8_SA(0, 0), a2, voffA);
;             PG8_WAIT_V(8); PG8_WAIT_L(0); PG8_BAR; PG8_MMA(1, 0, At, B0); PG8_MMA(1, 1, At, B1); PG8_BAR; PG8_SCHED;
.LBB0_1199:
	s_ashr_i32 s45, s44, 31
	s_lshl_b64 s[8:9], s[44:45], 19
	s_add_u32 s46, s36, s8
	s_addc_u32 s47, s37, s9
	s_and_b64 s[8:9], s[4:5], exec
	s_cselect_b32 s45, s47, s55
	s_cselect_b32 s76, s46, s54
	s_ashr_i32 s43, s42, 31
	s_lshl_b64 s[8:9], s[42:43], 19
	s_add_u32 s52, s34, s8
	s_addc_u32 s53, s35, s9
	s_and_b64 s[8:9], s[4:5], exec
	s_cselect_b32 s43, s53, s1
	s_cselect_b32 s77, s52, s0
	s_add_u32 s8, s54, 0x40080
	s_addc_u32 s9, s55, 0
	s_add_u32 s78, s0, 0x100
	v_mov_b32_e32 v0, 0
	s_addc_u32 s79, s1, 0
	s_mov_b32 s80, -2
	ds_read_b128 v[160:163], v154
	ds_read_b128 v[164:167], v154 offset:1024
	ds_read_b128 v[168:171], v154 offset:2048
	ds_read_b128 v[172:175], v154 offset:3072
	ds_read_b128 v[176:179], v155
	ds_read_b128 v[180:183], v155 offset:1024
	ds_read_b128 v[184:187], v155 offset:2048
	ds_read_b128 v[188:191], v155 offset:3072
	s_add_u32 s0, s8, 0xfffc0080
	s_addc_u32 s1, s9, -1
	s_cmp_eq_u32 s80, 12
	s_cselect_b32 s55, s45, s1
	s_cselect_b32 s54, s76, s0
	s_cselect_b32 s1, s43, s79
	s_cselect_b32 s0, s77, s78
	v_lshl_add_u64 v[144:145], s[8:9], 0, v[136:137]
	s_add_i32 m0, s38, 0xc000
	ds_read_b128 v[192:195], v156
	ds_read_b128 v[196:199], v156 offset:1024
	ds_read_b128 v[200:203], v156 offset:2048
	ds_read_b128 v[204:207], v156 offset:3072
	ds_read_b128 v[208:211], v156 offset:4096
	ds_read_b128 v[212:215], v156 offset:5120
	ds_read_b128 v[216:219], v156 offset:6144
	ds_read_b128 v[220:223], v156 offset:7168
	global_load_lds_dwordx4 v[144:145], off
	v_lshl_add_u64 v[144:145], s[8:9], 0, v[138:139]
	s_add_i32 m0, s38, 0xe000
	s_nop 0
	global_load_lds_dwordx4 v[144:145], off
	s_waitcnt vmcnt(8)
	s_waitcnt lgkmcnt(0)
	s_barrier
	s_waitcnt lgkmcnt(0)
	v_mfma_f32_16x16x32_bf16 v[124:127], v[160:163], v[192:195], 0
	v_mfma_f32_16x16x32_bf16 v[116:119], v[168:171], v[192:195], 0
	v_mfma_f32_16x16x32_bf16 v[108:111], v[160:163], v[200:203], 0
	v_mfma_f32_16x16x32_bf16 v[100:103], v[168:171], v[200:203], 0
	v_mfma_f32_16x16x32_bf16 v[92:95], v[160:163], v[208:211], 0
	v_mfma_f32_16x16x32_bf16 v[84:87], v[168:171], v[208:211], 0
	v_mfma_f32_16x16x32_bf16 v[76:79], v[160:163], v[216:219], 0
	v_mfma_f32_16x16x32_bf16 v[68:71], v[168:171], v[216:219], 0
	v_mfma_f32_16x16x32_bf16 v[124:127], v[164:167], v[196:199], v[124:127]
	v_mfma_f32_16x16x32_bf16 v[116:119], v[172:175], v[196:199], v[116:119]
	v_mfma_f32_16x16x32_bf16 v[108:111], v[164:167], v[204:207], v[108:111]
	v_mfma_f32_16x16x32_bf16 v[100:103], v[172:175], v[204:207], v[100:103]
	v_mfma_f32_16x16x32_bf16 v[92:95], v[164:167], v[212:215], v[92:95]
	v_mfma_f32_16x16x32_bf16 v[84:87], v[172:175], v[212:215], v[84:87]
	v_mfma_f32_16x16x32_bf16 v[76:79], v[164:167], v[220:223], v[76:79]
	v_mfma_f32_16x16x32_bf16 v[68:71], v[172:175], v[220:223], v[68:71]
	v_mfma_f32_16x16x32_bf16 v[120:123], v[176:179], v[192:195], 0
	v_mfma_f32_16x16x32_bf16 v[112:115], v[184:187], v[192:195], 0
	v_mfma_f32_16x16x32_bf16 v[104:107], v[176:179], v[200:203], 0
	v_mfma_f32_16x16x32_bf16 v[96:99], v[184:187], v[200:203], 0
	v_mfma_f32_16x16x32_bf16 v[88:91], v[176:179], v[208:211], 0
	v_mfma_f32_16x16x32_bf16 v[80:83], v[184:187], v[208:211], 0
	v_mfma_f32_16x16x32_bf16 v[72:75], v[176:179], v[216:219], 0
	v_mfma_f32_16x16x32_bf16 v[64:67], v[184:187], v[216:219], 0
	v_mfma_f32_16x16x32_bf16 v[120:123], v[180:183], v[196:199], v[120:123]
	v_mfma_f32_16x16x32_bf16 v[112:115], v[188:191], v[196:199], v[112:115]
	v_mfma_f32_16x16x32_bf16 v[104:107], v[180:183], v[204:207], v[104:107]
	v_mfma_f32_16x16x32_bf16 v[96:99], v[188:191], v[204:207], v[96:99]
	v_mfma_f32_16x16x32_bf16 v[88:91], v[180:183], v[212:215], v[88:91]
	v_mfma_f32_16x16x32_bf16 v[80:83], v[188:191], v[212:215], v[80:83]
	v_mfma_f32_16x16x32_bf16 v[72:75], v[180:183], v[220:223], v[72:75]
	v_mfma_f32_16x16x32_bf16 v[64:67], v[188:191], v[220:223], v[64:67]
	s_barrier
	s_add_i32 s81, s57, s31
	v_lshl_add_u64 v[144:145], s[0:1], 0, v[130:131]
	s_mov_b32 m0, s81
	ds_read_b128 v[192:195], v156 offset:16384
	ds_read_b128 v[196:199], v156 offset:17408
	ds_read_b128 v[200:203], v156 offset:18432
	ds_read_b128 v[204:207], v156 offset:19456
	ds_read_b128 v[208:211], v156 offset:20480
	ds_read_b128 v[212:215], v156 offset:21504
	ds_read_b128 v[216:219], v156 offset:22528
	ds_read_b128 v[220:223], v156 offset:23552
	global_load_lds_dwordx4 v[144:145], off
	s_add_i32 m0, s81, 0x2000
	s_add_u32 s82, s0, 0x40000
	v_lshl_add_u64 v[224:225], s[0:1], 0, v[134:135]
	s_addc_u32 s83, s1, 0
	s_add_i32 s81, s73, s31
	global_load_lds_dwordx4 v[224:225], off
	v_lshl_add_u64 v[226:227], s[82:83], 0, v[130:131]
	s_mov_b32 m0, s81
	v_lshl_add_u64 v[228:229], s[54:55], 0, v[132:133]
	global_load_lds_dwordx4 v[226:227], off
	v_lshl_add_u64 v[226:227], s[82:83], 0, v[134:135]
	s_add_i32 m0, s81, 0x2000
	s_nop 0
	global_load_lds_dwordx4 v[226:227], off
	v_lshl_add_u64 v[226:227], s[54:55], 0, v[128:129]
	s_mov_b32 m0, s38
	s_nop 0
	global_load_lds_dwordx4 v[226:227], off
	s_mov_b32 m0, s39
	s_nop 0
	global_load_lds_dwordx4 v[228:229], off
	s_waitcnt vmcnt(8)
	s_waitcnt lgkmcnt(0)
	s_barrier
; #define PG8_STAGE(bufoff, gbase, voff) do { _Pragma("unroll") for (int _i = 0; _i < 2; ++_i) \
;         __builtin_amdgcn_global_load_lds((const unsigned*)((const char*)(gbase) + (voff)[_i]), (PG8_LAS unsigned*)(lds + (bufoff) + ldsw + _i * 8192), 16, 0, 0); } while (0)
; #define PG8_LDA(dst, b, h) do { _Pragma("unroll") for (int m = 0; m < 4; ++m) _Pragma("unroll") for (int k = 0; k < 2; ++k) dst[m][k] = *(const PG8_LAS bf16x8*)(lds + PG8_SA(b, h) + aoff + m * 2048 + k * 1024); } while (0)
; #define PG8_LDB(dst, b, h) do { _Pragma("unroll") for (int n = 0; n < 2; ++n) _Pragma("unroll") for (int k = 0; k < 2; ++k) dst[n][k] = *(const PG8_LAS bf16x8*)(lds + PG8_SB(b, h) + boff + n * 2048 + k * 1024); } while (0)
; #define PG8_MMA(ai, bj, At, Bt) do { __builtin_amdgcn_s_setprio(1); _Pragma("unroll") for (int m = 0; m < 4; ++m) _Pragma("unroll") for (int n = 0; n < 2; ++n) _Pragma("unroll") for (int k = 0; k < 2; ++k) \
;         acc[ai][bj][m][n] = __builtin_amdgcn_mfma_f32_16x16x32_bf16(Bt[n][k], At[m][k], acc[ai][bj][m][n], 0, 0, 0); __builtin_amdgcn_s_setprio(0); } while (0)
; #define PG8_WAIT_V(n) asm volatile("s_waitcnt vmcnt(" #n ")" ::: "memory")
; #define PG8_WAIT_L(n) asm volatile("s_waitcnt lgkmcnt(" #n ")" ::: "memory")
; #define PG8_BAR __builtin_amdgcn_s_barrier()
; #define PG8_SCHED __builtin_amdgcn_sched_barrier(0)
; template <class Epi, class Sched, bool ALIGN_EPI = false, bool SP2 = false>
; __device__ __forceinline__ void gemm_phase(PG8_LAS unsigned char* lds, const Gemm g, const Sched& S, const Epi& E, const int tid_in) {
;     ...
;             PG8_WAIT_V(8); PG8_WAIT_L(0); PG8_BAR; PG8_MMA(1, 0, At, B0); PG8_MMA(1, 1, At, B1); PG8_BAR; PG8_SCHED;
;             PG8_LDB(B0, 1, 0); PG8_LDB(B1, 1, 1); PG8_SCHED; PG8_LDA(At, 1, 0); PG8_STAGE(PG8_SA(0, 1), a2 + hstep, voffA);
;             PG8_WAIT_V(8); PG8_WAIT_L(0); PG8_BAR; PG8_MMA(0, 0, At, B0); PG8_MMA(0, 1, At, B1); PG8_BAR; PG8_SCHED;
	s_waitcnt lgkmcnt(0)
	v_mfma_f32_16x16x32_bf16 v[60:63], v[160:163], v[192:195], 0
	v_mfma_f32_16x16x32_bf16 v[52:55], v[168:171], v[192:195], 0
	v_mfma_f32_16x16x32_bf16 v[44:47], v[160:163], v[200:203], 0
	v_mfma_f32_16x16x32_bf16 v[36:39], v[168:171], v[200:203], 0
	v_mfma_f32_16x16x32_bf16 v[28:31], v[160:163], v[208:211], 0
	v_mfma_f32_16x16x32_bf16 v[20:23], v[168:171], v[208:211], 0
	v_mfma_f32_16x16x32_bf16 v[12:15], v[160:163], v[216:219], 0
	v_mfma_f32_16x16x32_bf16 v[4:7], v[168:171], v[216:219], 0
	v_mfma_f32_16x16x32_bf16 v[60:63], v[164:167], v[196:199], v[60:63]
	v_mfma_f32_16x16x32_bf16 v[52:55], v[172:175], v[196:199], v[52:55]
	v_mfma_f32_16x16x32_bf16 v[44:47], v[164:167], v[204:207], v[44:47]
	v_mfma_f32_16x16x32_bf16 v[36:39], v[172:175], v[204:207], v[36:39]
	v_mfma_f32_16x16x32_bf16 v[28:31], v[164:167], v[212:215], v[28:31]
	v_mfma_f32_16x16x32_bf16 v[20:23], v[172:175], v[212:215], v[20:23]
	v_mfma_f32_16x16x32_bf16 v[12:15], v[164:167], v[220:223], v[12:15]
	v_mfma_f32_16x16x32_bf16 v[4:7], v[172:175], v[220:223], v[4:7]
	v_mfma_f32_16x16x32_bf16 v[56:59], v[176:179], v[192:195], 0
	v_mfma_f32_16x16x32_bf16 v[48:51], v[184:187], v[192:195], 0
	v_mfma_f32_16x16x32_bf16 v[40:43], v[176:179], v[200:203], 0
	v_mfma_f32_16x16x32_bf16 v[32:35], v[184:187], v[200:203], 0
	v_mfma_f32_16x16x32_bf16 v[24:27], v[176:179], v[208:211], 0
	v_mfma_f32_16x16x32_bf16 v[16:19], v[184:187], v[208:211], 0
	v_mfma_f32_16x16x32_bf16 v[8:11], v[176:179], v[216:219], 0
	v_mfma_f32_16x16x32_bf16 v[0:3], v[184:187], v[216:219], 0
	v_mfma_f32_16x16x32_bf16 v[56:59], v[180:183], v[196:199], v[56:59]
	v_mfma_f32_16x16x32_bf16 v[48:51], v[188:191], v[196:199], v[48:51]
	v_mfma_f32_16x16x32_bf16 v[40:43], v[180:183], v[204:207], v[40:43]
	v_mfma_f32_16x16x32_bf16 v[32:35], v[188:191], v[204:207], v[32:35]
	v_mfma_f32_16x16x32_bf16 v[24:27], v[180:183], v[212:215], v[24:27]
	v_mfma_f32_16x16x32_bf16 v[16:19], v[188:191], v[212:215], v[16:19]
	v_mfma_f32_16x16x32_bf16 v[8:11], v[180:183], v[220:223], v[8:11]
	v_mfma_f32_16x16x32_bf16 v[0:3], v[188:191], v[220:223], v[0:3]
	s_barrier
	s_add_i32 s81, 0, 0x18000
	v_add_u32_e32 v159, s81, v148
	s_add_i32 s82, 0, 0x1c000
	ds_read_b128 v[160:163], v159
	ds_read_b128 v[164:167], v159 offset:1024
	ds_read_b128 v[168:171], v159 offset:2048
	ds_read_b128 v[172:175], v159 offset:3072
	v_add_u32_e32 v159, s82, v148
	ds_read_b128 v[176:179], v159
	ds_read_b128 v[180:183], v159 offset:1024
	ds_read_b128 v[184:187], v159 offset:2048
	ds_read_b128 v[188:191], v159 offset:3072
	s_add_u32 s54, s54, 0x40000
	s_addc_u32 s55, s55, 0
	s_mov_b32 m0, s40
	v_lshl_add_u64 v[230:231], s[54:55], 0, v[128:129]
	ds_read_b128 v[192:195], v156 offset:32768
	ds_read_b128 v[196:199], v156 offset:33792
	ds_read_b128 v[200:203], v156 offset:34816
	ds_read_b128 v[204:207], v156 offset:35840
	ds_read_b128 v[208:211], v156 offset:36864
	ds_read_b128 v[212:215], v156 offset:37888
	ds_read_b128 v[216:219], v156 offset:38912
	ds_read_b128 v[220:223], v156 offset:39936
	global_load_lds_dwordx4 v[230:231], off
	v_lshl_add_u64 v[230:231], s[54:55], 0, v[132:133]
	s_mov_b32 m0, s41
	s_nop 0
	global_load_lds_dwordx4 v[230:231], off
	s_waitcnt vmcnt(8)
	s_waitcnt lgkmcnt(0)
	s_barrier
	s_waitcnt lgkmcnt(0)
	v_mfma_f32_16x16x32_bf16 v[124:127], v[160:163], v[192:195], v[124:127]
	v_mfma_f32_16x16x32_bf16 v[116:119], v[168:171], v[192:195], v[116:119]
	v_mfma_f32_16x16x32_bf16 v[108:111], v[160:163], v[200:203], v[108:111]
	v_mfma_f32_16x16x32_bf16 v[100:103], v[168:171], v[200:203], v[100:103]
	v_mfma_f32_16x16x32_bf16 v[92:95], v[160:163], v[208:211], v[92:95]
	v_mfma_f32_16x16x32_bf16 v[84:87], v[168:171], v[208:211], v[84:87]
	v_mfma_f32_16x16x32_bf16 v[76:79], v[160:163], v[216:219], v[76:79]
	v_mfma_f32_16x16x32_bf16 v[68:71], v[168:171], v[216:219], v[68:71]
	v_mfma_f32_16x16x32_bf16 v[124:127], v[164:167], v[196:199], v[124:127]
	v_mfma_f32_16x16x32_bf16 v[116:119], v[172:175], v[196:199], v[116:119]
	v_mfma_f32_16x16x32_bf16 v[108:111], v[164:167], v[204:207], v[108:111]
	v_mfma_f32_16x16x32_bf16 v[100:103], v[172:175], v[204:207], v[100:103]
	v_mfma_f32_16x16x32_bf16 v[92:95], v[164:167], v[212:215], v[92:95]
	v_mfma_f32_16x16x32_bf16 v[84:87], v[172:175], v[212:215], v[84:87]
	v_mfma_f32_16x16x32_bf16 v[76:79], v[164:167], v[220:223], v[76:79]
	v_mfma_f32_16x16x32_bf16 v[68:71], v[172:175], v[220:223], v[68:71]
	v_mfma_f32_16x16x32_bf16 v[120:123], v[176:179], v[192:195], v[120:123]
	v_mfma_f32_16x16x32_bf16 v[112:115], v[184:187], v[192:195], v[112:115]
	v_mfma_f32_16x16x32_bf16 v[104:107], v[176:179], v[200:203], v[104:107]
	v_mfma_f32_16x16x32_bf16 v[96:99], v[184:187], v[200:203], v[96:99]
	v_mfma_f32_16x16x32_bf16 v[88:91], v[176:179], v[208:211], v[88:91]
	v_mfma_f32_16x16x32_bf16 v[80:83], v[184:187], v[208:211], v[80:83]
	v_mfma_f32_16x16x32_bf16 v[72:75], v[176:179], v[216:219], v[72:75]
	v_mfma_f32_16x16x32_bf16 v[64:67], v[184:187], v[216:219], v[64:67]
	v_mfma_f32_16x16x32_bf16 v[120:123], v[180:183], v[196:199], v[120:123]
	v_mfma_f32_16x16x32_bf16 v[112:115], v[188:191], v[196:199], v[112:115]
	v_mfma_f32_16x16x32_bf16 v[104:107], v[180:183], v[204:207], v[104:107]
	v_mfma_f32_16x16x32_bf16 v[96:99], v[188:191], v[204:207], v[96:99]
	v_mfma_f32_16x16x32_bf16 v[88:91], v[180:183], v[212:215], v[88:91]
	v_mfma_f32_16x16x32_bf16 v[80:83], v[188:191], v[212:215], v[80:83]
	v_mfma_f32_16x16x32_bf16 v[72:75], v[180:183], v[220:223], v[72:75]
	v_mfma_f32_16x16x32_bf16 v[64:67], v[188:191], v[220:223], v[64:67]
	s_barrier
; #define PG8_STAGE(bufoff, gbase, voff) do { _Pragma("unroll") for (int _i = 0; _i < 2; ++_i) \
;         __builtin_amdgcn_global_load_lds((const unsigned*)((const char*)(gbase) + (voff)[_i]), (PG8_LAS unsigned*)(lds + (bufoff) + ldsw + _i * 8192), 16, 0, 0); } while (0)
; #define PG8_LDA(dst, b, h) do { _Pragma("unroll") for (int m = 0; m < 4; ++m) _Pragma("unroll") for (int k = 0; k < 2; ++k) dst[m][k] = *(const PG8_LAS bf16x8*)(lds + PG8_SA(b, h) + aoff + m * 2048 + k * 1024); } while (0)
; #define PG8_MMA(ai, bj, At, Bt) do { __builtin_amdgcn_s_setprio(1); _Pragma("unroll") for (int m = 0; m < 4; ++m) _Pragma("unroll") for (int n = 0; n < 2; ++n) _Pragma("unroll") for (int k = 0; k < 2; ++k) \
;         acc[ai][bj][m][n] = __builtin_amdgcn_mfma_f32_16x16x32_bf16(Bt[n][k], At[m][k], acc[ai][bj][m][n], 0, 0, 0); __builtin_amdgcn_s_setprio(0); } while (0)
; #define PG8_WAIT_V(n) asm volatile("s_waitcnt vmcnt(" #n ")" ::: "memory")
; #define PG8_WAIT_L(n) asm volatile("s_waitcnt lgkmcnt(" #n ")" ::: "memory")
; #define PG8_BAR __builtin_amdgcn_s_barrier()
; #define PG8_SCHED __builtin_amdgcn_sched_barrier(0)
; template <class Epi, class Sched, bool ALIGN_EPI = false, bool SP2 = false>
; __device__ __forceinline__ void gemm_phase(PG8_LAS unsigned char* lds, const Gemm g, const Sched& S, const Epi& E, const int tid_in) {
;     ...
;             PG8_LDA(At, 1, 1); PG8_STAGE(PG8_SB(1, 0), b3, voffB); PG8_STAGE(PG8_SB(1, 1), b3 + hstep, voffB); PG8_STAGE(PG8_SA(1, 0), a3, voffA);
;             PG8_WAIT_V(8); PG8_WAIT_L(0); PG8_BAR; PG8_MMA(1, 0, At, B0); PG8_MMA(1, 1, At, B1); PG8_BAR; PG8_SCHED;
	s_add_i32 s54, s81, s31
	v_lshl_add_u64 v[144:145], v[144:145], 0, s[26:27]
	s_mov_b32 m0, s54
	ds_read_b128 v[192:195], v156 offset:49152
	ds_read_b128 v[196:199], v156 offset:50176
	ds_read_b128 v[200:203], v156 offset:51200
	ds_read_b128 v[204:207], v156 offset:52224
	ds_read_b128 v[208:211], v156 offset:53248
	ds_read_b128 v[212:215], v156 offset:54272
	ds_read_b128 v[216:219], v156 offset:55296
	ds_read_b128 v[220:223], v156 offset:56320
	global_load_lds_dwordx4 v[144:145], off
	s_add_i32 m0, s54, 0x2000
	s_add_u32 s0, s0, 0x40080
	v_lshl_add_u64 v[144:145], v[224:225], 0, s[26:27]
	s_addc_u32 s1, s1, 0
	s_add_i32 s54, s82, s31
	global_load_lds_dwordx4 v[144:145], off
	v_lshl_add_u64 v[144:145], s[0:1], 0, v[130:131]
	s_mov_b32 m0, s54
	s_nop 0
	global_load_lds_dwordx4 v[144:145], off
	v_lshl_add_u64 v[144:145], s[0:1], 0, v[134:135]
	s_add_i32 m0, s54, 0x2000
	s_nop 0
	global_load_lds_dwordx4 v[144:145], off
	v_lshl_add_u64 v[144:145], v[226:227], 0, s[26:27]
	s_mov_b32 m0, s50
	s_nop 0
	global_load_lds_dwordx4 v[144:145], off
	v_lshl_add_u64 v[144:145], v[228:229], 0, s[26:27]
	s_mov_b32 m0, s51
	s_nop 0
	global_load_lds_dwordx4 v[144:145], off
	s_waitcnt vmcnt(8)
	s_waitcnt lgkmcnt(0)
	s_barrier
	s_waitcnt lgkmcnt(0)
	v_mfma_f32_16x16x32_bf16 v[60:63], v[160:163], v[192:195], v[60:63]
	v_mfma_f32_16x16x32_bf16 v[52:55], v[168:171], v[192:195], v[52:55]
	v_mfma_f32_16x16x32_bf16 v[44:47], v[160:163], v[200:203], v[44:47]
	v_mfma_f32_16x16x32_bf16 v[36:39], v[168:171], v[200:203], v[36:39]
	v_mfma_f32_16x16x32_bf16 v[28:31], v[160:163], v[208:211], v[28:31]
	v_mfma_f32_16x16x32_bf16 v[20:23], v[168:171], v[208:211], v[20:23]
	v_mfma_f32_16x16x32_bf16 v[12:15], v[160:163], v[216:219], v[12:15]
	v_mfma_f32_16x16x32_bf16 v[4:7], v[168:171], v[216:219], v[4:7]
	v_mfma_f32_16x16x32_bf16 v[60:63], v[164:167], v[196:199], v[60:63]
	v_mfma_f32_16x16x32_bf16 v[52:55], v[172:175], v[196:199], v[52:55]
	v_mfma_f32_16x16x32_bf16 v[44:47], v[164:167], v[204:207], v[44:47]
	v_mfma_f32_16x16x32_bf16 v[36:39], v[172:175], v[204:207], v[36:39]
	v_mfma_f32_16x16x32_bf16 v[28:31], v[164:167], v[212:215], v[28:31]
	v_mfma_f32_16x16x32_bf16 v[20:23], v[172:175], v[212:215], v[20:23]
	v_mfma_f32_16x16x32_bf16 v[12:15], v[164:167], v[220:223], v[12:15]
	v_mfma_f32_16x16x32_bf16 v[4:7], v[172:175], v[220:223], v[4:7]
	v_mfma_f32_16x16x32_bf16 v[56:59], v[176:179], v[192:195], v[56:59]
	v_mfma_f32_16x16x32_bf16 v[48:51], v[184:187], v[192:195], v[48:51]
	v_mfma_f32_16x16x32_bf16 v[40:43], v[176:179], v[200:203], v[40:43]
	v_mfma_f32_16x16x32_bf16 v[32:35], v[184:187], v[200:203], v[32:35]
	v_mfma_f32_16x16x32_bf16 v[24:27], v[176:179], v[208:211], v[24:27]
	v_mfma_f32_16x16x32_bf16 v[16:19], v[184:187], v[208:211], v[16:19]
	v_mfma_f32_16x16x32_bf16 v[8:11], v[176:179], v[216:219], v[8:11]
	v_mfma_f32_16x16x32_bf16 v[0:3], v[184:187], v[216:219], v[0:3]
	v_mfma_f32_16x16x32_bf16 v[56:59], v[180:183], v[196:199], v[56:59]
	v_mfma_f32_16x16x32_bf16 v[48:51], v[188:191], v[196:199], v[48:51]
	v_mfma_f32_16x16x32_bf16 v[40:43], v[180:183], v[204:207], v[40:43]
	v_mfma_f32_16x16x32_bf16 v[32:35], v[188:191], v[204:207], v[32:35]
	v_mfma_f32_16x16x32_bf16 v[24:27], v[180:183], v[212:215], v[24:27]
	v_mfma_f32_16x16x32_bf16 v[16:19], v[188:191], v[212:215], v[16:19]
	v_mfma_f32_16x16x32_bf16 v[8:11], v[180:183], v[220:223], v[8:11]
	v_mfma_f32_16x16x32_bf16 v[0:3], v[188:191], v[220:223], v[0:3]
	s_barrier
	s_add_i32 s80, s80, 2
	s_add_u32 s8, s8, 0x100
	s_addc_u32 s9, s9, 0
	s_add_u32 s78, s78, 0x100
	s_addc_u32 s79, s79, 0
	s_cmp_gt_u32 s80, 13
	s_cbranch_scc0 .LBB0_1200
	s_branch .Lmy_kdone_3
	.p2alignl 6, 3212836864

; #define PG8_STAGE(bufoff, gbase, voff) do { _Pragma("unroll") for (int _i = 0; _i < 2; ++_i) \
;         __builtin_amdgcn_global_load_lds((const unsigned*)((const char*)(gbase) + (voff)[_i]), (PG8_LAS unsigned*)(lds + (bufoff) + ldsw + _i * 8192), 16, 0, 0); } while (0)
; #define PG8_LDA(dst, b, h) do { _Pragma("unroll") for (int m = 0; m < 4; ++m) _Pragma("unroll") for (int k = 0; k < 2; ++k) dst[m][k] = *(const PG8_LAS bf16x8*)(lds + PG8_SA(b, h) + aoff + m * 2048 + k * 1024); } while (0)
; #define PG8_LDB(dst, b, h) do { _Pragma("unroll") for (int n = 0; n < 2; ++n) _Pragma("unroll") for (int k = 0; k < 2; ++k) dst[n][k] = *(const PG8_LAS bf16x8*)(lds + PG8_SB(b, h) + boff + n * 2048 + k * 1024); } while (0)
; #define PG8_WAIT_V(n) asm volatile("s_waitcnt vmcnt(" #n ")" ::: "memory")
; #define PG8_WAIT_L(n) asm volatile("s_waitcnt lgkmcnt(" #n ")" ::: "memory")
; #define PG8_BAR __builtin_amdgcn_s_barrier()
; #define PG8_SCHED __builtin_amdgcn_sched_barrier(0)
; template <class Epi, class Sched, bool ALIGN_EPI = false, bool SP2 = false>
; __device__ __forceinline__ void gemm_phase(PG8_LAS unsigned char* lds, const Gemm g, const Sched& S, const Epi& E, const int tid_in) {
;     ...
;         const char* nA = has_next ? (const char*)g.A + (size_t)nxt.pm * tstep : cA; const char* nB = has_next ? (const char*)g.Bt + (size_t)nxt.pn * tstep : cB;
;         for (int t = 0; t < nt; t += 2) {
;             const bool last = (t == nt - 2);
;             const char* a1 = cA + (size_t)(t + 1) * kstep;
;             const char* a2 = last ? nA : cA + (size_t)(t + 2) * kstep; const char* b2 = last ? nB : cB + (size_t)(t + 2) * kstep;
;             const char* a3 = a2 + kstep; const char* b3 = b2 + kstep;
;             if (last && has_next) S.a_ready(nxt);
;             if constexpr (SP2) {
;             PG8_LDB(B0, 0, 0); PG8_LDB(B1, 0, 1); PG8_SCHED; PG8_LDA(At, 0, 0); PG8_STAGE(PG8_SA(1, 1), a1 + hstep, voffA);
;             PG8_WAIT_V(8); PG8_WAIT_L(0); PG8_BAR; PG8_MMA(0, 0, At, B0); PG8_MMA(0, 1, At, B1); PG8_BAR; PG8_SCHED;
;             PG8_LDA(At, 0, 1); PG8_STAGE(PG8_SB(0, 0), b2, voffB); PG8_STAGE(PG8_SB(0, 1), b2 + hstep, voffB); PG8_STAGE(PG8_SA(0, 0), a2, voffA);
;             PG8_WAIT_V(8); PG8_WAIT_L(0); PG8_BAR; PG8_MMA(1, 0, At, B0); PG8_MMA(1, 1, At, B1); PG8_BAR; PG8_SCHED;
.LBB0_1281:
	s_add_u32 s76, s76, 0x100
	v_mov_b32_e32 v0, 0
	s_addc_u32 s77, s77, 0
	s_mov_b32 s81, -2
	ds_read_b128 v[92:95], v207
	ds_read_b128 v[100:103], v207 offset:1024
	ds_read_b128 v[112:115], v207 offset:2048
	ds_read_b128 v[124:127], v207 offset:3072
	ds_read_b128 v[136:139], v208
	ds_read_b128 v[148:151], v208 offset:1024
	ds_read_b128 v[152:155], v208 offset:2048
	ds_read_b128 v[156:159], v208 offset:3072
	s_add_u32 s78, s56, 0x100
	s_addc_u32 s79, s57, 0
	s_cmp_eq_u32 s81, 40
	s_cselect_b32 s75, s9, s79
	s_cselect_b32 s74, s8, s78
	s_cselect_b32 s1, s55, s77
	s_cselect_b32 s0, s54, s76
	v_lshl_add_u64 v[214:215], s[56:57], 0, v[192:193]
	s_add_i32 m0, s31, 0xc000
	ds_read_b128 v[160:163], v209
	ds_read_b128 v[164:167], v209 offset:1024
	ds_read_b128 v[168:171], v209 offset:2048
	ds_read_b128 v[172:175], v209 offset:3072
	ds_read_b128 v[176:179], v209 offset:4096
	ds_read_b128 v[180:183], v209 offset:5120
	ds_read_b128 v[200:203], v209 offset:6144
	ds_read_b128 v[210:213], v209 offset:7168
	global_load_lds_dwordx4 v[214:215], off
	v_lshl_add_u64 v[214:215], s[56:57], 0, v[194:195]
	s_add_i32 m0, s31, 0xe000
	s_nop 0
	global_load_lds_dwordx4 v[214:215], off
	s_waitcnt vmcnt(8)
	s_waitcnt lgkmcnt(0)
	s_barrier
	s_waitcnt lgkmcnt(0)
	v_mfma_f32_16x16x32_bf16 v[144:147], v[92:95], v[160:163], 0
	v_mfma_f32_16x16x32_bf16 v[140:143], v[112:115], v[160:163], 0
	v_mfma_f32_16x16x32_bf16 v[120:123], v[92:95], v[168:171], 0
	v_mfma_f32_16x16x32_bf16 v[116:119], v[112:115], v[168:171], 0
	v_mfma_f32_16x16x32_bf16 v[96:99], v[92:95], v[176:179], 0
	v_mfma_f32_16x16x32_bf16 v[88:91], v[112:115], v[176:179], 0
	v_mfma_f32_16x16x32_bf16 v[76:79], v[92:95], v[200:203], 0
	v_mfma_f32_16x16x32_bf16 v[72:75], v[112:115], v[200:203], 0
	v_mfma_f32_16x16x32_bf16 v[144:147], v[100:103], v[164:167], v[144:147]
	v_mfma_f32_16x16x32_bf16 v[140:143], v[124:127], v[164:167], v[140:143]
	v_mfma_f32_16x16x32_bf16 v[120:123], v[100:103], v[172:175], v[120:123]
	v_mfma_f32_16x16x32_bf16 v[116:119], v[124:127], v[172:175], v[116:119]
	v_mfma_f32_16x16x32_bf16 v[96:99], v[100:103], v[180:183], v[96:99]
	v_mfma_f32_16x16x32_bf16 v[88:91], v[124:127], v[180:183], v[88:91]
	v_mfma_f32_16x16x32_bf16 v[76:79], v[100:103], v[210:213], v[76:79]
	v_mfma_f32_16x16x32_bf16 v[72:75], v[124:127], v[210:213], v[72:75]
	v_mfma_f32_16x16x32_bf16 v[132:135], v[136:139], v[160:163], 0
	v_mfma_f32_16x16x32_bf16 v[128:131], v[152:155], v[160:163], 0
	v_mfma_f32_16x16x32_bf16 v[108:111], v[136:139], v[168:171], 0
	v_mfma_f32_16x16x32_bf16 v[104:107], v[152:155], v[168:171], 0
	v_mfma_f32_16x16x32_bf16 v[84:87], v[136:139], v[176:179], 0
	v_mfma_f32_16x16x32_bf16 v[80:83], v[152:155], v[176:179], 0
	v_mfma_f32_16x16x32_bf16 v[68:71], v[136:139], v[200:203], 0
	v_mfma_f32_16x16x32_bf16 v[64:67], v[152:155], v[200:203], 0
	v_mfma_f32_16x16x32_bf16 v[132:135], v[148:151], v[164:167], v[132:135]
	v_mfma_f32_16x16x32_bf16 v[128:131], v[156:159], v[164:167], v[128:131]
	v_mfma_f32_16x16x32_bf16 v[108:111], v[148:151], v[172:175], v[108:111]
	v_mfma_f32_16x16x32_bf16 v[104:107], v[156:159], v[172:175], v[104:107]
	v_mfma_f32_16x16x32_bf16 v[84:87], v[148:151], v[180:183], v[84:87]
	v_mfma_f32_16x16x32_bf16 v[80:83], v[156:159], v[180:183], v[80:83]
	v_mfma_f32_16x16x32_bf16 v[68:71], v[148:151], v[210:213], v[68:71]
	v_mfma_f32_16x16x32_bf16 v[64:67], v[156:159], v[210:213], v[64:67]
	s_barrier
	s_add_i32 s56, s48, s30
	v_lshl_add_u64 v[214:215], s[0:1], 0, v[186:187]
	s_mov_b32 m0, s56
	ds_read_b128 v[160:163], v209 offset:16384
	ds_read_b128 v[164:167], v209 offset:17408
	ds_read_b128 v[168:171], v209 offset:18432
	ds_read_b128 v[172:175], v209 offset:19456
	ds_read_b128 v[176:179], v209 offset:20480
	ds_read_b128 v[180:183], v209 offset:21504
	ds_read_b128 v[200:203], v209 offset:22528
	ds_read_b128 v[210:213], v209 offset:23552
	global_load_lds_dwordx4 v[214:215], off
	s_add_i32 m0, s56, 0x2000
	s_add_u32 s56, s0, 0xb0000
	v_lshl_add_u64 v[216:217], s[0:1], 0, v[190:191]
	s_addc_u32 s57, s1, 0
	s_add_i32 s82, s49, s30
	global_load_lds_dwordx4 v[216:217], off
	v_lshl_add_u64 v[218:219], s[56:57], 0, v[186:187]
	s_mov_b32 m0, s82
	v_lshl_add_u64 v[220:221], s[74:75], 0, v[188:189]
	global_load_lds_dwordx4 v[218:219], off
	v_lshl_add_u64 v[218:219], s[56:57], 0, v[190:191]
	s_add_i32 m0, s82, 0x2000
	s_nop 0
	global_load_lds_dwordx4 v[218:219], off
	v_lshl_add_u64 v[218:219], s[74:75], 0, v[184:185]
	s_mov_b32 m0, s31
	s_nop 0
	global_load_lds_dwordx4 v[218:219], off
	s_mov_b32 m0, s34
	s_nop 0
	global_load_lds_dwordx4 v[220:221], off
	s_waitcnt vmcnt(8)
	s_waitcnt lgkmcnt(0)
	s_barrier
; #define PG8_STAGE(bufoff, gbase, voff) do { _Pragma("unroll") for (int _i = 0; _i < 2; ++_i) \
;         __builtin_amdgcn_global_load_lds((const unsigned*)((const char*)(gbase) + (voff)[_i]), (PG8_LAS unsigned*)(lds + (bufoff) + ldsw + _i * 8192), 16, 0, 0); } while (0)
; #define PG8_LDA(dst, b, h) do { _Pragma("unroll") for (int m = 0; m < 4; ++m) _Pragma("unroll") for (int k = 0; k < 2; ++k) dst[m][k] = *(const PG8_LAS bf16x8*)(lds + PG8_SA(b, h) + aoff + m * 2048 + k * 1024); } while (0)
; #define PG8_LDB(dst, b, h) do { _Pragma("unroll") for (int n = 0; n < 2; ++n) _Pragma("unroll") for (int k = 0; k < 2; ++k) dst[n][k] = *(const PG8_LAS bf16x8*)(lds + PG8_SB(b, h) + boff + n * 2048 + k * 1024); } while (0)
; #define PG8_MMA(ai, bj, At, Bt) do { __builtin_amdgcn_s_setprio(1); _Pragma("unroll") for (int m = 0; m < 4; ++m) _Pragma("unroll") for (int n = 0; n < 2; ++n) _Pragma("unroll") for (int k = 0; k < 2; ++k) \
;         acc[ai][bj][m][n] = __builtin_amdgcn_mfma_f32_16x16x32_bf16(Bt[n][k], At[m][k], acc[ai][bj][m][n], 0, 0, 0); __builtin_amdgcn_s_setprio(0); } while (0)
; #define PG8_WAIT_V(n) asm volatile("s_waitcnt vmcnt(" #n ")" ::: "memory")
; #define PG8_WAIT_L(n) asm volatile("s_waitcnt lgkmcnt(" #n ")" ::: "memory")
; #define PG8_BAR __builtin_amdgcn_s_barrier()
; #define PG8_SCHED __builtin_amdgcn_sched_barrier(0)
; template <class Epi, class Sched, bool ALIGN_EPI = false, bool SP2 = false>
; __device__ __forceinline__ void gemm_phase(PG8_LAS unsigned char* lds, const Gemm g, const Sched& S, const Epi& E, const int tid_in) {
;     ...
;             PG8_WAIT_V(8); PG8_WAIT_L(0); PG8_BAR; PG8_MMA(1, 0, At, B0); PG8_MMA(1, 1, At, B1); PG8_BAR; PG8_SCHED;
;             PG8_LDB(B0, 1, 0); PG8_LDB(B1, 1, 1); PG8_SCHED; PG8_LDA(At, 1, 0); PG8_STAGE(PG8_SA(0, 1), a2 + hstep, voffA);
;             PG8_WAIT_V(8); PG8_WAIT_L(0); PG8_BAR; PG8_MMA(0, 0, At, B0); PG8_MMA(0, 1, At, B1); PG8_BAR; PG8_SCHED;
	s_waitcnt lgkmcnt(0)
	v_mfma_f32_16x16x32_bf16 v[60:63], v[92:95], v[160:163], 0
	v_mfma_f32_16x16x32_bf16 v[56:59], v[112:115], v[160:163], 0
	v_mfma_f32_16x16x32_bf16 v[44:47], v[92:95], v[168:171], 0
	v_mfma_f32_16x16x32_bf16 v[40:43], v[112:115], v[168:171], 0
	v_mfma_f32_16x16x32_bf16 v[28:31], v[92:95], v[176:179], 0
	v_mfma_f32_16x16x32_bf16 v[24:27], v[112:115], v[176:179], 0
	v_mfma_f32_16x16x32_bf16 v[12:15], v[92:95], v[200:203], 0
	v_mfma_f32_16x16x32_bf16 v[8:11], v[112:115], v[200:203], 0
	v_mfma_f32_16x16x32_bf16 v[60:63], v[100:103], v[164:167], v[60:63]
	v_mfma_f32_16x16x32_bf16 v[56:59], v[124:127], v[164:167], v[56:59]
	v_mfma_f32_16x16x32_bf16 v[44:47], v[100:103], v[172:175], v[44:47]
	v_mfma_f32_16x16x32_bf16 v[40:43], v[124:127], v[172:175], v[40:43]
	v_mfma_f32_16x16x32_bf16 v[28:31], v[100:103], v[180:183], v[28:31]
	v_mfma_f32_16x16x32_bf16 v[24:27], v[124:127], v[180:183], v[24:27]
	v_mfma_f32_16x16x32_bf16 v[12:15], v[100:103], v[210:213], v[12:15]
	v_mfma_f32_16x16x32_bf16 v[8:11], v[124:127], v[210:213], v[8:11]
	v_mfma_f32_16x16x32_bf16 v[52:55], v[136:139], v[160:163], 0
	v_mfma_f32_16x16x32_bf16 v[48:51], v[152:155], v[160:163], 0
	v_mfma_f32_16x16x32_bf16 v[36:39], v[136:139], v[168:171], 0
	v_mfma_f32_16x16x32_bf16 v[32:35], v[152:155], v[168:171], 0
	v_mfma_f32_16x16x32_bf16 v[20:23], v[136:139], v[176:179], 0
	v_mfma_f32_16x16x32_bf16 v[16:19], v[152:155], v[176:179], 0
	v_mfma_f32_16x16x32_bf16 v[4:7], v[136:139], v[200:203], 0
	v_mfma_f32_16x16x32_bf16 v[0:3], v[152:155], v[200:203], 0
	v_mfma_f32_16x16x32_bf16 v[52:55], v[148:151], v[164:167], v[52:55]
	v_mfma_f32_16x16x32_bf16 v[48:51], v[156:159], v[164:167], v[48:51]
	v_mfma_f32_16x16x32_bf16 v[36:39], v[148:151], v[172:175], v[36:39]
	v_mfma_f32_16x16x32_bf16 v[32:35], v[156:159], v[172:175], v[32:35]
	v_mfma_f32_16x16x32_bf16 v[20:23], v[148:151], v[180:183], v[20:23]
	v_mfma_f32_16x16x32_bf16 v[16:19], v[156:159], v[180:183], v[16:19]
	v_mfma_f32_16x16x32_bf16 v[4:7], v[148:151], v[210:213], v[4:7]
	v_mfma_f32_16x16x32_bf16 v[0:3], v[156:159], v[210:213], v[0:3]
	s_barrier
	s_add_i32 s82, 0, 0x18000
	s_add_i32 s83, 0, 0x1c000
	v_add_u32_e32 v124, s82, v205
	v_add_u32_e32 v156, s83, v205
	ds_read_b128 v[92:95], v124
	ds_read_b128 v[100:103], v124 offset:1024
	ds_read_b128 v[112:115], v124 offset:2048
	ds_read_b128 v[124:127], v124 offset:3072
	ds_read_b128 v[136:139], v156
	ds_read_b128 v[148:151], v156 offset:1024
	ds_read_b128 v[152:155], v156 offset:2048
	ds_read_b128 v[156:159], v156 offset:3072
	s_add_u32 s56, s74, 0xb0000
	s_addc_u32 s57, s75, 0
	s_mov_b32 m0, s35
	v_lshl_add_u64 v[222:223], s[56:57], 0, v[184:185]
	ds_read_b128 v[160:163], v209 offset:32768
	ds_read_b128 v[164:167], v209 offset:33792
	ds_read_b128 v[168:171], v209 offset:34816
	ds_read_b128 v[172:175], v209 offset:35840
	ds_read_b128 v[176:179], v209 offset:36864
	ds_read_b128 v[180:183], v209 offset:37888
	ds_read_b128 v[200:203], v209 offset:38912
	ds_read_b128 v[210:213], v209 offset:39936
	global_load_lds_dwordx4 v[222:223], off
	v_lshl_add_u64 v[222:223], s[56:57], 0, v[188:189]
	s_mov_b32 m0, s36
	s_nop 0
	global_load_lds_dwordx4 v[222:223], off
	s_waitcnt vmcnt(8)
	s_waitcnt lgkmcnt(0)
	s_barrier
	s_waitcnt lgkmcnt(0)
	v_mfma_f32_16x16x32_bf16 v[144:147], v[92:95], v[160:163], v[144:147]
	v_mfma_f32_16x16x32_bf16 v[140:143], v[112:115], v[160:163], v[140:143]
	v_mfma_f32_16x16x32_bf16 v[120:123], v[92:95], v[168:171], v[120:123]
	v_mfma_f32_16x16x32_bf16 v[116:119], v[112:115], v[168:171], v[116:119]
	v_mfma_f32_16x16x32_bf16 v[96:99], v[92:95], v[176:179], v[96:99]
	v_mfma_f32_16x16x32_bf16 v[88:91], v[112:115], v[176:179], v[88:91]
	v_mfma_f32_16x16x32_bf16 v[76:79], v[92:95], v[200:203], v[76:79]
	v_mfma_f32_16x16x32_bf16 v[72:75], v[112:115], v[200:203], v[72:75]
	v_mfma_f32_16x16x32_bf16 v[144:147], v[100:103], v[164:167], v[144:147]
	v_mfma_f32_16x16x32_bf16 v[140:143], v[124:127], v[164:167], v[140:143]
	v_mfma_f32_16x16x32_bf16 v[120:123], v[100:103], v[172:175], v[120:123]
	v_mfma_f32_16x16x32_bf16 v[116:119], v[124:127], v[172:175], v[116:119]
	v_mfma_f32_16x16x32_bf16 v[96:99], v[100:103], v[180:183], v[96:99]
	v_mfma_f32_16x16x32_bf16 v[88:91], v[124:127], v[180:183], v[88:91]
	v_mfma_f32_16x16x32_bf16 v[76:79], v[100:103], v[210:213], v[76:79]
	v_mfma_f32_16x16x32_bf16 v[72:75], v[124:127], v[210:213], v[72:75]
	v_mfma_f32_16x16x32_bf16 v[132:135], v[136:139], v[160:163], v[132:135]
	v_mfma_f32_16x16x32_bf16 v[128:131], v[152:155], v[160:163], v[128:131]
	v_mfma_f32_16x16x32_bf16 v[108:111], v[136:139], v[168:171], v[108:111]
	v_mfma_f32_16x16x32_bf16 v[104:107], v[152:155], v[168:171], v[104:107]
	v_mfma_f32_16x16x32_bf16 v[84:87], v[136:139], v[176:179], v[84:87]
	v_mfma_f32_16x16x32_bf16 v[80:83], v[152:155], v[176:179], v[80:83]
	v_mfma_f32_16x16x32_bf16 v[68:71], v[136:139], v[200:203], v[68:71]
	v_mfma_f32_16x16x32_bf16 v[64:67], v[152:155], v[200:203], v[64:67]
	v_mfma_f32_16x16x32_bf16 v[132:135], v[148:151], v[164:167], v[132:135]
	v_mfma_f32_16x16x32_bf16 v[128:131], v[156:159], v[164:167], v[128:131]
	v_mfma_f32_16x16x32_bf16 v[108:111], v[148:151], v[172:175], v[108:111]
	v_mfma_f32_16x16x32_bf16 v[104:107], v[156:159], v[172:175], v[104:107]
	v_mfma_f32_16x16x32_bf16 v[84:87], v[148:151], v[180:183], v[84:87]
	v_mfma_f32_16x16x32_bf16 v[80:83], v[156:159], v[180:183], v[80:83]
	v_mfma_f32_16x16x32_bf16 v[68:71], v[148:151], v[210:213], v[68:71]
	v_mfma_f32_16x16x32_bf16 v[64:67], v[156:159], v[210:213], v[64:67]
	s_barrier
; #define PG8_STAGE(bufoff, gbase, voff) do { _Pragma("unroll") for (int _i = 0; _i < 2; ++_i) \
;         __builtin_amdgcn_global_load_lds((const unsigned*)((const char*)(gbase) + (voff)[_i]), (PG8_LAS unsigned*)(lds + (bufoff) + ldsw + _i * 8192), 16, 0, 0); } while (0)
; #define PG8_LDA(dst, b, h) do { _Pragma("unroll") for (int m = 0; m < 4; ++m) _Pragma("unroll") for (int k = 0; k < 2; ++k) dst[m][k] = *(const PG8_LAS bf16x8*)(lds + PG8_SA(b, h) + aoff + m * 2048 + k * 1024); } while (0)
; #define PG8_MMA(ai, bj, At, Bt) do { __builtin_amdgcn_s_setprio(1); _Pragma("unroll") for (int m = 0; m < 4; ++m) _Pragma("unroll") for (int n = 0; n < 2; ++n) _Pragma("unroll") for (int k = 0; k < 2; ++k) \
;         acc[ai][bj][m][n] = __builtin_amdgcn_mfma_f32_16x16x32_bf16(Bt[n][k], At[m][k], acc[ai][bj][m][n], 0, 0, 0); __builtin_amdgcn_s_setprio(0); } while (0)
; #define PG8_WAIT_V(n) asm volatile("s_waitcnt vmcnt(" #n ")" ::: "memory")
; #define PG8_WAIT_L(n) asm volatile("s_waitcnt lgkmcnt(" #n ")" ::: "memory")
; #define PG8_BAR __builtin_amdgcn_s_barrier()
; #define PG8_SCHED __builtin_amdgcn_sched_barrier(0)
; template <class Epi, class Sched, bool ALIGN_EPI = false, bool SP2 = false>
; __device__ __forceinline__ void gemm_phase(PG8_LAS unsigned char* lds, const Gemm g, const Sched& S, const Epi& E, const int tid_in) {
;     ...
;             PG8_LDA(At, 1, 1); PG8_STAGE(PG8_SB(1, 0), b3, voffB); PG8_STAGE(PG8_SB(1, 1), b3 + hstep, voffB); PG8_STAGE(PG8_SA(1, 0), a3, voffA);
;             PG8_WAIT_V(8); PG8_WAIT_L(0); PG8_BAR; PG8_MMA(1, 0, At, B0); PG8_MMA(1, 1, At, B1); PG8_BAR; PG8_SCHED;
	s_add_i32 s56, s82, s30
	v_lshl_add_u64 v[214:215], v[214:215], 0, s[46:47]
	s_mov_b32 m0, s56
	ds_read_b128 v[160:163], v209 offset:49152
	ds_read_b128 v[164:167], v209 offset:50176
	ds_read_b128 v[168:171], v209 offset:51200
	ds_read_b128 v[172:175], v209 offset:52224
	ds_read_b128 v[176:179], v209 offset:53248
	ds_read_b128 v[180:183], v209 offset:54272
	ds_read_b128 v[200:203], v209 offset:55296
	ds_read_b128 v[210:213], v209 offset:56320
	global_load_lds_dwordx4 v[214:215], off
	s_add_i32 m0, s56, 0x2000
	s_add_u32 s0, s0, 0xb0080
	v_lshl_add_u64 v[214:215], v[216:217], 0, s[46:47]
	s_addc_u32 s1, s1, 0
	s_add_i32 s56, s83, s30
	global_load_lds_dwordx4 v[214:215], off
	v_lshl_add_u64 v[214:215], s[0:1], 0, v[186:187]
	s_mov_b32 m0, s56
	s_nop 0
	global_load_lds_dwordx4 v[214:215], off
	v_lshl_add_u64 v[214:215], s[0:1], 0, v[190:191]
	s_add_i32 m0, s56, 0x2000
	s_nop 0
	global_load_lds_dwordx4 v[214:215], off
	v_lshl_add_u64 v[214:215], v[218:219], 0, s[46:47]
	s_mov_b32 m0, s38
	s_nop 0
	global_load_lds_dwordx4 v[214:215], off
	v_lshl_add_u64 v[214:215], v[220:221], 0, s[46:47]
	s_mov_b32 m0, s39
	s_nop 0
	global_load_lds_dwordx4 v[214:215], off
	s_waitcnt vmcnt(8)
	s_waitcnt lgkmcnt(0)
	s_barrier
	s_waitcnt lgkmcnt(0)
	v_mfma_f32_16x16x32_bf16 v[60:63], v[92:95], v[160:163], v[60:63]
	v_mfma_f32_16x16x32_bf16 v[56:59], v[112:115], v[160:163], v[56:59]
	v_mfma_f32_16x16x32_bf16 v[44:47], v[92:95], v[168:171], v[44:47]
	v_mfma_f32_16x16x32_bf16 v[40:43], v[112:115], v[168:171], v[40:43]
	v_mfma_f32_16x16x32_bf16 v[28:31], v[92:95], v[176:179], v[28:31]
	v_mfma_f32_16x16x32_bf16 v[24:27], v[112:115], v[176:179], v[24:27]
	v_mfma_f32_16x16x32_bf16 v[12:15], v[92:95], v[200:203], v[12:15]
	v_mfma_f32_16x16x32_bf16 v[8:11], v[112:115], v[200:203], v[8:11]
	v_mfma_f32_16x16x32_bf16 v[60:63], v[100:103], v[164:167], v[60:63]
	v_mfma_f32_16x16x32_bf16 v[56:59], v[124:127], v[164:167], v[56:59]
	v_mfma_f32_16x16x32_bf16 v[44:47], v[100:103], v[172:175], v[44:47]
	v_mfma_f32_16x16x32_bf16 v[40:43], v[124:127], v[172:175], v[40:43]
	v_mfma_f32_16x16x32_bf16 v[28:31], v[100:103], v[180:183], v[28:31]
	v_mfma_f32_16x16x32_bf16 v[24:27], v[124:127], v[180:183], v[24:27]
	v_mfma_f32_16x16x32_bf16 v[12:15], v[100:103], v[210:213], v[12:15]
	v_mfma_f32_16x16x32_bf16 v[8:11], v[124:127], v[210:213], v[8:11]
	v_mfma_f32_16x16x32_bf16 v[52:55], v[136:139], v[160:163], v[52:55]
	v_mfma_f32_16x16x32_bf16 v[48:51], v[152:155], v[160:163], v[48:51]
	v_mfma_f32_16x16x32_bf16 v[36:39], v[136:139], v[168:171], v[36:39]
	v_mfma_f32_16x16x32_bf16 v[32:35], v[152:155], v[168:171], v[32:35]
	v_mfma_f32_16x16x32_bf16 v[20:23], v[136:139], v[176:179], v[20:23]
	v_mfma_f32_16x16x32_bf16 v[16:19], v[152:155], v[176:179], v[16:19]
	v_mfma_f32_16x16x32_bf16 v[4:7], v[136:139], v[200:203], v[4:7]
	v_mfma_f32_16x16x32_bf16 v[0:3], v[152:155], v[200:203], v[0:3]
	v_mfma_f32_16x16x32_bf16 v[52:55], v[148:151], v[164:167], v[52:55]
	v_mfma_f32_16x16x32_bf16 v[48:51], v[156:159], v[164:167], v[48:51]
	v_mfma_f32_16x16x32_bf16 v[36:39], v[148:151], v[172:175], v[36:39]
	v_mfma_f32_16x16x32_bf16 v[32:35], v[156:159], v[172:175], v[32:35]
	v_mfma_f32_16x16x32_bf16 v[20:23], v[148:151], v[180:183], v[20:23]
	v_mfma_f32_16x16x32_bf16 v[16:19], v[156:159], v[180:183], v[16:19]
	v_mfma_f32_16x16x32_bf16 v[4:7], v[148:151], v[210:213], v[4:7]
	v_mfma_f32_16x16x32_bf16 v[0:3], v[156:159], v[210:213], v[0:3]
	s_barrier
	s_add_i32 s81, s81, 2
	s_add_u32 s76, s76, 0x100
	s_addc_u32 s77, s77, 0
	s_cmp_gt_u32 s81, 41
	s_mov_b64 s[56:57], s[78:79]
	s_cbranch_scc0 .LBB0_1282
	s_branch .Lmy_kdone_4
	.p2alignl 6, 3212836864

; #define PG8_STAGE(bufoff, gbase, voff) do { _Pragma("unroll") for (int _i = 0; _i < 2; ++_i) \
;         __builtin_amdgcn_global_load_lds((const unsigned*)((const char*)(gbase) + (voff)[_i]), (PG8_LAS unsigned*)(lds + (bufoff) + ldsw + _i * 8192), 16, 0, 0); } while (0)
; #define PG8_LDA(dst, b, h) do { _Pragma("unroll") for (int m = 0; m < 4; ++m) _Pragma("unroll") for (int k = 0; k < 2; ++k) dst[m][k] = *(const PG8_LAS bf16x8*)(lds + PG8_SA(b, h) + aoff + m * 2048 + k * 1024); } while (0)
; #define PG8_LDB(dst, b, h) do { _Pragma("unroll") for (int n = 0; n < 2; ++n) _Pragma("unroll") for (int k = 0; k < 2; ++k) dst[n][k] = *(const PG8_LAS bf16x8*)(lds + PG8_SB(b, h) + boff + n * 2048 + k * 1024); } while (0)
; #define PG8_WAIT_V(n) asm volatile("s_waitcnt vmcnt(" #n ")" ::: "memory")
; #define PG8_WAIT_L(n) asm volatile("s_waitcnt lgkmcnt(" #n ")" ::: "memory")
; #define PG8_BAR __builtin_amdgcn_s_barrier()
; #define PG8_SCHED __builtin_amdgcn_sched_barrier(0)
; template <class Epi, class Sched, bool ALIGN_EPI = false, bool SP2 = false>
; __device__ __forceinline__ void gemm_phase(PG8_LAS unsigned char* lds, const Gemm g, const Sched& S, const Epi& E, const int tid_in) {
;     ...
;         const char* nA = has_next ? (const char*)g.A + (size_t)nxt.pm * tstep : cA; const char* nB = has_next ? (const char*)g.Bt + (size_t)nxt.pn * tstep : cB;
;         for (int t = 0; t < nt; t += 2) {
;             const bool last = (t == nt - 2);
;             const char* a1 = cA + (size_t)(t + 1) * kstep;
;             const char* a2 = last ? nA : cA + (size_t)(t + 2) * kstep; const char* b2 = last ? nB : cB + (size_t)(t + 2) * kstep;
;             const char* a3 = a2 + kstep; const char* b3 = b2 + kstep;
;             if (last && has_next) S.a_ready(nxt);
;             if constexpr (SP2) {
;             PG8_LDB(B0, 0, 0); PG8_LDB(B1, 0, 1); PG8_SCHED; PG8_LDA(At, 0, 0); PG8_STAGE(PG8_SA(1, 1), a1 + hstep, voffA);
;             PG8_WAIT_V(8); PG8_WAIT_L(0); PG8_BAR; PG8_MMA(0, 0, At, B0); PG8_MMA(0, 1, At, B1); PG8_BAR; PG8_SCHED;
;             PG8_LDA(At, 0, 1); PG8_STAGE(PG8_SB(0, 0), b2, voffB); PG8_STAGE(PG8_SB(0, 1), b2 + hstep, voffB); PG8_STAGE(PG8_SA(0, 0), a2, voffA);
;             PG8_WAIT_V(8); PG8_WAIT_L(0); PG8_BAR; PG8_MMA(1, 0, At, B0); PG8_MMA(1, 1, At, B1); PG8_BAR; PG8_SCHED;
.LBB0_1794:
	s_ashr_i32 s57, s56, 31
	s_lshl_b64 s[10:11], s[56:57], 19
	s_add_u32 s66, s5, s10
	s_addc_u32 s67, s30, s11
	s_and_b64 s[10:11], s[6:7], exec
	s_cselect_b32 s9, s67, s1
	s_cselect_b32 s14, s66, s0
	s_ashr_i32 s55, s54, 31
	s_lshl_b64 s[10:11], s[54:55], 19
	s_add_u32 s68, s3, s10
	s_addc_u32 s69, s4, s11
	s_and_b64 s[10:11], s[6:7], exec
	s_cselect_b32 s15, s69, s13
	s_cselect_b32 s16, s68, s12
	s_add_u32 s10, s0, 0x40080
	s_addc_u32 s11, s1, 0
	s_add_u32 s55, s12, 0x100
	v_mov_b32_e32 v0, 0
	s_addc_u32 s57, s13, 0
	s_mov_b32 s65, -2
	ds_read_b128 v[128:131], v204
	ds_read_b128 v[132:135], v204 offset:1024
	s_waitcnt lgkmcnt(0)
	ds_read_b128 v[156:159], v204 offset:2048
	ds_read_b128 v[160:163], v204 offset:3072
	ds_read_b128 v[164:167], v205
	ds_read_b128 v[168:171], v205 offset:1024
	ds_read_b128 v[172:175], v205 offset:2048
	ds_read_b128 v[176:179], v205 offset:3072
	s_add_u32 s0, s10, 0xfffc0080
	s_addc_u32 s1, s11, -1
	s_cmp_eq_u32 s65, 12
	s_cselect_b32 s13, s9, s1
	s_cselect_b32 s12, s14, s0
	s_cselect_b32 s1, s15, s57
	s_cselect_b32 s0, s16, s55
	v_lshl_add_u64 v[192:193], s[10:11], 0, v[148:149]
	s_add_i32 m0, s31, 0xc000
	ds_read_b128 v[180:183], v206
	ds_read_b128 v[184:187], v206 offset:1024
	ds_read_b128 v[188:191], v206 offset:2048
	ds_read_b128 v[210:213], v206 offset:3072
	ds_read_b128 v[214:217], v206 offset:4096
	ds_read_b128 v[218:221], v206 offset:5120
	ds_read_b128 v[222:225], v206 offset:6144
	ds_read_b128 v[226:229], v206 offset:7168
	global_load_lds_dwordx4 v[192:193], off
	v_lshl_add_u64 v[192:193], s[10:11], 0, v[150:151]
	s_add_i32 m0, s31, 0xe000
	s_nop 0
	global_load_lds_dwordx4 v[192:193], off
	s_waitcnt vmcnt(8)
	s_waitcnt lgkmcnt(0)
	s_barrier
	s_waitcnt lgkmcnt(0)
	v_mfma_f32_16x16x32_bf16 v[124:127], v[128:131], v[180:183], 0
	v_mfma_f32_16x16x32_bf16 v[120:123], v[156:159], v[180:183], 0
	v_mfma_f32_16x16x32_bf16 v[108:111], v[128:131], v[188:191], 0
	v_mfma_f32_16x16x32_bf16 v[104:107], v[156:159], v[188:191], 0
	v_mfma_f32_16x16x32_bf16 v[92:95], v[128:131], v[214:217], 0
	v_mfma_f32_16x16x32_bf16 v[88:91], v[156:159], v[214:217], 0
	v_mfma_f32_16x16x32_bf16 v[76:79], v[128:131], v[222:225], 0
	v_mfma_f32_16x16x32_bf16 v[72:75], v[156:159], v[222:225], 0
	v_mfma_f32_16x16x32_bf16 v[124:127], v[132:135], v[184:187], v[124:127]
	v_mfma_f32_16x16x32_bf16 v[120:123], v[160:163], v[184:187], v[120:123]
	v_mfma_f32_16x16x32_bf16 v[108:111], v[132:135], v[210:213], v[108:111]
	v_mfma_f32_16x16x32_bf16 v[104:107], v[160:163], v[210:213], v[104:107]
	v_mfma_f32_16x16x32_bf16 v[92:95], v[132:135], v[218:221], v[92:95]
	v_mfma_f32_16x16x32_bf16 v[88:91], v[160:163], v[218:221], v[88:91]
	v_mfma_f32_16x16x32_bf16 v[76:79], v[132:135], v[226:229], v[76:79]
	v_mfma_f32_16x16x32_bf16 v[72:75], v[160:163], v[226:229], v[72:75]
	v_mfma_f32_16x16x32_bf16 v[116:119], v[164:167], v[180:183], 0
	v_mfma_f32_16x16x32_bf16 v[112:115], v[172:175], v[180:183], 0
	v_mfma_f32_16x16x32_bf16 v[100:103], v[164:167], v[188:191], 0
	v_mfma_f32_16x16x32_bf16 v[96:99], v[172:175], v[188:191], 0
	v_mfma_f32_16x16x32_bf16 v[84:87], v[164:167], v[214:217], 0
	v_mfma_f32_16x16x32_bf16 v[80:83], v[172:175], v[214:217], 0
	v_mfma_f32_16x16x32_bf16 v[68:71], v[164:167], v[222:225], 0
	v_mfma_f32_16x16x32_bf16 v[64:67], v[172:175], v[222:225], 0
	v_mfma_f32_16x16x32_bf16 v[116:119], v[168:171], v[184:187], v[116:119]
	v_mfma_f32_16x16x32_bf16 v[112:115], v[176:179], v[184:187], v[112:115]
	v_mfma_f32_16x16x32_bf16 v[100:103], v[168:171], v[210:213], v[100:103]
	v_mfma_f32_16x16x32_bf16 v[96:99], v[176:179], v[210:213], v[96:99]
	v_mfma_f32_16x16x32_bf16 v[84:87], v[168:171], v[218:221], v[84:87]
	v_mfma_f32_16x16x32_bf16 v[80:83], v[176:179], v[218:221], v[80:83]
	v_mfma_f32_16x16x32_bf16 v[68:71], v[168:171], v[226:229], v[68:71]
	v_mfma_f32_16x16x32_bf16 v[64:67], v[176:179], v[226:229], v[64:67]
	s_barrier
	s_add_i32 s74, s49, s2
	v_lshl_add_u64 v[192:193], s[0:1], 0, v[136:137]
	s_mov_b32 m0, s74
	ds_read_b128 v[180:183], v206 offset:16384
	ds_read_b128 v[184:187], v206 offset:17408
	ds_read_b128 v[188:191], v206 offset:18432
	ds_read_b128 v[210:213], v206 offset:19456
	ds_read_b128 v[214:217], v206 offset:20480
	ds_read_b128 v[218:221], v206 offset:21504
	ds_read_b128 v[222:225], v206 offset:22528
	ds_read_b128 v[226:229], v206 offset:23552
	global_load_lds_dwordx4 v[192:193], off
	s_add_i32 m0, s74, 0x2000
	s_add_u32 s74, s0, 0x40000
	v_lshl_add_u64 v[230:231], s[0:1], 0, v[138:139]
	s_addc_u32 s75, s1, 0
	s_add_i32 s76, s50, s2
	global_load_lds_dwordx4 v[230:231], off
	v_lshl_add_u64 v[232:233], s[74:75], 0, v[136:137]
	s_mov_b32 m0, s76
	v_lshl_add_u64 v[234:235], s[12:13], 0, v[138:139]
	global_load_lds_dwordx4 v[232:233], off
	v_lshl_add_u64 v[232:233], s[74:75], 0, v[138:139]
	s_add_i32 m0, s76, 0x2000
	s_nop 0
	global_load_lds_dwordx4 v[232:233], off
	v_lshl_add_u64 v[232:233], s[12:13], 0, v[136:137]
	s_mov_b32 m0, s31
	s_nop 0
	global_load_lds_dwordx4 v[232:233], off
	s_mov_b32 m0, s34
	s_nop 0
	global_load_lds_dwordx4 v[234:235], off
	s_waitcnt vmcnt(8)
	s_waitcnt lgkmcnt(0)
	s_barrier
; #define PG8_STAGE(bufoff, gbase, voff) do { _Pragma("unroll") for (int _i = 0; _i < 2; ++_i) \
;         __builtin_amdgcn_global_load_lds((const unsigned*)((const char*)(gbase) + (voff)[_i]), (PG8_LAS unsigned*)(lds + (bufoff) + ldsw + _i * 8192), 16, 0, 0); } while (0)
; #define PG8_LDA(dst, b, h) do { _Pragma("unroll") for (int m = 0; m < 4; ++m) _Pragma("unroll") for (int k = 0; k < 2; ++k) dst[m][k] = *(const PG8_LAS bf16x8*)(lds + PG8_SA(b, h) + aoff + m * 2048 + k * 1024); } while (0)
; #define PG8_LDB(dst, b, h) do { _Pragma("unroll") for (int n = 0; n < 2; ++n) _Pragma("unroll") for (int k = 0; k < 2; ++k) dst[n][k] = *(const PG8_LAS bf16x8*)(lds + PG8_SB(b, h) + boff + n * 2048 + k * 1024); } while (0)
; #define PG8_MMA(ai, bj, At, Bt) do { __builtin_amdgcn_s_setprio(1); _Pragma("unroll") for (int m = 0; m < 4; ++m) _Pragma("unroll") for (int n = 0; n < 2; ++n) _Pragma("unroll") for (int k = 0; k < 2; ++k) \
;         acc[ai][bj][m][n] = __builtin_amdgcn_mfma_f32_16x16x32_bf16(Bt[n][k], At[m][k], acc[ai][bj][m][n], 0, 0, 0); __builtin_amdgcn_s_setprio(0); } while (0)
; #define PG8_WAIT_V(n) asm volatile("s_waitcnt vmcnt(" #n ")" ::: "memory")
; #define PG8_WAIT_L(n) asm volatile("s_waitcnt lgkmcnt(" #n ")" ::: "memory")
; #define PG8_BAR __builtin_amdgcn_s_barrier()
; #define PG8_SCHED __builtin_amdgcn_sched_barrier(0)
; template <class Epi, class Sched, bool ALIGN_EPI = false, bool SP2 = false>
; __device__ __forceinline__ void gemm_phase(PG8_LAS unsigned char* lds, const Gemm g, const Sched& S, const Epi& E, const int tid_in) {
;     ...
;             PG8_WAIT_V(8); PG8_WAIT_L(0); PG8_BAR; PG8_MMA(1, 0, At, B0); PG8_MMA(1, 1, At, B1); PG8_BAR; PG8_SCHED;
;             PG8_LDB(B0, 1, 0); PG8_LDB(B1, 1, 1); PG8_SCHED; PG8_LDA(At, 1, 0); PG8_STAGE(PG8_SA(0, 1), a2 + hstep, voffA);
;             PG8_WAIT_V(8); PG8_WAIT_L(0); PG8_BAR; PG8_MMA(0, 0, At, B0); PG8_MMA(0, 1, At, B1); PG8_BAR; PG8_SCHED;
	s_waitcnt lgkmcnt(0)
	v_mfma_f32_16x16x32_bf16 v[60:63], v[128:131], v[180:183], 0
	v_mfma_f32_16x16x32_bf16 v[56:59], v[156:159], v[180:183], 0
	v_mfma_f32_16x16x32_bf16 v[44:47], v[128:131], v[188:191], 0
	v_mfma_f32_16x16x32_bf16 v[40:43], v[156:159], v[188:191], 0
	v_mfma_f32_16x16x32_bf16 v[28:31], v[128:131], v[214:217], 0
	v_mfma_f32_16x16x32_bf16 v[24:27], v[156:159], v[214:217], 0
	v_mfma_f32_16x16x32_bf16 v[12:15], v[128:131], v[222:225], 0
	v_mfma_f32_16x16x32_bf16 v[8:11], v[156:159], v[222:225], 0
	v_mfma_f32_16x16x32_bf16 v[60:63], v[132:135], v[184:187], v[60:63]
	v_mfma_f32_16x16x32_bf16 v[56:59], v[160:163], v[184:187], v[56:59]
	v_mfma_f32_16x16x32_bf16 v[44:47], v[132:135], v[210:213], v[44:47]
	v_mfma_f32_16x16x32_bf16 v[40:43], v[160:163], v[210:213], v[40:43]
	v_mfma_f32_16x16x32_bf16 v[28:31], v[132:135], v[218:221], v[28:31]
	v_mfma_f32_16x16x32_bf16 v[24:27], v[160:163], v[218:221], v[24:27]
	v_mfma_f32_16x16x32_bf16 v[12:15], v[132:135], v[226:229], v[12:15]
	v_mfma_f32_16x16x32_bf16 v[8:11], v[160:163], v[226:229], v[8:11]
	v_mfma_f32_16x16x32_bf16 v[52:55], v[164:167], v[180:183], 0
	v_mfma_f32_16x16x32_bf16 v[48:51], v[172:175], v[180:183], 0
	v_mfma_f32_16x16x32_bf16 v[36:39], v[164:167], v[188:191], 0
	v_mfma_f32_16x16x32_bf16 v[32:35], v[172:175], v[188:191], 0
	v_mfma_f32_16x16x32_bf16 v[20:23], v[164:167], v[214:217], 0
	v_mfma_f32_16x16x32_bf16 v[16:19], v[172:175], v[214:217], 0
	v_mfma_f32_16x16x32_bf16 v[4:7], v[164:167], v[222:225], 0
	v_mfma_f32_16x16x32_bf16 v[0:3], v[172:175], v[222:225], 0
	v_mfma_f32_16x16x32_bf16 v[52:55], v[168:171], v[184:187], v[52:55]
	v_mfma_f32_16x16x32_bf16 v[48:51], v[176:179], v[184:187], v[48:51]
	v_mfma_f32_16x16x32_bf16 v[36:39], v[168:171], v[210:213], v[36:39]
	v_mfma_f32_16x16x32_bf16 v[32:35], v[176:179], v[210:213], v[32:35]
	v_mfma_f32_16x16x32_bf16 v[20:23], v[168:171], v[218:221], v[20:23]
	v_mfma_f32_16x16x32_bf16 v[16:19], v[176:179], v[218:221], v[16:19]
	v_mfma_f32_16x16x32_bf16 v[4:7], v[168:171], v[226:229], v[4:7]
	v_mfma_f32_16x16x32_bf16 v[0:3], v[176:179], v[226:229], v[0:3]
	s_barrier
	s_add_i32 s74, 0, 0x18000
	v_add_u32_e32 v140, s74, v195
	s_add_i32 s75, 0, 0x1c000
	ds_read_b128 v[128:131], v140
	ds_read_b128 v[132:135], v140 offset:1024
	ds_read_b128 v[156:159], v140 offset:2048
	ds_read_b128 v[160:163], v140 offset:3072
	v_add_u32_e32 v140, s75, v195
	ds_read_b128 v[164:167], v140
	ds_read_b128 v[168:171], v140 offset:1024
	ds_read_b128 v[172:175], v140 offset:2048
	ds_read_b128 v[176:179], v140 offset:3072
	s_add_u32 s12, s12, 0x40000
	s_addc_u32 s13, s13, 0
	s_mov_b32 m0, s35
	v_lshl_add_u64 v[236:237], s[12:13], 0, v[136:137]
	ds_read_b128 v[180:183], v206 offset:32768
	ds_read_b128 v[184:187], v206 offset:33792
	ds_read_b128 v[188:191], v206 offset:34816
	ds_read_b128 v[210:213], v206 offset:35840
	ds_read_b128 v[214:217], v206 offset:36864
	ds_read_b128 v[218:221], v206 offset:37888
	ds_read_b128 v[222:225], v206 offset:38912
	ds_read_b128 v[226:229], v206 offset:39936
	global_load_lds_dwordx4 v[236:237], off
	v_lshl_add_u64 v[236:237], s[12:13], 0, v[138:139]
	s_mov_b32 m0, s36
	s_nop 0
	global_load_lds_dwordx4 v[236:237], off
	s_waitcnt vmcnt(8)
	s_waitcnt lgkmcnt(0)
	s_barrier
	s_waitcnt lgkmcnt(0)
	v_mfma_f32_16x16x32_bf16 v[124:127], v[128:131], v[180:183], v[124:127]
	v_mfma_f32_16x16x32_bf16 v[120:123], v[156:159], v[180:183], v[120:123]
	v_mfma_f32_16x16x32_bf16 v[108:111], v[128:131], v[188:191], v[108:111]
	v_mfma_f32_16x16x32_bf16 v[104:107], v[156:159], v[188:191], v[104:107]
	v_mfma_f32_16x16x32_bf16 v[92:95], v[128:131], v[214:217], v[92:95]
	v_mfma_f32_16x16x32_bf16 v[88:91], v[156:159], v[214:217], v[88:91]
	v_mfma_f32_16x16x32_bf16 v[76:79], v[128:131], v[222:225], v[76:79]
	v_mfma_f32_16x16x32_bf16 v[72:75], v[156:159], v[222:225], v[72:75]
	v_mfma_f32_16x16x32_bf16 v[124:127], v[132:135], v[184:187], v[124:127]
	v_mfma_f32_16x16x32_bf16 v[120:123], v[160:163], v[184:187], v[120:123]
	v_mfma_f32_16x16x32_bf16 v[108:111], v[132:135], v[210:213], v[108:111]
	v_mfma_f32_16x16x32_bf16 v[104:107], v[160:163], v[210:213], v[104:107]
	v_mfma_f32_16x16x32_bf16 v[92:95], v[132:135], v[218:221], v[92:95]
	v_mfma_f32_16x16x32_bf16 v[88:91], v[160:163], v[218:221], v[88:91]
	v_mfma_f32_16x16x32_bf16 v[76:79], v[132:135], v[226:229], v[76:79]
	v_mfma_f32_16x16x32_bf16 v[72:75], v[160:163], v[226:229], v[72:75]
	v_mfma_f32_16x16x32_bf16 v[116:119], v[164:167], v[180:183], v[116:119]
	v_mfma_f32_16x16x32_bf16 v[112:115], v[172:175], v[180:183], v[112:115]
	v_mfma_f32_16x16x32_bf16 v[100:103], v[164:167], v[188:191], v[100:103]
	v_mfma_f32_16x16x32_bf16 v[96:99], v[172:175], v[188:191], v[96:99]
	v_mfma_f32_16x16x32_bf16 v[84:87], v[164:167], v[214:217], v[84:87]
	v_mfma_f32_16x16x32_bf16 v[80:83], v[172:175], v[214:217], v[80:83]
	v_mfma_f32_16x16x32_bf16 v[68:71], v[164:167], v[222:225], v[68:71]
	v_mfma_f32_16x16x32_bf16 v[64:67], v[172:175], v[222:225], v[64:67]
	v_mfma_f32_16x16x32_bf16 v[116:119], v[168:171], v[184:187], v[116:119]
	v_mfma_f32_16x16x32_bf16 v[112:115], v[176:179], v[184:187], v[112:115]
	v_mfma_f32_16x16x32_bf16 v[100:103], v[168:171], v[210:213], v[100:103]
	v_mfma_f32_16x16x32_bf16 v[96:99], v[176:179], v[210:213], v[96:99]
	v_mfma_f32_16x16x32_bf16 v[84:87], v[168:171], v[218:221], v[84:87]
	v_mfma_f32_16x16x32_bf16 v[80:83], v[176:179], v[218:221], v[80:83]
	v_mfma_f32_16x16x32_bf16 v[68:71], v[168:171], v[226:229], v[68:71]
	v_mfma_f32_16x16x32_bf16 v[64:67], v[176:179], v[226:229], v[64:67]
	s_barrier
; #define PG8_STAGE(bufoff, gbase, voff) do { _Pragma("unroll") for (int _i = 0; _i < 2; ++_i) \
;         __builtin_amdgcn_global_load_lds((const unsigned*)((const char*)(gbase) + (voff)[_i]), (PG8_LAS unsigned*)(lds + (bufoff) + ldsw + _i * 8192), 16, 0, 0); } while (0)
; #define PG8_LDA(dst, b, h) do { _Pragma("unroll") for (int m = 0; m < 4; ++m) _Pragma("unroll") for (int k = 0; k < 2; ++k) dst[m][k] = *(const PG8_LAS bf16x8*)(lds + PG8_SA(b, h) + aoff + m * 2048 + k * 1024); } while (0)
; #define PG8_MMA(ai, bj, At, Bt) do { __builtin_amdgcn_s_setprio(1); _Pragma("unroll") for (int m = 0; m < 4; ++m) _Pragma("unroll") for (int n = 0; n < 2; ++n) _Pragma("unroll") for (int k = 0; k < 2; ++k) \
;         acc[ai][bj][m][n] = __builtin_amdgcn_mfma_f32_16x16x32_bf16(Bt[n][k], At[m][k], acc[ai][bj][m][n], 0, 0, 0); __builtin_amdgcn_s_setprio(0); } while (0)
; #define PG8_WAIT_V(n) asm volatile("s_waitcnt vmcnt(" #n ")" ::: "memory")
; #define PG8_WAIT_L(n) asm volatile("s_waitcnt lgkmcnt(" #n ")" ::: "memory")
; #define PG8_BAR __builtin_amdgcn_s_barrier()
; #define PG8_SCHED __builtin_amdgcn_sched_barrier(0)
; template <class Epi, class Sched, bool ALIGN_EPI = false, bool SP2 = false>
; __device__ __forceinline__ void gemm_phase(PG8_LAS unsigned char* lds, const Gemm g, const Sched& S, const Epi& E, const int tid_in) {
;     ...
;             PG8_LDA(At, 1, 1); PG8_STAGE(PG8_SB(1, 0), b3, voffB); PG8_STAGE(PG8_SB(1, 1), b3 + hstep, voffB); PG8_STAGE(PG8_SA(1, 0), a3, voffA);
;             PG8_WAIT_V(8); PG8_WAIT_L(0); PG8_BAR; PG8_MMA(1, 0, At, B0); PG8_MMA(1, 1, At, B1); PG8_BAR; PG8_SCHED;
	s_add_i32 s12, s74, s2
	v_lshl_add_u64 v[192:193], v[192:193], 0, s[26:27]
	s_mov_b32 m0, s12
	ds_read_b128 v[180:183], v206 offset:49152
	ds_read_b128 v[184:187], v206 offset:50176
	ds_read_b128 v[188:191], v206 offset:51200
	ds_read_b128 v[210:213], v206 offset:52224
	ds_read_b128 v[214:217], v206 offset:53248
	ds_read_b128 v[218:221], v206 offset:54272
	ds_read_b128 v[222:225], v206 offset:55296
	ds_read_b128 v[226:229], v206 offset:56320
	global_load_lds_dwordx4 v[192:193], off
	s_add_i32 m0, s12, 0x2000
	s_add_u32 s0, s0, 0x40080
	v_lshl_add_u64 v[192:193], v[230:231], 0, s[26:27]
	s_addc_u32 s1, s1, 0
	s_add_i32 s12, s75, s2
	global_load_lds_dwordx4 v[192:193], off
	v_lshl_add_u64 v[192:193], s[0:1], 0, v[136:137]
	s_mov_b32 m0, s12
	s_nop 0
	global_load_lds_dwordx4 v[192:193], off
	v_lshl_add_u64 v[192:193], s[0:1], 0, v[138:139]
	s_add_i32 m0, s12, 0x2000
	s_nop 0
	global_load_lds_dwordx4 v[192:193], off
	v_lshl_add_u64 v[192:193], v[232:233], 0, s[26:27]
	s_mov_b32 m0, s96
	s_nop 0
	global_load_lds_dwordx4 v[192:193], off
	v_lshl_add_u64 v[192:193], v[234:235], 0, s[26:27]
	s_mov_b32 m0, s97
	s_nop 0
	global_load_lds_dwordx4 v[192:193], off
	s_waitcnt vmcnt(8)
	s_waitcnt lgkmcnt(0)
	s_barrier
	s_waitcnt lgkmcnt(0)
	v_mfma_f32_16x16x32_bf16 v[60:63], v[128:131], v[180:183], v[60:63]
	v_mfma_f32_16x16x32_bf16 v[56:59], v[156:159], v[180:183], v[56:59]
	v_mfma_f32_16x16x32_bf16 v[44:47], v[128:131], v[188:191], v[44:47]
	v_mfma_f32_16x16x32_bf16 v[40:43], v[156:159], v[188:191], v[40:43]
	v_mfma_f32_16x16x32_bf16 v[28:31], v[128:131], v[214:217], v[28:31]
	v_mfma_f32_16x16x32_bf16 v[24:27], v[156:159], v[214:217], v[24:27]
	v_mfma_f32_16x16x32_bf16 v[12:15], v[128:131], v[222:225], v[12:15]
	v_mfma_f32_16x16x32_bf16 v[8:11], v[156:159], v[222:225], v[8:11]
	v_mfma_f32_16x16x32_bf16 v[60:63], v[132:135], v[184:187], v[60:63]
	v_mfma_f32_16x16x32_bf16 v[56:59], v[160:163], v[184:187], v[56:59]
	v_mfma_f32_16x16x32_bf16 v[44:47], v[132:135], v[210:213], v[44:47]
	v_mfma_f32_16x16x32_bf16 v[40:43], v[160:163], v[210:213], v[40:43]
	v_mfma_f32_16x16x32_bf16 v[28:31], v[132:135], v[218:221], v[28:31]
	v_mfma_f32_16x16x32_bf16 v[24:27], v[160:163], v[218:221], v[24:27]
	v_mfma_f32_16x16x32_bf16 v[12:15], v[132:135], v[226:229], v[12:15]
	v_mfma_f32_16x16x32_bf16 v[8:11], v[160:163], v[226:229], v[8:11]
	v_mfma_f32_16x16x32_bf16 v[52:55], v[164:167], v[180:183], v[52:55]
	v_mfma_f32_16x16x32_bf16 v[48:51], v[172:175], v[180:183], v[48:51]
	v_mfma_f32_16x16x32_bf16 v[36:39], v[164:167], v[188:191], v[36:39]
	v_mfma_f32_16x16x32_bf16 v[32:35], v[172:175], v[188:191], v[32:35]
	v_mfma_f32_16x16x32_bf16 v[20:23], v[164:167], v[214:217], v[20:23]
	v_mfma_f32_16x16x32_bf16 v[16:19], v[172:175], v[214:217], v[16:19]
	v_mfma_f32_16x16x32_bf16 v[4:7], v[164:167], v[222:225], v[4:7]
	v_mfma_f32_16x16x32_bf16 v[0:3], v[172:175], v[222:225], v[0:3]
	v_mfma_f32_16x16x32_bf16 v[52:55], v[168:171], v[184:187], v[52:55]
	v_mfma_f32_16x16x32_bf16 v[48:51], v[176:179], v[184:187], v[48:51]
	v_mfma_f32_16x16x32_bf16 v[36:39], v[168:171], v[210:213], v[36:39]
	v_mfma_f32_16x16x32_bf16 v[32:35], v[176:179], v[210:213], v[32:35]
	v_mfma_f32_16x16x32_bf16 v[20:23], v[168:171], v[218:221], v[20:23]
	v_mfma_f32_16x16x32_bf16 v[16:19], v[176:179], v[218:221], v[16:19]
	v_mfma_f32_16x16x32_bf16 v[4:7], v[168:171], v[226:229], v[4:7]
	v_mfma_f32_16x16x32_bf16 v[0:3], v[176:179], v[226:229], v[0:3]
	s_barrier
	s_add_i32 s65, s65, 2
	s_add_u32 s10, s10, 0x100
	s_addc_u32 s11, s11, 0
	s_add_u32 s55, s55, 0x100
	s_addc_u32 s57, s57, 0
	s_cmp_gt_u32 s65, 13
	s_cbranch_scc0 .LBB0_1795
	s_branch .Lmy_kdone_5
	.p2alignl 6, 3212836864

; __device__ __forceinline__ void cmp_sample_unit(const CmpArgs& a, int b, int half, LAS unsigned char* lds, int tid) {
;     ...
; #pragma unroll 1
;     for (int ep = 0; ep < 16; ++ep) { const int e = ep & 7, pass = ep >> 3;
.LBB0_2487:
	s_addk_i32 s25, 0x80
	s_addk_i32 s26, 0x800
	s_cmp_eq_u32 s28, 16
	s_mov_b32 s27, s28
	s_cbranch_scc1 .LBB0_2496
	.p2alignl 6, 3212836864

; __device__ __forceinline__ void attn_sample_item(const SmpArgs& a, int b, int g, LAS unsigned char* lds, int tid) {
;     ...
;     if (tid < 64) { unsigned sp = 0u;
;         while ((unsigned)__builtin_amdgcn_readfirstlane((int)__hip_atomic_load(a.flags + 64 * b, __ATOMIC_RELAXED, __HIP_MEMORY_SCOPE_AGENT)) < 2u) { __builtin_amdgcn_s_sleep(2); if (++sp > (1u << 20)) break; }
;         __builtin_amdgcn_fence(__ATOMIC_ACQUIRE, "agent"); asm volatile("s_waitcnt vmcnt(0)" ::: "memory"); }
.LBB0_2502:
	s_andn2_b64 vcc, exec, s[8:9]
	s_cbranch_vccz .LBB0_2505
	.p2alignl 6, 3212836864

; __device__ __forceinline__ void attn_sample_item(const SmpArgs& a, int b, int g, LAS unsigned char* lds, int tid) {
;     ...
;     if (tid < 64) { float s = 0.f;
;         if (tid < 33) for (int nn = 4 * tid - 1; nn <= 4 * tid + 3; ++nn) if (nn >= 0 && nn < 127) s += (sc[nn] + sc[128 + nn]) + (sc[256 + nn] + sc[384 + nn]);
;         const bool valid = tid < 33, forced = (tid == 0) || (tid == 32) || (tid == 31);
;         const unsigned key = valid ? __float_as_uint(s + (forced ? 1e4f : 0.f)) : 0u;
;         unsigned thr = 0u;
; #pragma unroll 1
.LBB0_2559:
	s_or_b64 exec, exec, s[22:23]
	v_add_f32_e32 v2, v2, v3
	s_mov_b32 s20, 0
	v_cndmask_b32_e32 v2, 0, v2, vcc
	s_mov_b32 s14, 30
	.p2alignl 6, 3212836864

; __device__ __forceinline__ void attn_sample_item(const SmpArgs& a, int b, int g, LAS unsigned char* lds, int tid) {
;     ...
;         const unsigned long long gt = __ballot(key > thr); unsigned long long eq = __ballot(key == thr);
;         int need = 16 - __popcll(gt); unsigned long long sel = gt;
.Lmy_rs_go_i:
	v_cmp_lt_u32_e64 s[14:15], s20, v2
	v_cmp_eq_u32_e64 s[20:21], s20, v2
	s_bcnt1_i32_b64 s54, s[14:15]
	s_cmp_eq_u64 s[20:21], 0
	v_cmp_gt_u64_e64 s[22:23], s[54:55], 15
	s_cselect_b64 s[24:25], -1, 0
	s_or_b64 s[22:23], s[22:23], s[24:25]
	s_and_b64 vcc, exec, s[22:23]
	s_cbranch_vccnz .LBB0_2564
	s_sub_i32 s22, 16, s54
	.p2alignl 6, 3212836864

; #define LAS __attribute__((address_space(3)))
; __device__ __forceinline__ int nth_bit(unsigned long long m, int n) { for (int x = 0; x < n; ++x) m &= m - 1ull; return __builtin_ctzll(m); }
; __device__ __forceinline__ void attn_sample_item(const SmpArgs& a, int b, int g, LAS unsigned char* lds, int tid) {
;     ...
;     const unsigned long long mask = *maskp;
; #pragma unroll
;     for (int h = 0; h < 4; ++h) qv[h] = *(const LAS f32x4*)(qr + h * 64 + 4 * d4);
;     float oslc;
;     { float m[4], l[4]; f32x4 o[4];
; #pragma unroll
;       for (int h = 0; h < 4; ++h) { m[h] = -1e30f; l[h] = 0.f; o[h] = (f32x4){0.f, 0.f, 0.f, 0.f}; }
; #pragma unroll 1
;       for (int bi = 0; bi < 2; ++bi) { const int j = nth_bit(mask, 2 * w + bi);
.LBB0_2640:
	s_or_b64 exec, exec, s[0:1]
	s_lshl_b64 s[0:1], s[28:29], 11
	s_lshl_b64 s[14:15], s[28:29], 20
	s_add_u32 s0, s97, s0
	s_addc_u32 s1, s40, s1
	s_lshl_b32 s16, s54, 2
	s_add_u32 s0, s0, s16
	s_addc_u32 s1, s1, 0
	s_add_u32 s14, s60, s14
	s_addc_u32 s15, s61, s15
	s_add_u32 s88, s14, s16
	v_or_b32_e32 v96, v56, v57
	s_addc_u32 s89, s15, 0
	s_mov_b32 s16, 0
	s_mov_b64 s[14:15], -1
	v_mov_b32_e32 v5, 0xf149f2ca
	v_mov_b32_e32 v94, 0xf149f2ca
	v_mov_b32_e32 v95, 0xf149f2ca
	v_mov_b32_e32 v97, 0xf149f2ca
	v_mov_b32_e32 v59, v58
	v_mov_b32_e32 v56, v58
	v_mov_b32_e32 v57, v58
	v_mov_b32_e32 v62, v58
	v_mov_b32_e32 v63, v58
	v_mov_b32_e32 v64, v58
	v_mov_b32_e32 v65, v58
	v_mov_b32_e32 v66, v58
	v_mov_b32_e32 v67, v58
	v_mov_b32_e32 v68, v58
	v_mov_b32_e32 v69, v58
	v_mov_b32_e32 v72, v58
	v_mov_b32_e32 v73, v58
	v_mov_b32_e32 v74, v58
	v_mov_b32_e32 v75, v58
	v_mov_b32_e32 v60, v58
	v_mov_b32_e32 v61, v58
	v_mov_b32_e32 v70, v58
	v_mov_b32_e32 v71, v58
	s_barrier
	.p2alignl 6, 3212836864

; #define LAS __attribute__((address_space(3)))
; __device__ __forceinline__ void attn_build_ckcv(const AttnArgs& a, int ng, LAS unsigned char* lds, int tid) {
;     asm volatile("" : "+v"(tid));
;     const int c = tid >> 1, e0 = (tid & 1) * 32; const int cc = c < 255 ? c : 254; const float keep = c < 255 ? 1.0f : 0.0f;
;     const float* pk = a.PQ + ((size_t)CMP_ROWS_S + (size_t)ng * 256 + cc) * 256 + e0; const float* pv = a.PQ + ((size_t)CMP_ROWS_S + (size_t)(16 + ng) * 256 + cc) * 256 + e0;
;     const float* cb = a.CB + e0;
;     LAS unsigned char* dk = lds + A_CK + (e0 >> 3) * 4096 + c * 16; LAS unsigned char* dv = lds + A_CV + ((e0 >> 5) * 16 + (c >> 4)) * 1024 + (c & 15) * 64;
; #pragma unroll 2
.LBB0_2672:
	v_mbcnt_lo_u32_b32 v0, -1, 0
	v_mbcnt_hi_u32_b32 v0, -1, v0
	s_movk_i32 s0, 0xff
	v_add_u32_e32 v0, s33, v0
	s_ashr_i32 s29, s28, 31
	s_waitcnt vmcnt(4)
	v_ashrrev_i32_e32 v3, 1, v0
	v_cmp_gt_i32_e32 vcc, s0, v3
	v_lshlrev_b32_e32 v11, 5, v0
	s_lshl_b64 s[0:1], s[28:29], 18
	v_cndmask_b32_e32 v4, v231, v3, vcc
	v_ashrrev_i32_e32 v5, 31, v4
	v_lshlrev_b64 v[8:9], 10, v[4:5]
	v_lshlrev_b32_e32 v4, 14, v0
	v_lshlrev_b32_e32 v0, 7, v0
	v_and_b32_e32 v0, 0x80, v0
	v_lshl_add_u64 v[8:9], s[0:1], 0, v[8:9]
	v_and_b32_e32 v12, 0x4000, v4
	v_lshl_add_u64 v[6:7], s[38:39], 0, v[0:1]
	v_or_b32_e32 v8, v8, v0
	v_and_b32_e32 v0, 0xfffffc00, v11
	v_lshlrev_b32_e32 v13, 6, v3
	v_add_u32_e32 v0, v12, v0
	s_movk_i32 s0, 0x3c0
	v_cndmask_b32_e64 v2, 0, 1.0, vcc
	v_lshlrev_b32_e32 v4, 4, v3
	v_and_or_b32 v0, v13, s0, v0
	s_add_i32 s0, 0, 0x8000
	v_add3_u32 v10, 0, v12, v4
	v_mov_b32_e32 v3, v2
	v_mov_b32_e32 v4, v2
	v_mov_b32_e32 v5, v2
	v_lshl_add_u64 v[8:9], s[38:39], 0, v[8:9]
	v_add_u32_e32 v0, s0, v0
	s_mov_b64 s[6:7], 0
	.p2alignl 6, 3212836864

; #define LAS __attribute__((address_space(3)))
; __device__ __forceinline__ void attn_prompt_unit(const AttnArgs& a, int n, int g, int qt, LAS unsigned char* lds, int tid) {
;     ...
;         const int tk8 = lane >> 3, sub = lane & 7; const int tt = tb + tk8, cur = tt >> 6;
;         const f32x4 i0 = *(const LAS f32x4*)(impb + tk8 * 64 + 8 * sub), i1 = *(const LAS f32x4*)(impb + tk8 * 64 + 8 * sub + 4);
;         unsigned key[8];
; #pragma unroll
;         for (int e = 0; e < 8; ++e) { const int j = 8 * sub + e; const float imp = e < 4 ? i0[e & 3] : i1[e & 3];
;             const bool valid = j <= cur, forced = (j == 0) || (j == cur) || (j == cur - 1);
;             key[e] = valid ? __float_as_uint(imp + (forced ? 1e4f : 0.f)) : 0u; }
;         unsigned thr = 0u;
; #pragma unroll 1
.LBB0_2791:
	s_or_b64 exec, exec, s[0:1]
	v_lshlrev_b32_e32 v2, 5, v134
	v_and_b32_e32 v14, 56, v101
	v_and_b32_e32 v2, 0x700, v2
	v_lshlrev_b32_e32 v3, 2, v14
	v_ashrrev_i32_e32 v0, 6, v218
	v_add3_u32 v2, v4, v2, v3
	ds_read_b128 v[162:165], v217
	ds_read_b128 v[166:169], v217 offset:32
	ds_read_b128 v[170:173], v217 offset:64
	ds_read_b128 v[174:177], v217 offset:96
	ds_read_b128 v[6:9], v2
	ds_read_b128 v[10:13], v2 offset:16
	v_add_u32_e32 v2, -1, v0
	v_cmp_eq_u32_e32 vcc, 0, v14
	v_cmp_eq_u32_e64 s[8:9], v14, v0
	s_or_b64 s[0:1], vcc, s[8:9]
	v_cmp_eq_u32_e32 vcc, v14, v2
	s_or_b64 vcc, s[0:1], vcc
	v_mov_b32_e32 v3, 0
	v_cndmask_b32_e32 v5, 0, v230, vcc
	s_waitcnt lgkmcnt(1)
	v_add_f32_e32 v5, v5, v6
	v_or_b32_e32 v6, 1, v14
	v_cmp_eq_u32_e64 s[8:9], v6, v0
	v_cmp_eq_u32_e64 s[10:11], v6, v2
	s_or_b64 s[8:9], s[8:9], s[10:11]
	v_cndmask_b32_e64 v6, 0, v230, s[8:9]
	v_add_f32_e32 v6, v6, v7
	v_or_b32_e32 v7, 2, v14
	v_cmp_eq_u32_e64 s[8:9], v7, v0
	v_cmp_eq_u32_e64 s[12:13], v7, v2
	s_or_b64 s[8:9], s[8:9], s[12:13]
	v_cndmask_b32_e64 v15, 0, v230, s[8:9]
	v_add_f32_e32 v8, v15, v8
	v_cmp_gt_i32_e64 s[12:13], v7, v0
	v_cmp_le_i32_e32 vcc, v14, v0
	v_cmp_lt_i32_e64 s[10:11], v14, v0
	v_cndmask_b32_e64 v7, v8, 0, s[12:13]
	v_or_b32_e32 v8, 3, v14
	v_cmp_eq_u32_e64 s[8:9], v8, v0
	v_cmp_eq_u32_e64 s[14:15], v8, v2
	s_or_b64 s[8:9], s[8:9], s[14:15]
	v_cndmask_b32_e64 v15, 0, v230, s[8:9]
	v_add_f32_e32 v9, v15, v9
	v_cmp_gt_i32_e64 s[14:15], v8, v0
	v_cndmask_b32_e32 v5, 0, v5, vcc
	v_cndmask_b32_e64 v6, 0, v6, s[10:11]
	v_cndmask_b32_e64 v8, v9, 0, s[14:15]
	v_or_b32_e32 v9, 4, v14
	v_cmp_eq_u32_e64 s[8:9], v9, v0
	v_cmp_eq_u32_e64 s[16:17], v9, v2
	s_or_b64 s[8:9], s[8:9], s[16:17]
	v_cndmask_b32_e64 v15, 0, v230, s[8:9]
	s_waitcnt lgkmcnt(0)
	v_add_f32_e32 v10, v15, v10
	v_cmp_gt_i32_e64 s[16:17], v9, v0
	s_mov_b32 s0, 30
	s_nop 0
	v_cndmask_b32_e64 v9, v10, 0, s[16:17]
	v_or_b32_e32 v10, 5, v14
	v_cmp_eq_u32_e64 s[8:9], v10, v0
	v_cmp_eq_u32_e64 s[18:19], v10, v2
	s_or_b64 s[8:9], s[8:9], s[18:19]
	v_cndmask_b32_e64 v15, 0, v230, s[8:9]
	v_add_f32_e32 v11, v15, v11
	v_cmp_gt_i32_e64 s[18:19], v10, v0
	s_nop 1
	v_cndmask_b32_e64 v10, v11, 0, s[18:19]
	v_or_b32_e32 v11, 6, v14
	v_cmp_eq_u32_e64 s[8:9], v11, v0
	v_cmp_eq_u32_e64 s[20:21], v11, v2
	s_or_b64 s[8:9], s[8:9], s[20:21]
	v_cndmask_b32_e64 v15, 0, v230, s[8:9]
	v_add_f32_e32 v12, v15, v12
	v_cmp_gt_i32_e64 s[20:21], v11, v0
	s_nop 1
	v_cndmask_b32_e64 v11, v12, 0, s[20:21]
	v_or_b32_e32 v12, 7, v14
	v_cmp_eq_u32_e64 s[8:9], v12, v0
	v_cmp_eq_u32_e64 s[22:23], v12, v2
	s_or_b64 s[8:9], s[8:9], s[22:23]
	v_cndmask_b32_e64 v14, 0, v230, s[8:9]
	v_add_f32_e32 v13, v14, v13
	v_cmp_gt_i32_e64 s[22:23], v12, v0
	s_nop 1
	v_cndmask_b32_e64 v12, v13, 0, s[22:23]
	.p2alignl 6, 3212836864

; #define LAS __attribute__((address_space(3)))
; #define FB_ISSUE(T, S) do { __builtin_amdgcn_global_load_lds((const unsigned*)(ksrc + (size_t)(T) * 4096), (LAS unsigned*)(ring + (S) * A_SLOT), 16, 0, 0); \
;                             __builtin_amdgcn_global_load_lds((const unsigned*)(vsrc + (size_t)(T) * 4096), (LAS unsigned*)(ring + (S) * A_SLOT + 8192), 16, 0, 0); } while (0)
; template <int MODE> ...
;     ...
;     for (int tile = tile_lo; tile <= tile_hi; ++tile) {
;         if (tile < tile_hi) asm volatile("s_waitcnt vmcnt(2)" ::: "memory"); else asm volatile("s_waitcnt vmcnt(0)" ::: "memory");
;         __builtin_amdgcn_s_barrier(); asm volatile("" ::: "memory");
;         if (tile + 2 <= tile_hi) FB_ISSUE(tile + 2, sn);
;         const LAS unsigned char* kt = kbase + sc * A_SLOT; const LAS unsigned char* vt = vbase + sc * A_SLOT;
;         sc = sc == 2 ? 0 : sc + 1; sn = sn == 2 ? 0 : sn + 1;
.LBB0_2815:
	s_add_i32 s0, s23, 1
	s_cmp_lg_u32 s23, 2
	s_cselect_b32 s23, s0, 0
	s_add_i32 s0, s54, 1
	s_cmp_lg_u32 s54, 2
	s_cselect_b32 s54, s0, 0
	s_waitcnt lgkmcnt(0)
	s_add_u32 s16, s16, 1
	s_addc_u32 s17, s17, 0
	v_lshl_add_u64 v[142:143], v[142:143], 0, s[82:83]
	s_cmp_eq_u32 s25, s16
	v_lshl_add_u64 v[144:145], v[144:145], 0, s[82:83]
	s_cbranch_scc1 .LBB0_2830
	.p2alignl 6, 3212836864

; #define LAS __attribute__((address_space(3)))
; #define FB_ISSUE(T, S) do { __builtin_amdgcn_global_load_lds((const unsigned*)(ksrc + (size_t)(T) * 4096), (LAS unsigned*)(ring + (S) * A_SLOT), 16, 0, 0); \
;                             __builtin_amdgcn_global_load_lds((const unsigned*)(vsrc + (size_t)(T) * 4096), (LAS unsigned*)(ring + (S) * A_SLOT + 8192), 16, 0, 0); } while (0)
; template <int MODE> ...
;     ...
;     for (int tile = tile_lo; tile <= tile_hi; ++tile) {
;         if (tile < tile_hi) asm volatile("s_waitcnt vmcnt(2)" ::: "memory"); else asm volatile("s_waitcnt vmcnt(0)" ::: "memory");
;         __builtin_amdgcn_s_barrier(); asm volatile("" ::: "memory");
;         if (tile + 2 <= tile_hi) FB_ISSUE(tile + 2, sn);
;         const LAS unsigned char* kt = kbase + sc * A_SLOT; const LAS unsigned char* vt = vbase + sc * A_SLOT;
;         sc = sc == 2 ? 0 : sc + 1; sn = sn == 2 ? 0 : sn + 1;
.LBB0_2863:
	s_add_i32 s0, s28, 1
	s_cmp_lg_u32 s28, 2
	s_cselect_b32 s28, s0, 0
	s_add_i32 s0, s23, 1
	s_waitcnt lgkmcnt(0)
	s_cmp_lg_u32 s23, 2
	s_cselect_b32 s23, s0, 0
	s_add_i32 s21, s21, 1
	s_add_i32 s25, s25, 64
	s_and_b64 vcc, exec, s[16:17]
	s_cbranch_vccnz .LBB0_2881
	.p2alignl 6, 3212836864

.LBB0_2886:
	s_and_b64 vcc, exec, s[52:53]
	s_cbranch_vccnz .LBB0_2894
	.p2alignl 6, 3212836864

; __device__ __forceinline__ unsigned xb_ld(unsigned* p)              { return __hip_atomic_load(p, __ATOMIC_RELAXED, __HIP_MEMORY_SCOPE_AGENT); }
; __device__ __forceinline__ void xcd_barrier_complete(unsigned* bar, unsigned x, unsigned& nloc, unsigned& nx) {
;     ...
;     for (;;) {
;         sum = 0u; cnt = 0u; mine = 0u;
; #pragma unroll
;         for (unsigned j = 0; j < 16; ++j) { const unsigned c = xb_ld(&bar[XB_XCNT(j)]); sum += c; cnt += (c > 0u) ? 1u : 0u; mine = (j == x) ? c : mine; }
;         if (sum == G) break;
;         __builtin_amdgcn_s_sleep(1);
;         if ((++sp & 255u) == 0u) { if (xb_ld(&bar[XB_TMO])) break; if (sp > XB_SPIN_CAP) { atomicAdd(&bar[XB_TMO], 1u); break; } }
;     }
.LBB0_2904:
	s_and_b64 s[4:5], exec, s[20:21]
	s_or_b64 s[16:17], s[4:5], s[16:17]
	s_andn2_b64 s[4:5], s[18:19], exec
	s_and_b64 s[18:19], s[22:23], exec
	s_or_b64 s[18:19], s[4:5], s[18:19]
	s_andn2_b64 exec, exec, s[16:17]
	s_cbranch_execz .LBB0_2911
	.p2alignl 6, 3212836864

; #define PG8_STAGE(bufoff, gbase, voff) do { _Pragma("unroll") for (int _i = 0; _i < 2; ++_i) \
;         __builtin_amdgcn_global_load_lds((const unsigned*)((const char*)(gbase) + (voff)[_i]), (PG8_LAS unsigned*)(lds + (bufoff) + ldsw + _i * 8192), 16, 0, 0); } while (0)
; #define PG8_LDA(dst, b, h) do { _Pragma("unroll") for (int m = 0; m < 4; ++m) _Pragma("unroll") for (int k = 0; k < 2; ++k) dst[m][k] = *(const PG8_LAS bf16x8*)(lds + PG8_SA(b, h) + aoff + m * 2048 + k * 1024); } while (0)
; #define PG8_LDB(dst, b, h) do { _Pragma("unroll") for (int n = 0; n < 2; ++n) _Pragma("unroll") for (int k = 0; k < 2; ++k) dst[n][k] = *(const PG8_LAS bf16x8*)(lds + PG8_SB(b, h) + boff + n * 2048 + k * 1024); } while (0)
; #define PG8_WAIT_V(n) asm volatile("s_waitcnt vmcnt(" #n ")" ::: "memory")
; #define PG8_WAIT_L(n) asm volatile("s_waitcnt lgkmcnt(" #n ")" ::: "memory")
; #define PG8_BAR __builtin_amdgcn_s_barrier()
; #define PG8_SCHED __builtin_amdgcn_sched_barrier(0)
; template <class Epi, class Sched, bool ALIGN_EPI = false, bool SP2 = false>
; __device__ __forceinline__ void gemm_phase(PG8_LAS unsigned char* lds, const Gemm g, const Sched& S, const Epi& E, const int tid_in) {
;     ...
;         const char* nA = has_next ? (const char*)g.A + (size_t)nxt.pm * tstep : cA; const char* nB = has_next ? (const char*)g.Bt + (size_t)nxt.pn * tstep : cB;
;         for (int t = 0; t < nt; t += 2) {
;             const bool last = (t == nt - 2);
;             const char* a1 = cA + (size_t)(t + 1) * kstep;
;             const char* a2 = last ? nA : cA + (size_t)(t + 2) * kstep; const char* b2 = last ? nB : cB + (size_t)(t + 2) * kstep;
;             const char* a3 = a2 + kstep; const char* b3 = b2 + kstep;
;             if (last && has_next) S.a_ready(nxt);
;             if constexpr (SP2) {
;             PG8_LDB(B0, 0, 0); PG8_LDB(B1, 0, 1); PG8_SCHED; PG8_LDA(At, 0, 0); PG8_STAGE(PG8_SA(1, 1), a1 + hstep, voffA);
;             PG8_WAIT_V(8); PG8_WAIT_L(0); PG8_BAR; PG8_MMA(0, 0, At, B0); PG8_MMA(0, 1, At, B1); PG8_BAR; PG8_SCHED;
;             PG8_LDA(At, 0, 1); PG8_STAGE(PG8_SB(0, 0), b2, voffB); PG8_STAGE(PG8_SB(0, 1), b2 + hstep, voffB); PG8_STAGE(PG8_SA(0, 0), a2, voffA);
;             PG8_WAIT_V(8); PG8_WAIT_L(0); PG8_BAR; PG8_MMA(1, 0, At, B0); PG8_MMA(1, 1, At, B1); PG8_BAR; PG8_SCHED;
.LBB0_2953:
	s_ashr_i32 s55, s54, 31
	s_lshl_b64 s[56:57], s[54:55], 19
	s_add_u32 s56, s16, s56
	s_addc_u32 s57, s17, s57
	s_and_b64 s[58:59], s[8:9], exec
	s_cselect_b32 s55, s57, s63
	s_cselect_b32 s61, s56, s62
	s_ashr_i32 s53, s52, 31
	s_lshl_b64 s[58:59], s[52:53], 19
	s_add_u32 s58, s10, s58
	s_addc_u32 s59, s11, s59
	s_and_b64 s[64:65], s[8:9], exec
	s_cselect_b32 s53, s59, s1
	s_cselect_b32 s74, s58, s0
	s_add_u32 s62, s62, 0x40080
	s_addc_u32 s63, s63, 0
	s_add_u32 s75, s0, 0x100
	v_mov_b32_e32 v0, 0
	s_addc_u32 s76, s1, 0
	s_mov_b32 s77, -2
	ds_read_b128 v[92:95], v207
	ds_read_b128 v[100:103], v207 offset:1024
	ds_read_b128 v[112:115], v207 offset:2048
	ds_read_b128 v[124:127], v207 offset:3072
	ds_read_b128 v[136:139], v208
	ds_read_b128 v[148:151], v208 offset:1024
	ds_read_b128 v[152:155], v208 offset:2048
	ds_read_b128 v[156:159], v208 offset:3072
	s_add_u32 s0, s62, 0xfffc0080
	s_addc_u32 s1, s63, -1
	s_cmp_eq_u32 s77, 12
	s_cselect_b32 s65, s55, s1
	s_cselect_b32 s64, s61, s0
	s_cselect_b32 s1, s53, s76
	s_cselect_b32 s0, s74, s75
	v_lshl_add_u64 v[214:215], s[62:63], 0, v[192:193]
	s_add_i32 m0, s4, 0xc000
	ds_read_b128 v[160:163], v209
	ds_read_b128 v[164:167], v209 offset:1024
	ds_read_b128 v[168:171], v209 offset:2048
	ds_read_b128 v[172:175], v209 offset:3072
	ds_read_b128 v[176:179], v209 offset:4096
	ds_read_b128 v[180:183], v209 offset:5120
	ds_read_b128 v[200:203], v209 offset:6144
	ds_read_b128 v[210:213], v209 offset:7168
	global_load_lds_dwordx4 v[214:215], off
	v_lshl_add_u64 v[214:215], s[62:63], 0, v[194:195]
	s_add_i32 m0, s4, 0xe000
	s_nop 0
	global_load_lds_dwordx4 v[214:215], off
	s_waitcnt vmcnt(8)
	s_waitcnt lgkmcnt(0)
	s_barrier
	s_waitcnt lgkmcnt(0)
	v_mfma_f32_16x16x32_bf16 v[144:147], v[92:95], v[160:163], 0
	v_mfma_f32_16x16x32_bf16 v[140:143], v[112:115], v[160:163], 0
	v_mfma_f32_16x16x32_bf16 v[120:123], v[92:95], v[168:171], 0
	v_mfma_f32_16x16x32_bf16 v[116:119], v[112:115], v[168:171], 0
	v_mfma_f32_16x16x32_bf16 v[96:99], v[92:95], v[176:179], 0
	v_mfma_f32_16x16x32_bf16 v[88:91], v[112:115], v[176:179], 0
	v_mfma_f32_16x16x32_bf16 v[76:79], v[92:95], v[200:203], 0
	v_mfma_f32_16x16x32_bf16 v[72:75], v[112:115], v[200:203], 0
	v_mfma_f32_16x16x32_bf16 v[144:147], v[100:103], v[164:167], v[144:147]
	v_mfma_f32_16x16x32_bf16 v[140:143], v[124:127], v[164:167], v[140:143]
	v_mfma_f32_16x16x32_bf16 v[120:123], v[100:103], v[172:175], v[120:123]
	v_mfma_f32_16x16x32_bf16 v[116:119], v[124:127], v[172:175], v[116:119]
	v_mfma_f32_16x16x32_bf16 v[96:99], v[100:103], v[180:183], v[96:99]
	v_mfma_f32_16x16x32_bf16 v[88:91], v[124:127], v[180:183], v[88:91]
	v_mfma_f32_16x16x32_bf16 v[76:79], v[100:103], v[210:213], v[76:79]
	v_mfma_f32_16x16x32_bf16 v[72:75], v[124:127], v[210:213], v[72:75]
	v_mfma_f32_16x16x32_bf16 v[132:135], v[136:139], v[160:163], 0
	v_mfma_f32_16x16x32_bf16 v[128:131], v[152:155], v[160:163], 0
	v_mfma_f32_16x16x32_bf16 v[108:111], v[136:139], v[168:171], 0
	v_mfma_f32_16x16x32_bf16 v[104:107], v[152:155], v[168:171], 0
	v_mfma_f32_16x16x32_bf16 v[84:87], v[136:139], v[176:179], 0
	v_mfma_f32_16x16x32_bf16 v[80:83], v[152:155], v[176:179], 0
	v_mfma_f32_16x16x32_bf16 v[68:71], v[136:139], v[200:203], 0
	v_mfma_f32_16x16x32_bf16 v[64:67], v[152:155], v[200:203], 0
	v_mfma_f32_16x16x32_bf16 v[132:135], v[148:151], v[164:167], v[132:135]
	v_mfma_f32_16x16x32_bf16 v[128:131], v[156:159], v[164:167], v[128:131]
	v_mfma_f32_16x16x32_bf16 v[108:111], v[148:151], v[172:175], v[108:111]
	v_mfma_f32_16x16x32_bf16 v[104:107], v[156:159], v[172:175], v[104:107]
	v_mfma_f32_16x16x32_bf16 v[84:87], v[148:151], v[180:183], v[84:87]
	v_mfma_f32_16x16x32_bf16 v[80:83], v[156:159], v[180:183], v[80:83]
	v_mfma_f32_16x16x32_bf16 v[68:71], v[148:151], v[210:213], v[68:71]
	v_mfma_f32_16x16x32_bf16 v[64:67], v[156:159], v[210:213], v[64:67]
	s_barrier
	s_add_i32 s78, s3, s2
	v_lshl_add_u64 v[214:215], s[0:1], 0, v[186:187]
	s_mov_b32 m0, s78
	ds_read_b128 v[160:163], v209 offset:16384
	ds_read_b128 v[164:167], v209 offset:17408
	ds_read_b128 v[168:171], v209 offset:18432
	ds_read_b128 v[172:175], v209 offset:19456
	ds_read_b128 v[176:179], v209 offset:20480
	ds_read_b128 v[180:183], v209 offset:21504
	ds_read_b128 v[200:203], v209 offset:22528
	ds_read_b128 v[210:213], v209 offset:23552
	global_load_lds_dwordx4 v[214:215], off
	s_add_i32 m0, s78, 0x2000
	s_add_u32 s78, s0, 0x40000
	v_lshl_add_u64 v[216:217], s[0:1], 0, v[190:191]
	s_addc_u32 s79, s1, 0
	s_add_i32 s80, s41, s2
	global_load_lds_dwordx4 v[216:217], off
	v_lshl_add_u64 v[218:219], s[78:79], 0, v[186:187]
	s_mov_b32 m0, s80
	v_lshl_add_u64 v[220:221], s[64:65], 0, v[188:189]
	global_load_lds_dwordx4 v[218:219], off
	v_lshl_add_u64 v[218:219], s[78:79], 0, v[190:191]
	s_add_i32 m0, s80, 0x2000
	s_nop 0
	global_load_lds_dwordx4 v[218:219], off
	v_lshl_add_u64 v[218:219], s[64:65], 0, v[184:185]
	s_mov_b32 m0, s4
	s_nop 0
	global_load_lds_dwordx4 v[218:219], off
	s_mov_b32 m0, s5
	s_nop 0
	global_load_lds_dwordx4 v[220:221], off
	s_waitcnt vmcnt(8)
	s_waitcnt lgkmcnt(0)
	s_barrier
; #define PG8_STAGE(bufoff, gbase, voff) do { _Pragma("unroll") for (int _i = 0; _i < 2; ++_i) \
;         __builtin_amdgcn_global_load_lds((const unsigned*)((const char*)(gbase) + (voff)[_i]), (PG8_LAS unsigned*)(lds + (bufoff) + ldsw + _i * 8192), 16, 0, 0); } while (0)
; #define PG8_LDA(dst, b, h) do { _Pragma("unroll") for (int m = 0; m < 4; ++m) _Pragma("unroll") for (int k = 0; k < 2; ++k) dst[m][k] = *(const PG8_LAS bf16x8*)(lds + PG8_SA(b, h) + aoff + m * 2048 + k * 1024); } while (0)
; #define PG8_LDB(dst, b, h) do { _Pragma("unroll") for (int n = 0; n < 2; ++n) _Pragma("unroll") for (int k = 0; k < 2; ++k) dst[n][k] = *(const PG8_LAS bf16x8*)(lds + PG8_SB(b, h) + boff + n * 2048 + k * 1024); } while (0)
; #define PG8_MMA(ai, bj, At, Bt) do { __builtin_amdgcn_s_setprio(1); _Pragma("unroll") for (int m = 0; m < 4; ++m) _Pragma("unroll") for (int n = 0; n < 2; ++n) _Pragma("unroll") for (int k = 0; k < 2; ++k) \
;         acc[ai][bj][m][n] = __builtin_amdgcn_mfma_f32_16x16x32_bf16(Bt[n][k], At[m][k], acc[ai][bj][m][n], 0, 0, 0); __builtin_amdgcn_s_setprio(0); } while (0)
; #define PG8_WAIT_V(n) asm volatile("s_waitcnt vmcnt(" #n ")" ::: "memory")
; #define PG8_WAIT_L(n) asm volatile("s_waitcnt lgkmcnt(" #n ")" ::: "memory")
; #define PG8_BAR __builtin_amdgcn_s_barrier()
; #define PG8_SCHED __builtin_amdgcn_sched_barrier(0)
; template <class Epi, class Sched, bool ALIGN_EPI = false, bool SP2 = false>
; __device__ __forceinline__ void gemm_phase(PG8_LAS unsigned char* lds, const Gemm g, const Sched& S, const Epi& E, const int tid_in) {
;     ...
;             PG8_WAIT_V(8); PG8_WAIT_L(0); PG8_BAR; PG8_MMA(1, 0, At, B0); PG8_MMA(1, 1, At, B1); PG8_BAR; PG8_SCHED;
;             PG8_LDB(B0, 1, 0); PG8_LDB(B1, 1, 1); PG8_SCHED; PG8_LDA(At, 1, 0); PG8_STAGE(PG8_SA(0, 1), a2 + hstep, voffA);
;             PG8_WAIT_V(8); PG8_WAIT_L(0); PG8_BAR; PG8_MMA(0, 0, At, B0); PG8_MMA(0, 1, At, B1); PG8_BAR; PG8_SCHED;
	s_waitcnt lgkmcnt(0)
	v_mfma_f32_16x16x32_bf16 v[60:63], v[92:95], v[160:163], 0
	v_mfma_f32_16x16x32_bf16 v[56:59], v[112:115], v[160:163], 0
	v_mfma_f32_16x16x32_bf16 v[44:47], v[92:95], v[168:171], 0
	v_mfma_f32_16x16x32_bf16 v[40:43], v[112:115], v[168:171], 0
	v_mfma_f32_16x16x32_bf16 v[28:31], v[92:95], v[176:179], 0
	v_mfma_f32_16x16x32_bf16 v[24:27], v[112:115], v[176:179], 0
	v_mfma_f32_16x16x32_bf16 v[12:15], v[92:95], v[200:203], 0
	v_mfma_f32_16x16x32_bf16 v[8:11], v[112:115], v[200:203], 0
	v_mfma_f32_16x16x32_bf16 v[60:63], v[100:103], v[164:167], v[60:63]
	v_mfma_f32_16x16x32_bf16 v[56:59], v[124:127], v[164:167], v[56:59]
	v_mfma_f32_16x16x32_bf16 v[44:47], v[100:103], v[172:175], v[44:47]
	v_mfma_f32_16x16x32_bf16 v[40:43], v[124:127], v[172:175], v[40:43]
	v_mfma_f32_16x16x32_bf16 v[28:31], v[100:103], v[180:183], v[28:31]
	v_mfma_f32_16x16x32_bf16 v[24:27], v[124:127], v[180:183], v[24:27]
	v_mfma_f32_16x16x32_bf16 v[12:15], v[100:103], v[210:213], v[12:15]
	v_mfma_f32_16x16x32_bf16 v[8:11], v[124:127], v[210:213], v[8:11]
	v_mfma_f32_16x16x32_bf16 v[52:55], v[136:139], v[160:163], 0
	v_mfma_f32_16x16x32_bf16 v[48:51], v[152:155], v[160:163], 0
	v_mfma_f32_16x16x32_bf16 v[36:39], v[136:139], v[168:171], 0
	v_mfma_f32_16x16x32_bf16 v[32:35], v[152:155], v[168:171], 0
	v_mfma_f32_16x16x32_bf16 v[20:23], v[136:139], v[176:179], 0
	v_mfma_f32_16x16x32_bf16 v[16:19], v[152:155], v[176:179], 0
	v_mfma_f32_16x16x32_bf16 v[4:7], v[136:139], v[200:203], 0
	v_mfma_f32_16x16x32_bf16 v[0:3], v[152:155], v[200:203], 0
	v_mfma_f32_16x16x32_bf16 v[52:55], v[148:151], v[164:167], v[52:55]
	v_mfma_f32_16x16x32_bf16 v[48:51], v[156:159], v[164:167], v[48:51]
	v_mfma_f32_16x16x32_bf16 v[36:39], v[148:151], v[172:175], v[36:39]
	v_mfma_f32_16x16x32_bf16 v[32:35], v[156:159], v[172:175], v[32:35]
	v_mfma_f32_16x16x32_bf16 v[20:23], v[148:151], v[180:183], v[20:23]
	v_mfma_f32_16x16x32_bf16 v[16:19], v[156:159], v[180:183], v[16:19]
	v_mfma_f32_16x16x32_bf16 v[4:7], v[148:151], v[210:213], v[4:7]
	v_mfma_f32_16x16x32_bf16 v[0:3], v[156:159], v[210:213], v[0:3]
	s_barrier
	s_add_i32 s78, 0, 0x18000
	s_add_i32 s79, 0, 0x1c000
	v_add_u32_e32 v124, s78, v205
	v_add_u32_e32 v156, s79, v205
	ds_read_b128 v[92:95], v124
	ds_read_b128 v[100:103], v124 offset:1024
	ds_read_b128 v[112:115], v124 offset:2048
	ds_read_b128 v[124:127], v124 offset:3072
	ds_read_b128 v[136:139], v156
	ds_read_b128 v[148:151], v156 offset:1024
	ds_read_b128 v[152:155], v156 offset:2048
	ds_read_b128 v[156:159], v156 offset:3072
	s_add_u32 s64, s64, 0x40000
	s_addc_u32 s65, s65, 0
	s_mov_b32 m0, s30
	v_lshl_add_u64 v[222:223], s[64:65], 0, v[184:185]
	ds_read_b128 v[160:163], v209 offset:32768
	ds_read_b128 v[164:167], v209 offset:33792
	ds_read_b128 v[168:171], v209 offset:34816
	ds_read_b128 v[172:175], v209 offset:35840
	ds_read_b128 v[176:179], v209 offset:36864
	ds_read_b128 v[180:183], v209 offset:37888
	ds_read_b128 v[200:203], v209 offset:38912
	ds_read_b128 v[210:213], v209 offset:39936
	global_load_lds_dwordx4 v[222:223], off
	v_lshl_add_u64 v[222:223], s[64:65], 0, v[188:189]
	s_mov_b32 m0, s31
	s_nop 0
	global_load_lds_dwordx4 v[222:223], off
	s_waitcnt vmcnt(8)
	s_waitcnt lgkmcnt(0)
	s_barrier
	s_waitcnt lgkmcnt(0)
	v_mfma_f32_16x16x32_bf16 v[144:147], v[92:95], v[160:163], v[144:147]
	v_mfma_f32_16x16x32_bf16 v[140:143], v[112:115], v[160:163], v[140:143]
	v_mfma_f32_16x16x32_bf16 v[120:123], v[92:95], v[168:171], v[120:123]
	v_mfma_f32_16x16x32_bf16 v[116:119], v[112:115], v[168:171], v[116:119]
	v_mfma_f32_16x16x32_bf16 v[96:99], v[92:95], v[176:179], v[96:99]
	v_mfma_f32_16x16x32_bf16 v[88:91], v[112:115], v[176:179], v[88:91]
	v_mfma_f32_16x16x32_bf16 v[76:79], v[92:95], v[200:203], v[76:79]
	v_mfma_f32_16x16x32_bf16 v[72:75], v[112:115], v[200:203], v[72:75]
	v_mfma_f32_16x16x32_bf16 v[144:147], v[100:103], v[164:167], v[144:147]
	v_mfma_f32_16x16x32_bf16 v[140:143], v[124:127], v[164:167], v[140:143]
	v_mfma_f32_16x16x32_bf16 v[120:123], v[100:103], v[172:175], v[120:123]
	v_mfma_f32_16x16x32_bf16 v[116:119], v[124:127], v[172:175], v[116:119]
	v_mfma_f32_16x16x32_bf16 v[96:99], v[100:103], v[180:183], v[96:99]
	v_mfma_f32_16x16x32_bf16 v[88:91], v[124:127], v[180:183], v[88:91]
	v_mfma_f32_16x16x32_bf16 v[76:79], v[100:103], v[210:213], v[76:79]
	v_mfma_f32_16x16x32_bf16 v[72:75], v[124:127], v[210:213], v[72:75]
	v_mfma_f32_16x16x32_bf16 v[132:135], v[136:139], v[160:163], v[132:135]
	v_mfma_f32_16x16x32_bf16 v[128:131], v[152:155], v[160:163], v[128:131]
	v_mfma_f32_16x16x32_bf16 v[108:111], v[136:139], v[168:171], v[108:111]
	v_mfma_f32_16x16x32_bf16 v[104:107], v[152:155], v[168:171], v[104:107]
	v_mfma_f32_16x16x32_bf16 v[84:87], v[136:139], v[176:179], v[84:87]
	v_mfma_f32_16x16x32_bf16 v[80:83], v[152:155], v[176:179], v[80:83]
	v_mfma_f32_16x16x32_bf16 v[68:71], v[136:139], v[200:203], v[68:71]
	v_mfma_f32_16x16x32_bf16 v[64:67], v[152:155], v[200:203], v[64:67]
	v_mfma_f32_16x16x32_bf16 v[132:135], v[148:151], v[164:167], v[132:135]
	v_mfma_f32_16x16x32_bf16 v[128:131], v[156:159], v[164:167], v[128:131]
	v_mfma_f32_16x16x32_bf16 v[108:111], v[148:151], v[172:175], v[108:111]
	v_mfma_f32_16x16x32_bf16 v[104:107], v[156:159], v[172:175], v[104:107]
	v_mfma_f32_16x16x32_bf16 v[84:87], v[148:151], v[180:183], v[84:87]
	v_mfma_f32_16x16x32_bf16 v[80:83], v[156:159], v[180:183], v[80:83]
	v_mfma_f32_16x16x32_bf16 v[68:71], v[148:151], v[210:213], v[68:71]
	v_mfma_f32_16x16x32_bf16 v[64:67], v[156:159], v[210:213], v[64:67]
	s_barrier
; #define PG8_STAGE(bufoff, gbase, voff) do { _Pragma("unroll") for (int _i = 0; _i < 2; ++_i) \
;         __builtin_amdgcn_global_load_lds((const unsigned*)((const char*)(gbase) + (voff)[_i]), (PG8_LAS unsigned*)(lds + (bufoff) + ldsw + _i * 8192), 16, 0, 0); } while (0)
; #define PG8_LDA(dst, b, h) do { _Pragma("unroll") for (int m = 0; m < 4; ++m) _Pragma("unroll") for (int k = 0; k < 2; ++k) dst[m][k] = *(const PG8_LAS bf16x8*)(lds + PG8_SA(b, h) + aoff + m * 2048 + k * 1024); } while (0)
; #define PG8_MMA(ai, bj, At, Bt) do { __builtin_amdgcn_s_setprio(1); _Pragma("unroll") for (int m = 0; m < 4; ++m) _Pragma("unroll") for (int n = 0; n < 2; ++n) _Pragma("unroll") for (int k = 0; k < 2; ++k) \
;         acc[ai][bj][m][n] = __builtin_amdgcn_mfma_f32_16x16x32_bf16(Bt[n][k], At[m][k], acc[ai][bj][m][n], 0, 0, 0); __builtin_amdgcn_s_setprio(0); } while (0)
; #define PG8_WAIT_V(n) asm volatile("s_waitcnt vmcnt(" #n ")" ::: "memory")
; #define PG8_WAIT_L(n) asm volatile("s_waitcnt lgkmcnt(" #n ")" ::: "memory")
; #define PG8_BAR __builtin_amdgcn_s_barrier()
; #define PG8_SCHED __builtin_amdgcn_sched_barrier(0)
; template <class Epi, class Sched, bool ALIGN_EPI = false, bool SP2 = false>
; __device__ __forceinline__ void gemm_phase(PG8_LAS unsigned char* lds, const Gemm g, const Sched& S, const Epi& E, const int tid_in) {
;     ...
;             PG8_LDA(At, 1, 1); PG8_STAGE(PG8_SB(1, 0), b3, voffB); PG8_STAGE(PG8_SB(1, 1), b3 + hstep, voffB); PG8_STAGE(PG8_SA(1, 0), a3, voffA);
;             PG8_WAIT_V(8); PG8_WAIT_L(0); PG8_BAR; PG8_MMA(1, 0, At, B0); PG8_MMA(1, 1, At, B1); PG8_BAR; PG8_SCHED;
	s_add_i32 s64, s78, s2
	v_lshl_add_u64 v[214:215], v[214:215], 0, s[22:23]
	s_mov_b32 m0, s64
	ds_read_b128 v[160:163], v209 offset:49152
	ds_read_b128 v[164:167], v209 offset:50176
	ds_read_b128 v[168:171], v209 offset:51200
	ds_read_b128 v[172:175], v209 offset:52224
	ds_read_b128 v[176:179], v209 offset:53248
	ds_read_b128 v[180:183], v209 offset:54272
	ds_read_b128 v[200:203], v209 offset:55296
	ds_read_b128 v[210:213], v209 offset:56320
	global_load_lds_dwordx4 v[214:215], off
	s_add_i32 m0, s64, 0x2000
	s_add_u32 s0, s0, 0x40080
	v_lshl_add_u64 v[214:215], v[216:217], 0, s[22:23]
	s_addc_u32 s1, s1, 0
	s_add_i32 s64, s79, s2
	global_load_lds_dwordx4 v[214:215], off
	v_lshl_add_u64 v[214:215], s[0:1], 0, v[186:187]
	s_mov_b32 m0, s64
	s_nop 0
	global_load_lds_dwordx4 v[214:215], off
	v_lshl_add_u64 v[214:215], s[0:1], 0, v[190:191]
	s_add_i32 m0, s64, 0x2000
	s_nop 0
	global_load_lds_dwordx4 v[214:215], off
	v_lshl_add_u64 v[214:215], v[218:219], 0, s[22:23]
	s_mov_b32 m0, s35
	s_nop 0
	global_load_lds_dwordx4 v[214:215], off
	v_lshl_add_u64 v[214:215], v[220:221], 0, s[22:23]
	s_mov_b32 m0, s36
	s_nop 0
	global_load_lds_dwordx4 v[214:215], off
	s_waitcnt vmcnt(8)
	s_waitcnt lgkmcnt(0)
	s_barrier
	s_waitcnt lgkmcnt(0)
	v_mfma_f32_16x16x32_bf16 v[60:63], v[92:95], v[160:163], v[60:63]
	v_mfma_f32_16x16x32_bf16 v[56:59], v[112:115], v[160:163], v[56:59]
	v_mfma_f32_16x16x32_bf16 v[44:47], v[92:95], v[168:171], v[44:47]
	v_mfma_f32_16x16x32_bf16 v[40:43], v[112:115], v[168:171], v[40:43]
	v_mfma_f32_16x16x32_bf16 v[28:31], v[92:95], v[176:179], v[28:31]
	v_mfma_f32_16x16x32_bf16 v[24:27], v[112:115], v[176:179], v[24:27]
	v_mfma_f32_16x16x32_bf16 v[12:15], v[92:95], v[200:203], v[12:15]
	v_mfma_f32_16x16x32_bf16 v[8:11], v[112:115], v[200:203], v[8:11]
	v_mfma_f32_16x16x32_bf16 v[60:63], v[100:103], v[164:167], v[60:63]
	v_mfma_f32_16x16x32_bf16 v[56:59], v[124:127], v[164:167], v[56:59]
	v_mfma_f32_16x16x32_bf16 v[44:47], v[100:103], v[172:175], v[44:47]
	v_mfma_f32_16x16x32_bf16 v[40:43], v[124:127], v[172:175], v[40:43]
	v_mfma_f32_16x16x32_bf16 v[28:31], v[100:103], v[180:183], v[28:31]
	v_mfma_f32_16x16x32_bf16 v[24:27], v[124:127], v[180:183], v[24:27]
	v_mfma_f32_16x16x32_bf16 v[12:15], v[100:103], v[210:213], v[12:15]
	v_mfma_f32_16x16x32_bf16 v[8:11], v[124:127], v[210:213], v[8:11]
	v_mfma_f32_16x16x32_bf16 v[52:55], v[136:139], v[160:163], v[52:55]
	v_mfma_f32_16x16x32_bf16 v[48:51], v[152:155], v[160:163], v[48:51]
	v_mfma_f32_16x16x32_bf16 v[36:39], v[136:139], v[168:171], v[36:39]
	v_mfma_f32_16x16x32_bf16 v[32:35], v[152:155], v[168:171], v[32:35]
	v_mfma_f32_16x16x32_bf16 v[20:23], v[136:139], v[176:179], v[20:23]
	v_mfma_f32_16x16x32_bf16 v[16:19], v[152:155], v[176:179], v[16:19]
	v_mfma_f32_16x16x32_bf16 v[4:7], v[136:139], v[200:203], v[4:7]
	v_mfma_f32_16x16x32_bf16 v[0:3], v[152:155], v[200:203], v[0:3]
	v_mfma_f32_16x16x32_bf16 v[52:55], v[148:151], v[164:167], v[52:55]
	v_mfma_f32_16x16x32_bf16 v[48:51], v[156:159], v[164:167], v[48:51]
	v_mfma_f32_16x16x32_bf16 v[36:39], v[148:151], v[172:175], v[36:39]
	v_mfma_f32_16x16x32_bf16 v[32:35], v[156:159], v[172:175], v[32:35]
	v_mfma_f32_16x16x32_bf16 v[20:23], v[148:151], v[180:183], v[20:23]
	v_mfma_f32_16x16x32_bf16 v[16:19], v[156:159], v[180:183], v[16:19]
	v_mfma_f32_16x16x32_bf16 v[4:7], v[148:151], v[210:213], v[4:7]
	v_mfma_f32_16x16x32_bf16 v[0:3], v[156:159], v[210:213], v[0:3]
	s_barrier
	s_add_i32 s77, s77, 2
	s_add_u32 s62, s62, 0x100
	s_addc_u32 s63, s63, 0
	s_add_u32 s75, s75, 0x100
	s_addc_u32 s76, s76, 0
	s_cmp_gt_u32 s77, 13
	s_cbranch_scc0 .LBB0_2954
	s_branch .Lmy_kdone_6
	.p2alignl 6, 3212836864

; #define PG8_STAGE(bufoff, gbase, voff) do { _Pragma("unroll") for (int _i = 0; _i < 2; ++_i) \
;         __builtin_amdgcn_global_load_lds((const unsigned*)((const char*)(gbase) + (voff)[_i]), (PG8_LAS unsigned*)(lds + (bufoff) + ldsw + _i * 8192), 16, 0, 0); } while (0)
; #define PG8_LDA(dst, b, h) do { _Pragma("unroll") for (int m = 0; m < 4; ++m) _Pragma("unroll") for (int k = 0; k < 2; ++k) dst[m][k] = *(const PG8_LAS bf16x8*)(lds + PG8_SA(b, h) + aoff + m * 2048 + k * 1024); } while (0)
; #define PG8_LDB(dst, b, h) do { _Pragma("unroll") for (int n = 0; n < 2; ++n) _Pragma("unroll") for (int k = 0; k < 2; ++k) dst[n][k] = *(const PG8_LAS bf16x8*)(lds + PG8_SB(b, h) + boff + n * 2048 + k * 1024); } while (0)
; #define PG8_WAIT_V(n) asm volatile("s_waitcnt vmcnt(" #n ")" ::: "memory")
; #define PG8_WAIT_L(n) asm volatile("s_waitcnt lgkmcnt(" #n ")" ::: "memory")
; #define PG8_BAR __builtin_amdgcn_s_barrier()
; #define PG8_SCHED __builtin_amdgcn_sched_barrier(0)
; template <class Epi, class Sched, bool ALIGN_EPI = false, bool SP2 = false>
; __device__ __forceinline__ void gemm_phase(PG8_LAS unsigned char* lds, const Gemm g, const Sched& S, const Epi& E, const int tid_in) {
;     ...
;         const char* nA = has_next ? (const char*)g.A + (size_t)nxt.pm * tstep : cA; const char* nB = has_next ? (const char*)g.Bt + (size_t)nxt.pn * tstep : cB;
;         for (int t = 0; t < nt; t += 2) {
;             const bool last = (t == nt - 2);
;             const char* a1 = cA + (size_t)(t + 1) * kstep;
;             const char* a2 = last ? nA : cA + (size_t)(t + 2) * kstep; const char* b2 = last ? nB : cB + (size_t)(t + 2) * kstep;
;             const char* a3 = a2 + kstep; const char* b3 = b2 + kstep;
;             if (last && has_next) S.a_ready(nxt);
;             if constexpr (SP2) {
;             PG8_LDB(B0, 0, 0); PG8_LDB(B1, 0, 1); PG8_SCHED; PG8_LDA(At, 0, 0); PG8_STAGE(PG8_SA(1, 1), a1 + hstep, voffA);
;             PG8_WAIT_V(8); PG8_WAIT_L(0); PG8_BAR; PG8_MMA(0, 0, At, B0); PG8_MMA(0, 1, At, B1); PG8_BAR; PG8_SCHED;
;             PG8_LDA(At, 0, 1); PG8_STAGE(PG8_SB(0, 0), b2, voffB); PG8_STAGE(PG8_SB(0, 1), b2 + hstep, voffB); PG8_STAGE(PG8_SA(0, 0), a2, voffA);
;             PG8_WAIT_V(8); PG8_WAIT_L(0); PG8_BAR; PG8_MMA(1, 0, At, B0); PG8_MMA(1, 1, At, B1); PG8_BAR; PG8_SCHED;
.LBB0_3052:
	s_ashr_i32 s25, s24, 31
	s_lshl_b64 s[26:27], s[24:25], 19
	s_add_u32 s26, s30, s26
	s_addc_u32 s27, s31, s27
	s_and_b64 s[28:29], s[6:7], exec
	s_cselect_b32 s25, s27, s11
	s_cselect_b32 s49, s26, s10
	s_ashr_i32 s23, s22, 31
	s_lshl_b64 s[28:29], s[22:23], 19
	s_add_u32 s28, s4, s28
	s_addc_u32 s29, s5, s29
	s_and_b64 s[38:39], s[6:7], exec
	s_cselect_b32 s23, s29, s1
	s_cselect_b32 s50, s28, s0
	s_add_u32 s10, s10, 0x40080
	s_addc_u32 s11, s11, 0
	s_add_u32 s51, s0, 0x100
	v_mov_b32_e32 v0, 0
	s_addc_u32 s52, s1, 0
	s_mov_b32 s53, -2
	ds_read_b128 v[160:163], v154
	ds_read_b128 v[164:167], v154 offset:1024
	ds_read_b128 v[168:171], v154 offset:2048
	ds_read_b128 v[172:175], v154 offset:3072
	ds_read_b128 v[176:179], v155
	ds_read_b128 v[180:183], v155 offset:1024
	ds_read_b128 v[184:187], v155 offset:2048
	ds_read_b128 v[188:191], v155 offset:3072
	s_add_u32 s0, s10, 0xfffc0080
	s_addc_u32 s1, s11, -1
	s_cmp_eq_u32 s53, 12
	s_cselect_b32 s39, s25, s1
	s_cselect_b32 s38, s49, s0
	s_cselect_b32 s1, s23, s52
	s_cselect_b32 s0, s50, s51
	v_lshl_add_u64 v[144:145], s[10:11], 0, v[136:137]
	s_add_i32 m0, s35, 0xc000
	ds_read_b128 v[192:195], v156
	ds_read_b128 v[196:199], v156 offset:1024
	ds_read_b128 v[200:203], v156 offset:2048
	ds_read_b128 v[204:207], v156 offset:3072
	ds_read_b128 v[208:211], v156 offset:4096
	ds_read_b128 v[212:215], v156 offset:5120
	ds_read_b128 v[216:219], v156 offset:6144
	ds_read_b128 v[220:223], v156 offset:7168
	global_load_lds_dwordx4 v[144:145], off
	v_lshl_add_u64 v[144:145], s[10:11], 0, v[138:139]
	s_add_i32 m0, s35, 0xe000
	s_nop 0
	global_load_lds_dwordx4 v[144:145], off
	s_waitcnt vmcnt(8)
	s_waitcnt lgkmcnt(0)
	s_barrier
	s_waitcnt lgkmcnt(0)
	v_mfma_f32_16x16x32_bf16 v[124:127], v[160:163], v[192:195], 0
	v_mfma_f32_16x16x32_bf16 v[116:119], v[168:171], v[192:195], 0
	v_mfma_f32_16x16x32_bf16 v[108:111], v[160:163], v[200:203], 0
	v_mfma_f32_16x16x32_bf16 v[100:103], v[168:171], v[200:203], 0
	v_mfma_f32_16x16x32_bf16 v[92:95], v[160:163], v[208:211], 0
	v_mfma_f32_16x16x32_bf16 v[84:87], v[168:171], v[208:211], 0
	v_mfma_f32_16x16x32_bf16 v[76:79], v[160:163], v[216:219], 0
	v_mfma_f32_16x16x32_bf16 v[68:71], v[168:171], v[216:219], 0
	v_mfma_f32_16x16x32_bf16 v[124:127], v[164:167], v[196:199], v[124:127]
	v_mfma_f32_16x16x32_bf16 v[116:119], v[172:175], v[196:199], v[116:119]
	v_mfma_f32_16x16x32_bf16 v[108:111], v[164:167], v[204:207], v[108:111]
	v_mfma_f32_16x16x32_bf16 v[100:103], v[172:175], v[204:207], v[100:103]
	v_mfma_f32_16x16x32_bf16 v[92:95], v[164:167], v[212:215], v[92:95]
	v_mfma_f32_16x16x32_bf16 v[84:87], v[172:175], v[212:215], v[84:87]
	v_mfma_f32_16x16x32_bf16 v[76:79], v[164:167], v[220:223], v[76:79]
	v_mfma_f32_16x16x32_bf16 v[68:71], v[172:175], v[220:223], v[68:71]
	v_mfma_f32_16x16x32_bf16 v[120:123], v[176:179], v[192:195], 0
	v_mfma_f32_16x16x32_bf16 v[112:115], v[184:187], v[192:195], 0
	v_mfma_f32_16x16x32_bf16 v[104:107], v[176:179], v[200:203], 0
	v_mfma_f32_16x16x32_bf16 v[96:99], v[184:187], v[200:203], 0
	v_mfma_f32_16x16x32_bf16 v[88:91], v[176:179], v[208:211], 0
	v_mfma_f32_16x16x32_bf16 v[80:83], v[184:187], v[208:211], 0
	v_mfma_f32_16x16x32_bf16 v[72:75], v[176:179], v[216:219], 0
	v_mfma_f32_16x16x32_bf16 v[64:67], v[184:187], v[216:219], 0
	v_mfma_f32_16x16x32_bf16 v[120:123], v[180:183], v[196:199], v[120:123]
	v_mfma_f32_16x16x32_bf16 v[112:115], v[188:191], v[196:199], v[112:115]
	v_mfma_f32_16x16x32_bf16 v[104:107], v[180:183], v[204:207], v[104:107]
	v_mfma_f32_16x16x32_bf16 v[96:99], v[188:191], v[204:207], v[96:99]
	v_mfma_f32_16x16x32_bf16 v[88:91], v[180:183], v[212:215], v[88:91]
	v_mfma_f32_16x16x32_bf16 v[80:83], v[188:191], v[212:215], v[80:83]
	v_mfma_f32_16x16x32_bf16 v[72:75], v[180:183], v[220:223], v[72:75]
	v_mfma_f32_16x16x32_bf16 v[64:67], v[188:191], v[220:223], v[64:67]
	s_barrier
	s_add_i32 s54, s3, s34
	v_lshl_add_u64 v[144:145], s[0:1], 0, v[130:131]
	s_mov_b32 m0, s54
	ds_read_b128 v[192:195], v156 offset:16384
	ds_read_b128 v[196:199], v156 offset:17408
	ds_read_b128 v[200:203], v156 offset:18432
	ds_read_b128 v[204:207], v156 offset:19456
	ds_read_b128 v[208:211], v156 offset:20480
	ds_read_b128 v[212:215], v156 offset:21504
	ds_read_b128 v[216:219], v156 offset:22528
	ds_read_b128 v[220:223], v156 offset:23552
	global_load_lds_dwordx4 v[144:145], off
	s_add_i32 m0, s54, 0x2000
	s_add_u32 s54, s0, 0x40000
	v_lshl_add_u64 v[224:225], s[0:1], 0, v[134:135]
	s_addc_u32 s55, s1, 0
	s_add_i32 s56, s46, s34
	global_load_lds_dwordx4 v[224:225], off
	v_lshl_add_u64 v[226:227], s[54:55], 0, v[130:131]
	s_mov_b32 m0, s56
	v_lshl_add_u64 v[228:229], s[38:39], 0, v[132:133]
	global_load_lds_dwordx4 v[226:227], off
	v_lshl_add_u64 v[226:227], s[54:55], 0, v[134:135]
	s_add_i32 m0, s56, 0x2000
	s_nop 0
	global_load_lds_dwordx4 v[226:227], off
	v_lshl_add_u64 v[226:227], s[38:39], 0, v[128:129]
	s_mov_b32 m0, s35
	s_nop 0
	global_load_lds_dwordx4 v[226:227], off
	s_mov_b32 m0, s36
	s_nop 0
	global_load_lds_dwordx4 v[228:229], off
	s_waitcnt vmcnt(8)
	s_waitcnt lgkmcnt(0)
	s_barrier
; #define PG8_STAGE(bufoff, gbase, voff) do { _Pragma("unroll") for (int _i = 0; _i < 2; ++_i) \
;         __builtin_amdgcn_global_load_lds((const unsigned*)((const char*)(gbase) + (voff)[_i]), (PG8_LAS unsigned*)(lds + (bufoff) + ldsw + _i * 8192), 16, 0, 0); } while (0)
; #define PG8_LDA(dst, b, h) do { _Pragma("unroll") for (int m = 0; m < 4; ++m) _Pragma("unroll") for (int k = 0; k < 2; ++k) dst[m][k] = *(const PG8_LAS bf16x8*)(lds + PG8_SA(b, h) + aoff + m * 2048 + k * 1024); } while (0)
; #define PG8_LDB(dst, b, h) do { _Pragma("unroll") for (int n = 0; n < 2; ++n) _Pragma("unroll") for (int k = 0; k < 2; ++k) dst[n][k] = *(const PG8_LAS bf16x8*)(lds + PG8_SB(b, h) + boff + n * 2048 + k * 1024); } while (0)
; #define PG8_MMA(ai, bj, At, Bt) do { __builtin_amdgcn_s_setprio(1); _Pragma("unroll") for (int m = 0; m < 4; ++m) _Pragma("unroll") for (int n = 0; n < 2; ++n) _Pragma("unroll") for (int k = 0; k < 2; ++k) \
;         acc[ai][bj][m][n] = __builtin_amdgcn_mfma_f32_16x16x32_bf16(Bt[n][k], At[m][k], acc[ai][bj][m][n], 0, 0, 0); __builtin_amdgcn_s_setprio(0); } while (0)
; #define PG8_WAIT_V(n) asm volatile("s_waitcnt vmcnt(" #n ")" ::: "memory")
; #define PG8_WAIT_L(n) asm volatile("s_waitcnt lgkmcnt(" #n ")" ::: "memory")
; #define PG8_BAR __builtin_amdgcn_s_barrier()
; #define PG8_SCHED __builtin_amdgcn_sched_barrier(0)
; template <class Epi, class Sched, bool ALIGN_EPI = false, bool SP2 = false>
; __device__ __forceinline__ void gemm_phase(PG8_LAS unsigned char* lds, const Gemm g, const Sched& S, const Epi& E, const int tid_in) {
;     ...
;             PG8_WAIT_V(8); PG8_WAIT_L(0); PG8_BAR; PG8_MMA(1, 0, At, B0); PG8_MMA(1, 1, At, B1); PG8_BAR; PG8_SCHED;
;             PG8_LDB(B0, 1, 0); PG8_LDB(B1, 1, 1); PG8_SCHED; PG8_LDA(At, 1, 0); PG8_STAGE(PG8_SA(0, 1), a2 + hstep, voffA);
;             PG8_WAIT_V(8); PG8_WAIT_L(0); PG8_BAR; PG8_MMA(0, 0, At, B0); PG8_MMA(0, 1, At, B1); PG8_BAR; PG8_SCHED;
	s_waitcnt lgkmcnt(0)
	v_mfma_f32_16x16x32_bf16 v[60:63], v[160:163], v[192:195], 0
	v_mfma_f32_16x16x32_bf16 v[52:55], v[168:171], v[192:195], 0
	v_mfma_f32_16x16x32_bf16 v[44:47], v[160:163], v[200:203], 0
	v_mfma_f32_16x16x32_bf16 v[36:39], v[168:171], v[200:203], 0
	v_mfma_f32_16x16x32_bf16 v[28:31], v[160:163], v[208:211], 0
	v_mfma_f32_16x16x32_bf16 v[20:23], v[168:171], v[208:211], 0
	v_mfma_f32_16x16x32_bf16 v[12:15], v[160:163], v[216:219], 0
	v_mfma_f32_16x16x32_bf16 v[4:7], v[168:171], v[216:219], 0
	v_mfma_f32_16x16x32_bf16 v[60:63], v[164:167], v[196:199], v[60:63]
	v_mfma_f32_16x16x32_bf16 v[52:55], v[172:175], v[196:199], v[52:55]
	v_mfma_f32_16x16x32_bf16 v[44:47], v[164:167], v[204:207], v[44:47]
	v_mfma_f32_16x16x32_bf16 v[36:39], v[172:175], v[204:207], v[36:39]
	v_mfma_f32_16x16x32_bf16 v[28:31], v[164:167], v[212:215], v[28:31]
	v_mfma_f32_16x16x32_bf16 v[20:23], v[172:175], v[212:215], v[20:23]
	v_mfma_f32_16x16x32_bf16 v[12:15], v[164:167], v[220:223], v[12:15]
	v_mfma_f32_16x16x32_bf16 v[4:7], v[172:175], v[220:223], v[4:7]
	v_mfma_f32_16x16x32_bf16 v[56:59], v[176:179], v[192:195], 0
	v_mfma_f32_16x16x32_bf16 v[48:51], v[184:187], v[192:195], 0
	v_mfma_f32_16x16x32_bf16 v[40:43], v[176:179], v[200:203], 0
	v_mfma_f32_16x16x32_bf16 v[32:35], v[184:187], v[200:203], 0
	v_mfma_f32_16x16x32_bf16 v[24:27], v[176:179], v[208:211], 0
	v_mfma_f32_16x16x32_bf16 v[16:19], v[184:187], v[208:211], 0
	v_mfma_f32_16x16x32_bf16 v[8:11], v[176:179], v[216:219], 0
	v_mfma_f32_16x16x32_bf16 v[0:3], v[184:187], v[216:219], 0
	v_mfma_f32_16x16x32_bf16 v[56:59], v[180:183], v[196:199], v[56:59]
	v_mfma_f32_16x16x32_bf16 v[48:51], v[188:191], v[196:199], v[48:51]
	v_mfma_f32_16x16x32_bf16 v[40:43], v[180:183], v[204:207], v[40:43]
	v_mfma_f32_16x16x32_bf16 v[32:35], v[188:191], v[204:207], v[32:35]
	v_mfma_f32_16x16x32_bf16 v[24:27], v[180:183], v[212:215], v[24:27]
	v_mfma_f32_16x16x32_bf16 v[16:19], v[188:191], v[212:215], v[16:19]
	v_mfma_f32_16x16x32_bf16 v[8:11], v[180:183], v[220:223], v[8:11]
	v_mfma_f32_16x16x32_bf16 v[0:3], v[188:191], v[220:223], v[0:3]
	s_barrier
	s_add_i32 s54, 0, 0x18000
	v_add_u32_e32 v159, s54, v148
	s_add_i32 s55, 0, 0x1c000
	ds_read_b128 v[160:163], v159
	ds_read_b128 v[164:167], v159 offset:1024
	ds_read_b128 v[168:171], v159 offset:2048
	ds_read_b128 v[172:175], v159 offset:3072
	v_add_u32_e32 v159, s55, v148
	ds_read_b128 v[176:179], v159
	ds_read_b128 v[180:183], v159 offset:1024
	ds_read_b128 v[184:187], v159 offset:2048
	ds_read_b128 v[188:191], v159 offset:3072
	s_add_u32 s38, s38, 0x40000
	s_addc_u32 s39, s39, 0
	s_mov_b32 m0, s37
	v_lshl_add_u64 v[230:231], s[38:39], 0, v[128:129]
	ds_read_b128 v[192:195], v156 offset:32768
	ds_read_b128 v[196:199], v156 offset:33792
	ds_read_b128 v[200:203], v156 offset:34816
	ds_read_b128 v[204:207], v156 offset:35840
	ds_read_b128 v[208:211], v156 offset:36864
	ds_read_b128 v[212:215], v156 offset:37888
	ds_read_b128 v[216:219], v156 offset:38912
	ds_read_b128 v[220:223], v156 offset:39936
	global_load_lds_dwordx4 v[230:231], off
	v_lshl_add_u64 v[230:231], s[38:39], 0, v[132:133]
	s_mov_b32 m0, s40
	s_nop 0
	global_load_lds_dwordx4 v[230:231], off
	s_waitcnt vmcnt(8)
	s_waitcnt lgkmcnt(0)
	s_barrier
	s_waitcnt lgkmcnt(0)
	v_mfma_f32_16x16x32_bf16 v[124:127], v[160:163], v[192:195], v[124:127]
	v_mfma_f32_16x16x32_bf16 v[116:119], v[168:171], v[192:195], v[116:119]
	v_mfma_f32_16x16x32_bf16 v[108:111], v[160:163], v[200:203], v[108:111]
	v_mfma_f32_16x16x32_bf16 v[100:103], v[168:171], v[200:203], v[100:103]
	v_mfma_f32_16x16x32_bf16 v[92:95], v[160:163], v[208:211], v[92:95]
	v_mfma_f32_16x16x32_bf16 v[84:87], v[168:171], v[208:211], v[84:87]
	v_mfma_f32_16x16x32_bf16 v[76:79], v[160:163], v[216:219], v[76:79]
	v_mfma_f32_16x16x32_bf16 v[68:71], v[168:171], v[216:219], v[68:71]
	v_mfma_f32_16x16x32_bf16 v[124:127], v[164:167], v[196:199], v[124:127]
	v_mfma_f32_16x16x32_bf16 v[116:119], v[172:175], v[196:199], v[116:119]
	v_mfma_f32_16x16x32_bf16 v[108:111], v[164:167], v[204:207], v[108:111]
	v_mfma_f32_16x16x32_bf16 v[100:103], v[172:175], v[204:207], v[100:103]
	v_mfma_f32_16x16x32_bf16 v[92:95], v[164:167], v[212:215], v[92:95]
	v_mfma_f32_16x16x32_bf16 v[84:87], v[172:175], v[212:215], v[84:87]
	v_mfma_f32_16x16x32_bf16 v[76:79], v[164:167], v[220:223], v[76:79]
	v_mfma_f32_16x16x32_bf16 v[68:71], v[172:175], v[220:223], v[68:71]
	v_mfma_f32_16x16x32_bf16 v[120:123], v[176:179], v[192:195], v[120:123]
	v_mfma_f32_16x16x32_bf16 v[112:115], v[184:187], v[192:195], v[112:115]
	v_mfma_f32_16x16x32_bf16 v[104:107], v[176:179], v[200:203], v[104:107]
	v_mfma_f32_16x16x32_bf16 v[96:99], v[184:187], v[200:203], v[96:99]
	v_mfma_f32_16x16x32_bf16 v[88:91], v[176:179], v[208:211], v[88:91]
	v_mfma_f32_16x16x32_bf16 v[80:83], v[184:187], v[208:211], v[80:83]
	v_mfma_f32_16x16x32_bf16 v[72:75], v[176:179], v[216:219], v[72:75]
	v_mfma_f32_16x16x32_bf16 v[64:67], v[184:187], v[216:219], v[64:67]
	v_mfma_f32_16x16x32_bf16 v[120:123], v[180:183], v[196:199], v[120:123]
	v_mfma_f32_16x16x32_bf16 v[112:115], v[188:191], v[196:199], v[112:115]
	v_mfma_f32_16x16x32_bf16 v[104:107], v[180:183], v[204:207], v[104:107]
	v_mfma_f32_16x16x32_bf16 v[96:99], v[188:191], v[204:207], v[96:99]
	v_mfma_f32_16x16x32_bf16 v[88:91], v[180:183], v[212:215], v[88:91]
	v_mfma_f32_16x16x32_bf16 v[80:83], v[188:191], v[212:215], v[80:83]
	v_mfma_f32_16x16x32_bf16 v[72:75], v[180:183], v[220:223], v[72:75]
	v_mfma_f32_16x16x32_bf16 v[64:67], v[188:191], v[220:223], v[64:67]
	s_barrier
; #define PG8_STAGE(bufoff, gbase, voff) do { _Pragma("unroll") for (int _i = 0; _i < 2; ++_i) \
;         __builtin_amdgcn_global_load_lds((const unsigned*)((const char*)(gbase) + (voff)[_i]), (PG8_LAS unsigned*)(lds + (bufoff) + ldsw + _i * 8192), 16, 0, 0); } while (0)
; #define PG8_LDA(dst, b, h) do { _Pragma("unroll") for (int m = 0; m < 4; ++m) _Pragma("unroll") for (int k = 0; k < 2; ++k) dst[m][k] = *(const PG8_LAS bf16x8*)(lds + PG8_SA(b, h) + aoff + m * 2048 + k * 1024); } while (0)
; #define PG8_MMA(ai, bj, At, Bt) do { __builtin_amdgcn_s_setprio(1); _Pragma("unroll") for (int m = 0; m < 4; ++m) _Pragma("unroll") for (int n = 0; n < 2; ++n) _Pragma("unroll") for (int k = 0; k < 2; ++k) \
;         acc[ai][bj][m][n] = __builtin_amdgcn_mfma_f32_16x16x32_bf16(Bt[n][k], At[m][k], acc[ai][bj][m][n], 0, 0, 0); __builtin_amdgcn_s_setprio(0); } while (0)
; #define PG8_WAIT_V(n) asm volatile("s_waitcnt vmcnt(" #n ")" ::: "memory")
; #define PG8_WAIT_L(n) asm volatile("s_waitcnt lgkmcnt(" #n ")" ::: "memory")
; #define PG8_BAR __builtin_amdgcn_s_barrier()
; #define PG8_SCHED __builtin_amdgcn_sched_barrier(0)
; template <class Epi, class Sched, bool ALIGN_EPI = false, bool SP2 = false>
; __device__ __forceinline__ void gemm_phase(PG8_LAS unsigned char* lds, const Gemm g, const Sched& S, const Epi& E, const int tid_in) {
;     ...
;             PG8_LDA(At, 1, 1); PG8_STAGE(PG8_SB(1, 0), b3, voffB); PG8_STAGE(PG8_SB(1, 1), b3 + hstep, voffB); PG8_STAGE(PG8_SA(1, 0), a3, voffA);
;             PG8_WAIT_V(8); PG8_WAIT_L(0); PG8_BAR; PG8_MMA(1, 0, At, B0); PG8_MMA(1, 1, At, B1); PG8_BAR; PG8_SCHED;
	s_add_i32 s38, s54, s34
	v_lshl_add_u64 v[144:145], v[144:145], 0, s[18:19]
	s_mov_b32 m0, s38
	ds_read_b128 v[192:195], v156 offset:49152
	ds_read_b128 v[196:199], v156 offset:50176
	ds_read_b128 v[200:203], v156 offset:51200
	ds_read_b128 v[204:207], v156 offset:52224
	ds_read_b128 v[208:211], v156 offset:53248
	ds_read_b128 v[212:215], v156 offset:54272
	ds_read_b128 v[216:219], v156 offset:55296
	ds_read_b128 v[220:223], v156 offset:56320
	global_load_lds_dwordx4 v[144:145], off
	s_add_i32 m0, s38, 0x2000
	s_add_u32 s0, s0, 0x40080
	v_lshl_add_u64 v[144:145], v[224:225], 0, s[18:19]
	s_addc_u32 s1, s1, 0
	s_add_i32 s38, s55, s34
	global_load_lds_dwordx4 v[144:145], off
	v_lshl_add_u64 v[144:145], s[0:1], 0, v[130:131]
	s_mov_b32 m0, s38
	s_nop 0
	global_load_lds_dwordx4 v[144:145], off
	v_lshl_add_u64 v[144:145], s[0:1], 0, v[134:135]
	s_add_i32 m0, s38, 0x2000
	s_nop 0
	global_load_lds_dwordx4 v[144:145], off
	v_lshl_add_u64 v[144:145], v[226:227], 0, s[18:19]
	s_mov_b32 m0, s43
	s_nop 0
	global_load_lds_dwordx4 v[144:145], off
	v_lshl_add_u64 v[144:145], v[228:229], 0, s[18:19]
	s_mov_b32 m0, s44
	s_nop 0
	global_load_lds_dwordx4 v[144:145], off
	s_waitcnt vmcnt(8)
	s_waitcnt lgkmcnt(0)
	s_barrier
	s_waitcnt lgkmcnt(0)
	v_mfma_f32_16x16x32_bf16 v[60:63], v[160:163], v[192:195], v[60:63]
	v_mfma_f32_16x16x32_bf16 v[52:55], v[168:171], v[192:195], v[52:55]
	v_mfma_f32_16x16x32_bf16 v[44:47], v[160:163], v[200:203], v[44:47]
	v_mfma_f32_16x16x32_bf16 v[36:39], v[168:171], v[200:203], v[36:39]
	v_mfma_f32_16x16x32_bf16 v[28:31], v[160:163], v[208:211], v[28:31]
	v_mfma_f32_16x16x32_bf16 v[20:23], v[168:171], v[208:211], v[20:23]
	v_mfma_f32_16x16x32_bf16 v[12:15], v[160:163], v[216:219], v[12:15]
	v_mfma_f32_16x16x32_bf16 v[4:7], v[168:171], v[216:219], v[4:7]
	v_mfma_f32_16x16x32_bf16 v[60:63], v[164:167], v[196:199], v[60:63]
	v_mfma_f32_16x16x32_bf16 v[52:55], v[172:175], v[196:199], v[52:55]
	v_mfma_f32_16x16x32_bf16 v[44:47], v[164:167], v[204:207], v[44:47]
	v_mfma_f32_16x16x32_bf16 v[36:39], v[172:175], v[204:207], v[36:39]
	v_mfma_f32_16x16x32_bf16 v[28:31], v[164:167], v[212:215], v[28:31]
	v_mfma_f32_16x16x32_bf16 v[20:23], v[172:175], v[212:215], v[20:23]
	v_mfma_f32_16x16x32_bf16 v[12:15], v[164:167], v[220:223], v[12:15]
	v_mfma_f32_16x16x32_bf16 v[4:7], v[172:175], v[220:223], v[4:7]
	v_mfma_f32_16x16x32_bf16 v[56:59], v[176:179], v[192:195], v[56:59]
	v_mfma_f32_16x16x32_bf16 v[48:51], v[184:187], v[192:195], v[48:51]
	v_mfma_f32_16x16x32_bf16 v[40:43], v[176:179], v[200:203], v[40:43]
	v_mfma_f32_16x16x32_bf16 v[32:35], v[184:187], v[200:203], v[32:35]
	v_mfma_f32_16x16x32_bf16 v[24:27], v[176:179], v[208:211], v[24:27]
	v_mfma_f32_16x16x32_bf16 v[16:19], v[184:187], v[208:211], v[16:19]
	v_mfma_f32_16x16x32_bf16 v[8:11], v[176:179], v[216:219], v[8:11]
	v_mfma_f32_16x16x32_bf16 v[0:3], v[184:187], v[216:219], v[0:3]
	v_mfma_f32_16x16x32_bf16 v[56:59], v[180:183], v[196:199], v[56:59]
	v_mfma_f32_16x16x32_bf16 v[48:51], v[188:191], v[196:199], v[48:51]
	v_mfma_f32_16x16x32_bf16 v[40:43], v[180:183], v[204:207], v[40:43]
	v_mfma_f32_16x16x32_bf16 v[32:35], v[188:191], v[204:207], v[32:35]
	v_mfma_f32_16x16x32_bf16 v[24:27], v[180:183], v[212:215], v[24:27]
	v_mfma_f32_16x16x32_bf16 v[16:19], v[188:191], v[212:215], v[16:19]
	v_mfma_f32_16x16x32_bf16 v[8:11], v[180:183], v[220:223], v[8:11]
	v_mfma_f32_16x16x32_bf16 v[0:3], v[188:191], v[220:223], v[0:3]
	s_barrier
	s_add_i32 s53, s53, 2
	s_add_u32 s10, s10, 0x100
	s_addc_u32 s11, s11, 0
	s_add_u32 s51, s51, 0x100
	s_addc_u32 s52, s52, 0
	s_cmp_gt_u32 s53, 13
	s_cbranch_scc0 .LBB0_3053
	s_branch .Lmy_kdone_7
	.p2alignl 6, 3212836864

; #define PG8_STAGE(bufoff, gbase, voff) do { _Pragma("unroll") for (int _i = 0; _i < 2; ++_i) \
;         __builtin_amdgcn_global_load_lds((const unsigned*)((const char*)(gbase) + (voff)[_i]), (PG8_LAS unsigned*)(lds + (bufoff) + ldsw + _i * 8192), 16, 0, 0); } while (0)
; #define PG8_LDA(dst, b, h) do { _Pragma("unroll") for (int m = 0; m < 4; ++m) _Pragma("unroll") for (int k = 0; k < 2; ++k) dst[m][k] = *(const PG8_LAS bf16x8*)(lds + PG8_SA(b, h) + aoff + m * 2048 + k * 1024); } while (0)
; #define PG8_LDB(dst, b, h) do { _Pragma("unroll") for (int n = 0; n < 2; ++n) _Pragma("unroll") for (int k = 0; k < 2; ++k) dst[n][k] = *(const PG8_LAS bf16x8*)(lds + PG8_SB(b, h) + boff + n * 2048 + k * 1024); } while (0)
; #define PG8_WAIT_V(n) asm volatile("s_waitcnt vmcnt(" #n ")" ::: "memory")
; #define PG8_WAIT_L(n) asm volatile("s_waitcnt lgkmcnt(" #n ")" ::: "memory")
; #define PG8_BAR __builtin_amdgcn_s_barrier()
; #define PG8_SCHED __builtin_amdgcn_sched_barrier(0)
; template <class Epi, class Sched, bool ALIGN_EPI = false, bool SP2 = false>
; __device__ __forceinline__ void gemm_phase(PG8_LAS unsigned char* lds, const Gemm g, const Sched& S, const Epi& E, const int tid_in) {
;     ...
;         const char* nA = has_next ? (const char*)g.A + (size_t)nxt.pm * tstep : cA; const char* nB = has_next ? (const char*)g.Bt + (size_t)nxt.pn * tstep : cB;
;         for (int t = 0; t < nt; t += 2) {
;             const bool last = (t == nt - 2);
;             const char* a1 = cA + (size_t)(t + 1) * kstep;
;             const char* a2 = last ? nA : cA + (size_t)(t + 2) * kstep; const char* b2 = last ? nB : cB + (size_t)(t + 2) * kstep;
;             const char* a3 = a2 + kstep; const char* b3 = b2 + kstep;
;             if (last && has_next) S.a_ready(nxt);
;             if constexpr (SP2) {
;             PG8_LDB(B0, 0, 0); PG8_LDB(B1, 0, 1); PG8_SCHED; PG8_LDA(At, 0, 0); PG8_STAGE(PG8_SA(1, 1), a1 + hstep, voffA);
;             PG8_WAIT_V(8); PG8_WAIT_L(0); PG8_BAR; PG8_MMA(0, 0, At, B0); PG8_MMA(0, 1, At, B1); PG8_BAR; PG8_SCHED;
;             PG8_LDA(At, 0, 1); PG8_STAGE(PG8_SB(0, 0), b2, voffB); PG8_STAGE(PG8_SB(0, 1), b2 + hstep, voffB); PG8_STAGE(PG8_SA(0, 0), a2, voffA);
;             PG8_WAIT_V(8); PG8_WAIT_L(0); PG8_BAR; PG8_MMA(1, 0, At, B0); PG8_MMA(1, 1, At, B1); PG8_BAR; PG8_SCHED;
.LBB0_3134:
	s_add_u32 s81, s0, 0x100
	v_mov_b32_e32 v0, 0
	s_addc_u32 s82, s1, 0
	s_mov_b32 s83, -2
	ds_read_b128 v[92:95], v207
	ds_read_b128 v[100:103], v207 offset:1024
	ds_read_b128 v[112:115], v207 offset:2048
	ds_read_b128 v[124:127], v207 offset:3072
	ds_read_b128 v[136:139], v208
	ds_read_b128 v[148:151], v208 offset:1024
	ds_read_b128 v[152:155], v208 offset:2048
	ds_read_b128 v[156:159], v208 offset:3072
	s_add_u32 s62, s60, 0x100
	s_addc_u32 s63, s61, 0
	s_cmp_eq_u32 s83, 40
	s_cselect_b32 s65, s9, s63
	s_cselect_b32 s64, s8, s62
	s_cselect_b32 s1, s59, s82
	s_cselect_b32 s0, s58, s81
	v_lshl_add_u64 v[214:215], s[60:61], 0, v[192:193]
	s_add_i32 m0, s4, 0xc000
	ds_read_b128 v[160:163], v209
	ds_read_b128 v[164:167], v209 offset:1024
	ds_read_b128 v[168:171], v209 offset:2048
	ds_read_b128 v[172:175], v209 offset:3072
	ds_read_b128 v[176:179], v209 offset:4096
	ds_read_b128 v[180:183], v209 offset:5120
	ds_read_b128 v[200:203], v209 offset:6144
	ds_read_b128 v[210:213], v209 offset:7168
	global_load_lds_dwordx4 v[214:215], off
	v_lshl_add_u64 v[214:215], s[60:61], 0, v[194:195]
	s_add_i32 m0, s4, 0xe000
	s_nop 0
	global_load_lds_dwordx4 v[214:215], off
	s_waitcnt vmcnt(8)
	s_waitcnt lgkmcnt(0)
	s_barrier
	s_waitcnt lgkmcnt(0)
	v_mfma_f32_16x16x32_bf16 v[144:147], v[92:95], v[160:163], 0
	v_mfma_f32_16x16x32_bf16 v[140:143], v[112:115], v[160:163], 0
	v_mfma_f32_16x16x32_bf16 v[120:123], v[92:95], v[168:171], 0
	v_mfma_f32_16x16x32_bf16 v[116:119], v[112:115], v[168:171], 0
	v_mfma_f32_16x16x32_bf16 v[96:99], v[92:95], v[176:179], 0
	v_mfma_f32_16x16x32_bf16 v[88:91], v[112:115], v[176:179], 0
	v_mfma_f32_16x16x32_bf16 v[76:79], v[92:95], v[200:203], 0
	v_mfma_f32_16x16x32_bf16 v[72:75], v[112:115], v[200:203], 0
	v_mfma_f32_16x16x32_bf16 v[144:147], v[100:103], v[164:167], v[144:147]
	v_mfma_f32_16x16x32_bf16 v[140:143], v[124:127], v[164:167], v[140:143]
	v_mfma_f32_16x16x32_bf16 v[120:123], v[100:103], v[172:175], v[120:123]
	v_mfma_f32_16x16x32_bf16 v[116:119], v[124:127], v[172:175], v[116:119]
	v_mfma_f32_16x16x32_bf16 v[96:99], v[100:103], v[180:183], v[96:99]
	v_mfma_f32_16x16x32_bf16 v[88:91], v[124:127], v[180:183], v[88:91]
	v_mfma_f32_16x16x32_bf16 v[76:79], v[100:103], v[210:213], v[76:79]
	v_mfma_f32_16x16x32_bf16 v[72:75], v[124:127], v[210:213], v[72:75]
	v_mfma_f32_16x16x32_bf16 v[132:135], v[136:139], v[160:163], 0
	v_mfma_f32_16x16x32_bf16 v[128:131], v[152:155], v[160:163], 0
	v_mfma_f32_16x16x32_bf16 v[108:111], v[136:139], v[168:171], 0
	v_mfma_f32_16x16x32_bf16 v[104:107], v[152:155], v[168:171], 0
	v_mfma_f32_16x16x32_bf16 v[84:87], v[136:139], v[176:179], 0
	v_mfma_f32_16x16x32_bf16 v[80:83], v[152:155], v[176:179], 0
	v_mfma_f32_16x16x32_bf16 v[68:71], v[136:139], v[200:203], 0
	v_mfma_f32_16x16x32_bf16 v[64:67], v[152:155], v[200:203], 0
	v_mfma_f32_16x16x32_bf16 v[132:135], v[148:151], v[164:167], v[132:135]
	v_mfma_f32_16x16x32_bf16 v[128:131], v[156:159], v[164:167], v[128:131]
	v_mfma_f32_16x16x32_bf16 v[108:111], v[148:151], v[172:175], v[108:111]
	v_mfma_f32_16x16x32_bf16 v[104:107], v[156:159], v[172:175], v[104:107]
	v_mfma_f32_16x16x32_bf16 v[84:87], v[148:151], v[180:183], v[84:87]
	v_mfma_f32_16x16x32_bf16 v[80:83], v[156:159], v[180:183], v[80:83]
	v_mfma_f32_16x16x32_bf16 v[68:71], v[148:151], v[210:213], v[68:71]
	v_mfma_f32_16x16x32_bf16 v[64:67], v[156:159], v[210:213], v[64:67]
	s_barrier
	s_add_i32 s60, s3, s2
	v_lshl_add_u64 v[214:215], s[0:1], 0, v[186:187]
	s_mov_b32 m0, s60
	ds_read_b128 v[160:163], v209 offset:16384
	ds_read_b128 v[164:167], v209 offset:17408
	ds_read_b128 v[168:171], v209 offset:18432
	ds_read_b128 v[172:175], v209 offset:19456
	ds_read_b128 v[176:179], v209 offset:20480
	ds_read_b128 v[180:183], v209 offset:21504
	ds_read_b128 v[200:203], v209 offset:22528
	ds_read_b128 v[210:213], v209 offset:23552
	global_load_lds_dwordx4 v[214:215], off
	s_add_i32 m0, s60, 0x2000
	s_add_u32 s60, s0, 0xb0000
	v_lshl_add_u64 v[216:217], s[0:1], 0, v[190:191]
	s_addc_u32 s61, s1, 0
	s_add_i32 s84, s69, s2
	global_load_lds_dwordx4 v[216:217], off
	v_lshl_add_u64 v[218:219], s[60:61], 0, v[186:187]
	s_mov_b32 m0, s84
	v_lshl_add_u64 v[220:221], s[64:65], 0, v[188:189]
	global_load_lds_dwordx4 v[218:219], off
	v_lshl_add_u64 v[218:219], s[60:61], 0, v[190:191]
	s_add_i32 m0, s84, 0x2000
	s_nop 0
	global_load_lds_dwordx4 v[218:219], off
	v_lshl_add_u64 v[218:219], s[64:65], 0, v[184:185]
	s_mov_b32 m0, s4
	s_nop 0
	global_load_lds_dwordx4 v[218:219], off
	s_mov_b32 m0, s5
	s_nop 0
	global_load_lds_dwordx4 v[220:221], off
	s_waitcnt vmcnt(8)
	s_waitcnt lgkmcnt(0)
	s_barrier
; #define PG8_STAGE(bufoff, gbase, voff) do { _Pragma("unroll") for (int _i = 0; _i < 2; ++_i) \
;         __builtin_amdgcn_global_load_lds((const unsigned*)((const char*)(gbase) + (voff)[_i]), (PG8_LAS unsigned*)(lds + (bufoff) + ldsw + _i * 8192), 16, 0, 0); } while (0)
; #define PG8_LDA(dst, b, h) do { _Pragma("unroll") for (int m = 0; m < 4; ++m) _Pragma("unroll") for (int k = 0; k < 2; ++k) dst[m][k] = *(const PG8_LAS bf16x8*)(lds + PG8_SA(b, h) + aoff + m * 2048 + k * 1024); } while (0)
; #define PG8_LDB(dst, b, h) do { _Pragma("unroll") for (int n = 0; n < 2; ++n) _Pragma("unroll") for (int k = 0; k < 2; ++k) dst[n][k] = *(const PG8_LAS bf16x8*)(lds + PG8_SB(b, h) + boff + n * 2048 + k * 1024); } while (0)
; #define PG8_MMA(ai, bj, At, Bt) do { __builtin_amdgcn_s_setprio(1); _Pragma("unroll") for (int m = 0; m < 4; ++m) _Pragma("unroll") for (int n = 0; n < 2; ++n) _Pragma("unroll") for (int k = 0; k < 2; ++k) \
;         acc[ai][bj][m][n] = __builtin_amdgcn_mfma_f32_16x16x32_bf16(Bt[n][k], At[m][k], acc[ai][bj][m][n], 0, 0, 0); __builtin_amdgcn_s_setprio(0); } while (0)
; #define PG8_WAIT_V(n) asm volatile("s_waitcnt vmcnt(" #n ")" ::: "memory")
; #define PG8_WAIT_L(n) asm volatile("s_waitcnt lgkmcnt(" #n ")" ::: "memory")
; #define PG8_BAR __builtin_amdgcn_s_barrier()
; #define PG8_SCHED __builtin_amdgcn_sched_barrier(0)
; template <class Epi, class Sched, bool ALIGN_EPI = false, bool SP2 = false>
; __device__ __forceinline__ void gemm_phase(PG8_LAS unsigned char* lds, const Gemm g, const Sched& S, const Epi& E, const int tid_in) {
;     ...
;             PG8_WAIT_V(8); PG8_WAIT_L(0); PG8_BAR; PG8_MMA(1, 0, At, B0); PG8_MMA(1, 1, At, B1); PG8_BAR; PG8_SCHED;
;             PG8_LDB(B0, 1, 0); PG8_LDB(B1, 1, 1); PG8_SCHED; PG8_LDA(At, 1, 0); PG8_STAGE(PG8_SA(0, 1), a2 + hstep, voffA);
;             PG8_WAIT_V(8); PG8_WAIT_L(0); PG8_BAR; PG8_MMA(0, 0, At, B0); PG8_MMA(0, 1, At, B1); PG8_BAR; PG8_SCHED;
	s_waitcnt lgkmcnt(0)
	v_mfma_f32_16x16x32_bf16 v[60:63], v[92:95], v[160:163], 0
	v_mfma_f32_16x16x32_bf16 v[56:59], v[112:115], v[160:163], 0
	v_mfma_f32_16x16x32_bf16 v[44:47], v[92:95], v[168:171], 0
	v_mfma_f32_16x16x32_bf16 v[40:43], v[112:115], v[168:171], 0
	v_mfma_f32_16x16x32_bf16 v[28:31], v[92:95], v[176:179], 0
	v_mfma_f32_16x16x32_bf16 v[24:27], v[112:115], v[176:179], 0
	v_mfma_f32_16x16x32_bf16 v[12:15], v[92:95], v[200:203], 0
	v_mfma_f32_16x16x32_bf16 v[8:11], v[112:115], v[200:203], 0
	v_mfma_f32_16x16x32_bf16 v[60:63], v[100:103], v[164:167], v[60:63]
	v_mfma_f32_16x16x32_bf16 v[56:59], v[124:127], v[164:167], v[56:59]
	v_mfma_f32_16x16x32_bf16 v[44:47], v[100:103], v[172:175], v[44:47]
	v_mfma_f32_16x16x32_bf16 v[40:43], v[124:127], v[172:175], v[40:43]
	v_mfma_f32_16x16x32_bf16 v[28:31], v[100:103], v[180:183], v[28:31]
	v_mfma_f32_16x16x32_bf16 v[24:27], v[124:127], v[180:183], v[24:27]
	v_mfma_f32_16x16x32_bf16 v[12:15], v[100:103], v[210:213], v[12:15]
	v_mfma_f32_16x16x32_bf16 v[8:11], v[124:127], v[210:213], v[8:11]
	v_mfma_f32_16x16x32_bf16 v[52:55], v[136:139], v[160:163], 0
	v_mfma_f32_16x16x32_bf16 v[48:51], v[152:155], v[160:163], 0
	v_mfma_f32_16x16x32_bf16 v[36:39], v[136:139], v[168:171], 0
	v_mfma_f32_16x16x32_bf16 v[32:35], v[152:155], v[168:171], 0
	v_mfma_f32_16x16x32_bf16 v[20:23], v[136:139], v[176:179], 0
	v_mfma_f32_16x16x32_bf16 v[16:19], v[152:155], v[176:179], 0
	v_mfma_f32_16x16x32_bf16 v[4:7], v[136:139], v[200:203], 0
	v_mfma_f32_16x16x32_bf16 v[0:3], v[152:155], v[200:203], 0
	v_mfma_f32_16x16x32_bf16 v[52:55], v[148:151], v[164:167], v[52:55]
	v_mfma_f32_16x16x32_bf16 v[48:51], v[156:159], v[164:167], v[48:51]
	v_mfma_f32_16x16x32_bf16 v[36:39], v[148:151], v[172:175], v[36:39]
	v_mfma_f32_16x16x32_bf16 v[32:35], v[156:159], v[172:175], v[32:35]
	v_mfma_f32_16x16x32_bf16 v[20:23], v[148:151], v[180:183], v[20:23]
	v_mfma_f32_16x16x32_bf16 v[16:19], v[156:159], v[180:183], v[16:19]
	v_mfma_f32_16x16x32_bf16 v[4:7], v[148:151], v[210:213], v[4:7]
	v_mfma_f32_16x16x32_bf16 v[0:3], v[156:159], v[210:213], v[0:3]
	s_barrier
	s_add_i32 s84, 0, 0x18000
	s_add_i32 s85, 0, 0x1c000
	v_add_u32_e32 v124, s84, v205
	v_add_u32_e32 v156, s85, v205
	ds_read_b128 v[92:95], v124
	ds_read_b128 v[100:103], v124 offset:1024
	ds_read_b128 v[112:115], v124 offset:2048
	ds_read_b128 v[124:127], v124 offset:3072
	ds_read_b128 v[136:139], v156
	ds_read_b128 v[148:151], v156 offset:1024
	ds_read_b128 v[152:155], v156 offset:2048
	ds_read_b128 v[156:159], v156 offset:3072
	s_add_u32 s60, s64, 0xb0000
	s_addc_u32 s61, s65, 0
	s_mov_b32 m0, s34
	v_lshl_add_u64 v[222:223], s[60:61], 0, v[184:185]
	ds_read_b128 v[160:163], v209 offset:32768
	ds_read_b128 v[164:167], v209 offset:33792
	ds_read_b128 v[168:171], v209 offset:34816
	ds_read_b128 v[172:175], v209 offset:35840
	ds_read_b128 v[176:179], v209 offset:36864
	ds_read_b128 v[180:183], v209 offset:37888
	ds_read_b128 v[200:203], v209 offset:38912
	ds_read_b128 v[210:213], v209 offset:39936
	global_load_lds_dwordx4 v[222:223], off
	v_lshl_add_u64 v[222:223], s[60:61], 0, v[188:189]
	s_mov_b32 m0, s35
	s_nop 0
	global_load_lds_dwordx4 v[222:223], off
	s_waitcnt vmcnt(8)
	s_waitcnt lgkmcnt(0)
	s_barrier
	s_waitcnt lgkmcnt(0)
	v_mfma_f32_16x16x32_bf16 v[144:147], v[92:95], v[160:163], v[144:147]
	v_mfma_f32_16x16x32_bf16 v[140:143], v[112:115], v[160:163], v[140:143]
	v_mfma_f32_16x16x32_bf16 v[120:123], v[92:95], v[168:171], v[120:123]
	v_mfma_f32_16x16x32_bf16 v[116:119], v[112:115], v[168:171], v[116:119]
	v_mfma_f32_16x16x32_bf16 v[96:99], v[92:95], v[176:179], v[96:99]
	v_mfma_f32_16x16x32_bf16 v[88:91], v[112:115], v[176:179], v[88:91]
	v_mfma_f32_16x16x32_bf16 v[76:79], v[92:95], v[200:203], v[76:79]
	v_mfma_f32_16x16x32_bf16 v[72:75], v[112:115], v[200:203], v[72:75]
	v_mfma_f32_16x16x32_bf16 v[144:147], v[100:103], v[164:167], v[144:147]
	v_mfma_f32_16x16x32_bf16 v[140:143], v[124:127], v[164:167], v[140:143]
	v_mfma_f32_16x16x32_bf16 v[120:123], v[100:103], v[172:175], v[120:123]
	v_mfma_f32_16x16x32_bf16 v[116:119], v[124:127], v[172:175], v[116:119]
	v_mfma_f32_16x16x32_bf16 v[96:99], v[100:103], v[180:183], v[96:99]
	v_mfma_f32_16x16x32_bf16 v[88:91], v[124:127], v[180:183], v[88:91]
	v_mfma_f32_16x16x32_bf16 v[76:79], v[100:103], v[210:213], v[76:79]
	v_mfma_f32_16x16x32_bf16 v[72:75], v[124:127], v[210:213], v[72:75]
	v_mfma_f32_16x16x32_bf16 v[132:135], v[136:139], v[160:163], v[132:135]
	v_mfma_f32_16x16x32_bf16 v[128:131], v[152:155], v[160:163], v[128:131]
	v_mfma_f32_16x16x32_bf16 v[108:111], v[136:139], v[168:171], v[108:111]
	v_mfma_f32_16x16x32_bf16 v[104:107], v[152:155], v[168:171], v[104:107]
	v_mfma_f32_16x16x32_bf16 v[84:87], v[136:139], v[176:179], v[84:87]
	v_mfma_f32_16x16x32_bf16 v[80:83], v[152:155], v[176:179], v[80:83]
	v_mfma_f32_16x16x32_bf16 v[68:71], v[136:139], v[200:203], v[68:71]
	v_mfma_f32_16x16x32_bf16 v[64:67], v[152:155], v[200:203], v[64:67]
	v_mfma_f32_16x16x32_bf16 v[132:135], v[148:151], v[164:167], v[132:135]
	v_mfma_f32_16x16x32_bf16 v[128:131], v[156:159], v[164:167], v[128:131]
	v_mfma_f32_16x16x32_bf16 v[108:111], v[148:151], v[172:175], v[108:111]
	v_mfma_f32_16x16x32_bf16 v[104:107], v[156:159], v[172:175], v[104:107]
	v_mfma_f32_16x16x32_bf16 v[84:87], v[148:151], v[180:183], v[84:87]
	v_mfma_f32_16x16x32_bf16 v[80:83], v[156:159], v[180:183], v[80:83]
	v_mfma_f32_16x16x32_bf16 v[68:71], v[148:151], v[210:213], v[68:71]
	v_mfma_f32_16x16x32_bf16 v[64:67], v[156:159], v[210:213], v[64:67]
	s_barrier
; #define PG8_STAGE(bufoff, gbase, voff) do { _Pragma("unroll") for (int _i = 0; _i < 2; ++_i) \
;         __builtin_amdgcn_global_load_lds((const unsigned*)((const char*)(gbase) + (voff)[_i]), (PG8_LAS unsigned*)(lds + (bufoff) + ldsw + _i * 8192), 16, 0, 0); } while (0)
; #define PG8_LDA(dst, b, h) do { _Pragma("unroll") for (int m = 0; m < 4; ++m) _Pragma("unroll") for (int k = 0; k < 2; ++k) dst[m][k] = *(const PG8_LAS bf16x8*)(lds + PG8_SA(b, h) + aoff + m * 2048 + k * 1024); } while (0)
; #define PG8_MMA(ai, bj, At, Bt) do { __builtin_amdgcn_s_setprio(1); _Pragma("unroll") for (int m = 0; m < 4; ++m) _Pragma("unroll") for (int n = 0; n < 2; ++n) _Pragma("unroll") for (int k = 0; k < 2; ++k) \
;         acc[ai][bj][m][n] = __builtin_amdgcn_mfma_f32_16x16x32_bf16(Bt[n][k], At[m][k], acc[ai][bj][m][n], 0, 0, 0); __builtin_amdgcn_s_setprio(0); } while (0)
; #define PG8_WAIT_V(n) asm volatile("s_waitcnt vmcnt(" #n ")" ::: "memory")
; #define PG8_WAIT_L(n) asm volatile("s_waitcnt lgkmcnt(" #n ")" ::: "memory")
; #define PG8_BAR __builtin_amdgcn_s_barrier()
; #define PG8_SCHED __builtin_amdgcn_sched_barrier(0)
; template <class Epi, class Sched, bool ALIGN_EPI = false, bool SP2 = false>
; __device__ __forceinline__ void gemm_phase(PG8_LAS unsigned char* lds, const Gemm g, const Sched& S, const Epi& E, const int tid_in) {
;     ...
;             PG8_LDA(At, 1, 1); PG8_STAGE(PG8_SB(1, 0), b3, voffB); PG8_STAGE(PG8_SB(1, 1), b3 + hstep, voffB); PG8_STAGE(PG8_SA(1, 0), a3, voffA);
;             PG8_WAIT_V(8); PG8_WAIT_L(0); PG8_BAR; PG8_MMA(1, 0, At, B0); PG8_MMA(1, 1, At, B1); PG8_BAR; PG8_SCHED;
	s_add_i32 s60, s84, s2
	v_lshl_add_u64 v[214:215], v[214:215], 0, s[26:27]
	s_mov_b32 m0, s60
	ds_read_b128 v[160:163], v209 offset:49152
	ds_read_b128 v[164:167], v209 offset:50176
	ds_read_b128 v[168:171], v209 offset:51200
	ds_read_b128 v[172:175], v209 offset:52224
	ds_read_b128 v[176:179], v209 offset:53248
	ds_read_b128 v[180:183], v209 offset:54272
	ds_read_b128 v[200:203], v209 offset:55296
	ds_read_b128 v[210:213], v209 offset:56320
	global_load_lds_dwordx4 v[214:215], off
	s_add_i32 m0, s60, 0x2000
	s_add_u32 s0, s0, 0xb0080
	v_lshl_add_u64 v[214:215], v[216:217], 0, s[26:27]
	s_addc_u32 s1, s1, 0
	s_add_i32 s60, s85, s2
	global_load_lds_dwordx4 v[214:215], off
	v_lshl_add_u64 v[214:215], s[0:1], 0, v[186:187]
	s_mov_b32 m0, s60
	s_nop 0
	global_load_lds_dwordx4 v[214:215], off
	v_lshl_add_u64 v[214:215], s[0:1], 0, v[190:191]
	s_add_i32 m0, s60, 0x2000
	s_nop 0
	global_load_lds_dwordx4 v[214:215], off
	v_lshl_add_u64 v[214:215], v[218:219], 0, s[26:27]
	s_mov_b32 m0, s37
	s_nop 0
	global_load_lds_dwordx4 v[214:215], off
	v_lshl_add_u64 v[214:215], v[220:221], 0, s[26:27]
	s_mov_b32 m0, s66
	s_nop 0
	global_load_lds_dwordx4 v[214:215], off
	s_waitcnt vmcnt(8)
	s_waitcnt lgkmcnt(0)
	s_barrier
	s_waitcnt lgkmcnt(0)
	v_mfma_f32_16x16x32_bf16 v[60:63], v[92:95], v[160:163], v[60:63]
	v_mfma_f32_16x16x32_bf16 v[56:59], v[112:115], v[160:163], v[56:59]
	v_mfma_f32_16x16x32_bf16 v[44:47], v[92:95], v[168:171], v[44:47]
	v_mfma_f32_16x16x32_bf16 v[40:43], v[112:115], v[168:171], v[40:43]
	v_mfma_f32_16x16x32_bf16 v[28:31], v[92:95], v[176:179], v[28:31]
	v_mfma_f32_16x16x32_bf16 v[24:27], v[112:115], v[176:179], v[24:27]
	v_mfma_f32_16x16x32_bf16 v[12:15], v[92:95], v[200:203], v[12:15]
	v_mfma_f32_16x16x32_bf16 v[8:11], v[112:115], v[200:203], v[8:11]
	v_mfma_f32_16x16x32_bf16 v[60:63], v[100:103], v[164:167], v[60:63]
	v_mfma_f32_16x16x32_bf16 v[56:59], v[124:127], v[164:167], v[56:59]
	v_mfma_f32_16x16x32_bf16 v[44:47], v[100:103], v[172:175], v[44:47]
	v_mfma_f32_16x16x32_bf16 v[40:43], v[124:127], v[172:175], v[40:43]
	v_mfma_f32_16x16x32_bf16 v[28:31], v[100:103], v[180:183], v[28:31]
	v_mfma_f32_16x16x32_bf16 v[24:27], v[124:127], v[180:183], v[24:27]
	v_mfma_f32_16x16x32_bf16 v[12:15], v[100:103], v[210:213], v[12:15]
	v_mfma_f32_16x16x32_bf16 v[8:11], v[124:127], v[210:213], v[8:11]
	v_mfma_f32_16x16x32_bf16 v[52:55], v[136:139], v[160:163], v[52:55]
	v_mfma_f32_16x16x32_bf16 v[48:51], v[152:155], v[160:163], v[48:51]
	v_mfma_f32_16x16x32_bf16 v[36:39], v[136:139], v[168:171], v[36:39]
	v_mfma_f32_16x16x32_bf16 v[32:35], v[152:155], v[168:171], v[32:35]
	v_mfma_f32_16x16x32_bf16 v[20:23], v[136:139], v[176:179], v[20:23]
	v_mfma_f32_16x16x32_bf16 v[16:19], v[152:155], v[176:179], v[16:19]
	v_mfma_f32_16x16x32_bf16 v[4:7], v[136:139], v[200:203], v[4:7]
	v_mfma_f32_16x16x32_bf16 v[0:3], v[152:155], v[200:203], v[0:3]
	v_mfma_f32_16x16x32_bf16 v[52:55], v[148:151], v[164:167], v[52:55]
	v_mfma_f32_16x16x32_bf16 v[48:51], v[156:159], v[164:167], v[48:51]
	v_mfma_f32_16x16x32_bf16 v[36:39], v[148:151], v[172:175], v[36:39]
	v_mfma_f32_16x16x32_bf16 v[32:35], v[156:159], v[172:175], v[32:35]
	v_mfma_f32_16x16x32_bf16 v[20:23], v[148:151], v[180:183], v[20:23]
	v_mfma_f32_16x16x32_bf16 v[16:19], v[156:159], v[180:183], v[16:19]
	v_mfma_f32_16x16x32_bf16 v[4:7], v[148:151], v[210:213], v[4:7]
	v_mfma_f32_16x16x32_bf16 v[0:3], v[156:159], v[210:213], v[0:3]
	s_barrier
	s_add_i32 s83, s83, 2
	s_add_u32 s81, s81, 0x100
	s_addc_u32 s82, s82, 0
	s_cmp_gt_u32 s83, 41
	s_mov_b64 s[60:61], s[62:63]
	s_cbranch_scc0 .LBB0_3135
	s_branch .Lmy_kdone_8
	.p2alignl 6, 3212836864
